# down-proj sample-row GEMM k-steps software-pipelined (3 load banks); next-unit division by shifts; redundant mid-block setprio removed
# baseline (speedup 1.0000x reference)
.LBB0_693:
.LBB0_694:
	s_add_i32 s19, 0, 0x10000
	s_add_i32 s36, 0, 0x14000
	v_add_u32_e32 v12, s19, v214
	v_add_u32_e32 v28, s36, v214
	ds_read_b128 v[0:3], v12
	ds_read_b128 v[4:7], v12 offset:1024
	ds_read_b128 v[8:11], v12 offset:2048
	ds_read_b128 v[12:15], v12 offset:3072
	ds_read_b128 v[16:19], v28
	ds_read_b128 v[20:23], v28 offset:1024
	ds_read_b128 v[24:27], v28 offset:2048
	ds_read_b128 v[28:31], v28 offset:3072
	s_add_u32 s4, s82, 0x40080
	s_addc_u32 s5, s83, 0
	v_lshl_add_u64 v[68:69], s[4:5], 0, v[50:51]
	s_add_i32 m0, s23, 0xc000
	ds_read_b128 v[32:35], v215
	ds_read_b128 v[36:39], v215 offset:1024
	ds_read_b128 v[40:43], v215 offset:2048
	ds_read_b128 v[44:47], v215 offset:3072
	ds_read_b128 v[52:55], v215 offset:4096
	ds_read_b128 v[56:59], v215 offset:5120
	ds_read_b128 v[60:63], v215 offset:6144
	ds_read_b128 v[64:67], v215 offset:7168
	global_load_lds_dwordx4 v[68:69], off
	v_lshl_add_u64 v[68:69], s[4:5], 0, v[120:121]
	s_add_i32 m0, s23, 0xe000
	s_nop 0
	global_load_lds_dwordx4 v[68:69], off
	s_waitcnt vmcnt(40) lgkmcnt(0)
	s_setprio 1
	s_barrier
	v_mfma_f32_16x16x32_bf16 v[68:71], v[0:3], v[32:35], 0
	v_mfma_f32_16x16x32_bf16 v[72:75], v[8:11], v[32:35], 0
	v_mfma_f32_16x16x32_bf16 v[76:79], v[0:3], v[40:43], 0
	v_mfma_f32_16x16x32_bf16 v[80:83], v[8:11], v[40:43], 0
	v_mfma_f32_16x16x32_bf16 v[84:87], v[0:3], v[52:55], 0
	v_mfma_f32_16x16x32_bf16 v[88:91], v[8:11], v[52:55], 0
	v_mfma_f32_16x16x32_bf16 v[92:95], v[0:3], v[60:63], 0
	v_mfma_f32_16x16x32_bf16 v[96:99], v[8:11], v[60:63], 0
	v_mfma_f32_16x16x32_bf16 v[68:71], v[4:7], v[36:39], v[68:71]
	v_mfma_f32_16x16x32_bf16 v[72:75], v[12:15], v[36:39], v[72:75]
	v_mfma_f32_16x16x32_bf16 v[76:79], v[4:7], v[44:47], v[76:79]
	v_mfma_f32_16x16x32_bf16 v[80:83], v[12:15], v[44:47], v[80:83]
	v_mfma_f32_16x16x32_bf16 v[84:87], v[4:7], v[56:59], v[84:87]
	v_mfma_f32_16x16x32_bf16 v[88:91], v[12:15], v[56:59], v[88:91]
	v_mfma_f32_16x16x32_bf16 v[92:95], v[4:7], v[64:67], v[92:95]
	v_mfma_f32_16x16x32_bf16 v[96:99], v[12:15], v[64:67], v[96:99]
	v_mfma_f32_16x16x32_bf16 v[100:103], v[16:19], v[32:35], 0
	v_mfma_f32_16x16x32_bf16 v[32:35], v[24:27], v[32:35], 0
	v_mfma_f32_16x16x32_bf16 v[122:125], v[20:23], v[36:39], v[100:103]
	v_mfma_f32_16x16x32_bf16 v[32:35], v[28:31], v[36:39], v[32:35]
	v_mfma_f32_16x16x32_bf16 v[36:39], v[16:19], v[40:43], 0
	v_mfma_f32_16x16x32_bf16 v[40:43], v[24:27], v[40:43], 0
	v_mfma_f32_16x16x32_bf16 v[36:39], v[20:23], v[44:47], v[36:39]
	v_mfma_f32_16x16x32_bf16 v[40:43], v[28:31], v[44:47], v[40:43]
	v_mfma_f32_16x16x32_bf16 v[44:47], v[16:19], v[52:55], 0
	v_mfma_f32_16x16x32_bf16 v[52:55], v[24:27], v[52:55], 0
	v_mfma_f32_16x16x32_bf16 v[126:129], v[28:31], v[56:59], v[52:55]
	v_mfma_f32_16x16x32_bf16 v[52:55], v[16:19], v[60:63], 0
	v_mfma_f32_16x16x32_bf16 v[44:47], v[20:23], v[56:59], v[44:47]
	v_mfma_f32_16x16x32_bf16 v[130:133], v[20:23], v[64:67], v[52:55]
	v_mfma_f32_16x16x32_bf16 v[52:55], v[24:27], v[60:63], 0
	v_mfma_f32_16x16x32_bf16 v[134:137], v[28:31], v[64:67], v[52:55]
	s_barrier
	s_setprio 0
	v_lshl_add_u64 v[154:155], s[24:25], 0, v[48:49]
	s_add_i32 s4, s19, s88
	v_lshl_add_u64 v[116:117], v[154:155], 0, s[16:17]
	s_mov_b32 m0, s4
	s_nop 0
	ds_read_b128 v[52:55], v215 offset:16384
	ds_read_b128 v[56:59], v215 offset:17408
	ds_read_b128 v[60:63], v215 offset:18432
	ds_read_b128 v[64:67], v215 offset:19456
	ds_read_b128 v[100:103], v215 offset:20480
	ds_read_b128 v[104:107], v215 offset:21504
	ds_read_b128 v[108:111], v215 offset:22528
	ds_read_b128 v[112:115], v215 offset:23552
	global_load_lds_dwordx4 v[116:117], off
	s_add_i32 m0, s4, 0x2000
	v_lshl_add_u64 v[190:191], s[24:25], 0, v[160:161]
	s_add_u32 s4, s24, 0x10100
	v_lshl_add_u64 v[116:117], v[190:191], 0, s[16:17]
	s_addc_u32 s5, s25, 0
	s_add_i32 s19, s36, s88
	global_load_lds_dwordx4 v[116:117], off
	v_lshl_add_u64 v[116:117], s[4:5], 0, v[48:49]
	s_mov_b32 m0, s19
	v_lshl_add_u64 v[248:249], s[82:83], 0, v[50:51]
	global_load_lds_dwordx4 v[116:117], off
	v_lshl_add_u64 v[116:117], s[4:5], 0, v[160:161]
	s_add_i32 m0, s19, 0x2000
	v_mov_b32_e32 v252, v253
	global_load_lds_dwordx4 v[116:117], off
	v_lshl_add_u64 v[116:117], v[248:249], 0, s[16:17]
	s_mov_b32 m0, s23
	v_mov_b32_e32 v253, v250
	v_lshl_add_u64 v[250:251], s[82:83], 0, v[120:121]
	global_load_lds_dwordx4 v[116:117], off
	v_lshl_add_u64 v[116:117], v[250:251], 0, s[16:17]
	s_mov_b32 m0, s91
	s_nop 0
	global_load_lds_dwordx4 v[116:117], off
	s_waitcnt vmcnt(40) lgkmcnt(0)
	s_setprio 1
	s_barrier
	v_mfma_f32_16x16x32_bf16 v[116:119], v[0:3], v[52:55], 0
	v_mfma_f32_16x16x32_bf16 v[138:141], v[4:7], v[56:59], v[116:119]
	v_mfma_f32_16x16x32_bf16 v[116:119], v[8:11], v[52:55], 0
	v_mfma_f32_16x16x32_bf16 v[142:145], v[12:15], v[56:59], v[116:119]
	v_mfma_f32_16x16x32_bf16 v[116:119], v[0:3], v[60:63], 0
	v_mfma_f32_16x16x32_bf16 v[146:149], v[4:7], v[64:67], v[116:119]
	v_mfma_f32_16x16x32_bf16 v[116:119], v[8:11], v[60:63], 0
	v_mfma_f32_16x16x32_bf16 v[150:153], v[12:15], v[64:67], v[116:119]
	v_mfma_f32_16x16x32_bf16 v[116:119], v[0:3], v[100:103], 0
	v_mfma_f32_16x16x32_bf16 v[0:3], v[0:3], v[108:111], 0
	v_mfma_f32_16x16x32_bf16 v[162:165], v[4:7], v[104:107], v[116:119]
	v_mfma_f32_16x16x32_bf16 v[0:3], v[4:7], v[112:115], v[0:3]
	v_mfma_f32_16x16x32_bf16 v[4:7], v[8:11], v[108:111], 0
	v_mfma_f32_16x16x32_bf16 v[116:119], v[8:11], v[100:103], 0
	v_mfma_f32_16x16x32_bf16 v[4:7], v[12:15], v[112:115], v[4:7]
	v_mfma_f32_16x16x32_bf16 v[170:173], v[12:15], v[104:107], v[116:119]
	v_mfma_f32_16x16x32_bf16 v[8:11], v[16:19], v[52:55], 0
	v_mfma_f32_16x16x32_bf16 v[12:15], v[24:27], v[52:55], 0
	v_mfma_f32_16x16x32_bf16 v[52:55], v[16:19], v[60:63], 0
	v_mfma_f32_16x16x32_bf16 v[178:181], v[20:23], v[64:67], v[52:55]
	v_mfma_f32_16x16x32_bf16 v[52:55], v[24:27], v[60:63], 0
	v_mfma_f32_16x16x32_bf16 v[182:185], v[28:31], v[64:67], v[52:55]
	v_mfma_f32_16x16x32_bf16 v[52:55], v[16:19], v[100:103], 0
	v_mfma_f32_16x16x32_bf16 v[16:19], v[16:19], v[108:111], 0
	v_mfma_f32_16x16x32_bf16 v[8:11], v[20:23], v[56:59], v[8:11]
	v_mfma_f32_16x16x32_bf16 v[12:15], v[28:31], v[56:59], v[12:15]
	v_mfma_f32_16x16x32_bf16 v[186:189], v[20:23], v[104:107], v[52:55]
	v_mfma_f32_16x16x32_bf16 v[52:55], v[24:27], v[100:103], 0
	v_mfma_f32_16x16x32_bf16 v[198:201], v[20:23], v[112:115], v[16:19]
	v_mfma_f32_16x16x32_bf16 v[16:19], v[24:27], v[108:111], 0
	v_mfma_f32_16x16x32_bf16 v[194:197], v[28:31], v[104:107], v[52:55]
	v_mfma_f32_16x16x32_bf16 v[202:205], v[28:31], v[112:115], v[16:19]
	s_barrier
	s_setprio 0
	s_add_i32 s19, 0, 0x18000
	s_add_i32 s36, 0, 0x1c000
	v_add_u32_e32 v28, s19, v214
	v_add_u32_e32 v52, s36, v214
	ds_read_b128 v[16:19], v28
	ds_read_b128 v[20:23], v28 offset:1024
	ds_read_b128 v[24:27], v28 offset:2048
	ds_read_b128 v[28:31], v28 offset:3072
	ds_read_b128 v[206:209], v52
	ds_read_b128 v[210:213], v52 offset:1024
	ds_read_b128 v[216:219], v52 offset:2048
	ds_read_b128 v[220:223], v52 offset:3072
	s_add_u32 s4, s82, 0x40100
	s_addc_u32 s5, s83, 0
	s_mov_b32 m0, s38
	v_lshl_add_u64 v[60:61], s[4:5], 0, v[50:51]
	ds_read_b128 v[52:55], v215 offset:32768
	ds_read_b128 v[56:59], v215 offset:33792
	ds_read_b128 v[224:227], v215 offset:34816
	ds_read_b128 v[228:231], v215 offset:35840
	ds_read_b128 v[232:235], v215 offset:36864
	ds_read_b128 v[236:239], v215 offset:37888
	ds_read_b128 v[240:243], v215 offset:38912
	ds_read_b128 v[244:247], v215 offset:39936
	global_load_lds_dwordx4 v[60:61], off
	v_lshl_add_u64 v[60:61], s[4:5], 0, v[120:121]
	s_mov_b32 m0, s39
	s_nop 0
	global_load_lds_dwordx4 v[60:61], off
	s_waitcnt vmcnt(8) lgkmcnt(0)
	s_setprio 1
	s_barrier
	v_mfma_f32_16x16x32_bf16 v[60:63], v[16:19], v[52:55], v[68:71]
	v_mfma_f32_16x16x32_bf16 v[174:177], v[20:23], v[56:59], v[60:63]
	v_mfma_f32_16x16x32_bf16 v[60:63], v[24:27], v[52:55], v[72:75]
	v_mfma_f32_16x16x32_bf16 v[166:169], v[28:31], v[56:59], v[60:63]
	v_mfma_f32_16x16x32_bf16 v[60:63], v[16:19], v[224:227], v[76:79]
	v_mfma_f32_16x16x32_bf16 v[156:159], v[20:23], v[228:231], v[60:63]
	v_mfma_f32_16x16x32_bf16 v[60:63], v[24:27], v[224:227], v[80:83]
	v_mfma_f32_16x16x32_bf16 v[116:119], v[28:31], v[228:231], v[60:63]
	v_mfma_f32_16x16x32_bf16 v[60:63], v[16:19], v[232:235], v[84:87]
	v_mfma_f32_16x16x32_bf16 v[112:115], v[20:23], v[236:239], v[60:63]
	v_mfma_f32_16x16x32_bf16 v[60:63], v[24:27], v[232:235], v[88:91]
	v_mfma_f32_16x16x32_bf16 v[108:111], v[28:31], v[236:239], v[60:63]
	v_mfma_f32_16x16x32_bf16 v[60:63], v[16:19], v[240:243], v[92:95]
	v_mfma_f32_16x16x32_bf16 v[104:107], v[20:23], v[244:247], v[60:63]
	v_mfma_f32_16x16x32_bf16 v[60:63], v[24:27], v[240:243], v[96:99]
	v_mfma_f32_16x16x32_bf16 v[100:103], v[28:31], v[244:247], v[60:63]
	v_mfma_f32_16x16x32_bf16 v[60:63], v[206:209], v[52:55], v[122:125]
	v_mfma_f32_16x16x32_bf16 v[32:35], v[216:219], v[52:55], v[32:35]
	v_mfma_f32_16x16x32_bf16 v[64:67], v[210:213], v[56:59], v[60:63]
	v_mfma_f32_16x16x32_bf16 v[60:63], v[220:223], v[56:59], v[32:35]
	v_mfma_f32_16x16x32_bf16 v[32:35], v[206:209], v[224:227], v[36:39]
	v_mfma_f32_16x16x32_bf16 v[56:59], v[210:213], v[228:231], v[32:35]
	v_mfma_f32_16x16x32_bf16 v[32:35], v[216:219], v[224:227], v[40:43]
	v_mfma_f32_16x16x32_bf16 v[52:55], v[220:223], v[228:231], v[32:35]
	v_mfma_f32_16x16x32_bf16 v[32:35], v[206:209], v[232:235], v[44:47]
	v_mfma_f32_16x16x32_bf16 v[44:47], v[210:213], v[236:239], v[32:35]
	v_mfma_f32_16x16x32_bf16 v[32:35], v[216:219], v[232:235], v[126:129]
	v_mfma_f32_16x16x32_bf16 v[40:43], v[220:223], v[236:239], v[32:35]
	v_mfma_f32_16x16x32_bf16 v[32:35], v[206:209], v[240:243], v[130:133]
	v_mfma_f32_16x16x32_bf16 v[36:39], v[210:213], v[244:247], v[32:35]
	v_mfma_f32_16x16x32_bf16 v[32:35], v[216:219], v[240:243], v[134:137]
	v_mov_b32_e32 v241, 0x7f
	v_mov_b64_e32 v[242:243], 0x400
	v_mfma_f32_16x16x32_bf16 v[32:35], v[220:223], v[244:247], v[32:35]
	v_mov_b32_e32 v247, 0x77
	v_mov_b32_e32 v246, 0x7c
	v_mov_b32_e32 v245, 0x7d
	v_mov_b32_e32 v244, 0x7e
	s_setprio 0
	s_barrier
	s_mov_b64 s[42:43], 0x180
	s_add_i32 s4, s19, s88
	v_lshl_add_u64 v[68:69], v[154:155], 0, s[42:43]
	s_mov_b32 m0, s4
	ds_read_b128 v[122:125], v215 offset:49152
	ds_read_b128 v[126:129], v215 offset:50176
	ds_read_b128 v[130:133], v215 offset:51200
	ds_read_b128 v[134:137], v215 offset:52224
	ds_read_b128 v[224:227], v215 offset:53248
	ds_read_b128 v[228:231], v215 offset:54272
	ds_read_b128 v[232:235], v215 offset:55296
	ds_read_b128 v[236:239], v215 offset:56320
	global_load_lds_dwordx4 v[68:69], off
	s_add_i32 m0, s4, 0x2000
	s_add_u32 s4, s24, 0x10180
	v_lshl_add_u64 v[68:69], v[190:191], 0, s[42:43]
	s_addc_u32 s5, s25, 0
	s_add_i32 s19, s36, s88
	global_load_lds_dwordx4 v[68:69], off
	v_lshl_add_u64 v[68:69], s[4:5], 0, v[48:49]
	s_mov_b32 m0, s19
	s_nop 0
	global_load_lds_dwordx4 v[68:69], off
	v_lshl_add_u64 v[68:69], s[4:5], 0, v[160:161]
	s_add_i32 m0, s19, 0x2000
	s_nop 0
	global_load_lds_dwordx4 v[68:69], off
	v_lshl_add_u64 v[68:69], v[248:249], 0, s[42:43]
	s_mov_b32 m0, s49
	v_mov_b32_e32 v248, 0x260
	global_load_lds_dwordx4 v[68:69], off
	v_lshl_add_u64 v[68:69], v[250:251], 0, s[42:43]
	s_mov_b32 m0, s52
	v_mov_b32_e32 v250, v253
	global_load_lds_dwordx4 v[68:69], off
	s_waitcnt vmcnt(8)
	s_waitcnt lgkmcnt(0)
	v_mov_b32_e32 v253, v252
	s_barrier
	s_setprio 1
	s_waitcnt lgkmcnt(0)
	v_mfma_f32_16x16x32_bf16 v[68:71], v[16:19], v[122:125], v[138:141]
	v_mfma_f32_16x16x32_bf16 v[96:99], v[20:23], v[126:129], v[68:71]
	v_mfma_f32_16x16x32_bf16 v[68:71], v[24:27], v[122:125], v[142:145]
	v_mfma_f32_16x16x32_bf16 v[92:95], v[28:31], v[126:129], v[68:71]
	v_mfma_f32_16x16x32_bf16 v[68:71], v[16:19], v[130:133], v[146:149]
	v_mfma_f32_16x16x32_bf16 v[88:91], v[20:23], v[134:137], v[68:71]
	v_mfma_f32_16x16x32_bf16 v[68:71], v[24:27], v[130:133], v[150:153]
	v_mfma_f32_16x16x32_bf16 v[84:87], v[28:31], v[134:137], v[68:71]
	v_mfma_f32_16x16x32_bf16 v[68:71], v[16:19], v[224:227], v[162:165]
	v_mfma_f32_16x16x32_bf16 v[0:3], v[16:19], v[232:235], v[0:3]
	v_mfma_f32_16x16x32_bf16 v[80:83], v[20:23], v[228:231], v[68:71]
	v_mfma_f32_16x16x32_bf16 v[68:71], v[24:27], v[224:227], v[170:173]
	v_mfma_f32_16x16x32_bf16 v[72:75], v[20:23], v[236:239], v[0:3]
	v_mfma_f32_16x16x32_bf16 v[0:3], v[24:27], v[232:235], v[4:7]
	v_mfma_f32_16x16x32_bf16 v[76:79], v[28:31], v[228:231], v[68:71]
	v_mfma_f32_16x16x32_bf16 v[68:71], v[28:31], v[236:239], v[0:3]
	v_mfma_f32_16x16x32_bf16 v[0:3], v[206:209], v[122:125], v[8:11]
	v_mfma_f32_16x16x32_bf16 v[28:31], v[210:213], v[126:129], v[0:3]
	v_mfma_f32_16x16x32_bf16 v[0:3], v[216:219], v[122:125], v[12:15]
	v_mfma_f32_16x16x32_bf16 v[24:27], v[220:223], v[126:129], v[0:3]
	v_mfma_f32_16x16x32_bf16 v[0:3], v[206:209], v[130:133], v[178:181]
	v_mfma_f32_16x16x32_bf16 v[20:23], v[210:213], v[134:137], v[0:3]
	v_mfma_f32_16x16x32_bf16 v[0:3], v[216:219], v[130:133], v[182:185]
	v_mfma_f32_16x16x32_bf16 v[16:19], v[220:223], v[134:137], v[0:3]
	v_mfma_f32_16x16x32_bf16 v[0:3], v[206:209], v[224:227], v[186:189]
	v_mfma_f32_16x16x32_bf16 v[12:15], v[210:213], v[228:231], v[0:3]
	v_mfma_f32_16x16x32_bf16 v[0:3], v[216:219], v[224:227], v[194:197]
	v_mfma_f32_16x16x32_bf16 v[8:11], v[220:223], v[228:231], v[0:3]
	v_mfma_f32_16x16x32_bf16 v[0:3], v[206:209], v[232:235], v[198:201]
	v_mfma_f32_16x16x32_bf16 v[4:7], v[210:213], v[236:239], v[0:3]
	v_mfma_f32_16x16x32_bf16 v[0:3], v[216:219], v[232:235], v[202:205]
	v_mfma_f32_16x16x32_bf16 v[0:3], v[220:223], v[236:239], v[0:3]
	s_barrier
	s_setprio 0
	s_mov_b32 s19, 2

.LBB0_696:
	s_add_i32 s92, s19, 2
	s_or_b32 s94, s19, 1
	s_lshl_b64 s[4:5], s[92:93], 7
	s_add_u32 s42, s82, s4
	s_addc_u32 s43, s83, s5
	s_add_u32 s4, s24, s4
	s_addc_u32 s5, s25, s5
	s_add_i32 s80, 0, 0x10000
	s_cmp_eq_u32 s19, 2
	s_cselect_b32 s43, s77, s43
	s_cselect_b32 s42, s76, s42
	s_cselect_b32 s5, s36, s5
	s_cselect_b32 s4, s37, s4
	s_add_i32 s81, 0, 0x14000
	v_add_u32_e32 v134, s80, v214
	v_add_u32_e32 v150, s81, v214
	ds_read_b128 v[122:125], v134
	ds_read_b128 v[126:129], v134 offset:1024
	ds_read_b128 v[130:133], v134 offset:2048
	ds_read_b128 v[134:137], v134 offset:3072
	ds_read_b128 v[138:141], v150
	ds_read_b128 v[142:145], v150 offset:1024
	ds_read_b128 v[146:149], v150 offset:2048
	ds_read_b128 v[150:153], v150 offset:3072
	s_mov_b32 s95, s93
	s_lshl_b64 s[94:95], s[94:95], 7
	s_add_u32 s94, s73, s94
	s_addc_u32 s95, s75, s95
	v_lshl_add_u64 v[154:155], s[94:95], 0, v[50:51]
	s_add_i32 m0, s23, 0xc000
	ds_read_b128 v[162:165], v215
	ds_read_b128 v[170:173], v215 offset:1024
	ds_read_b128 v[178:181], v215 offset:2048
	ds_read_b128 v[182:185], v215 offset:3072
	ds_read_b128 v[186:189], v215 offset:4096
	ds_read_b128 v[194:197], v215 offset:5120
	ds_read_b128 v[198:201], v215 offset:6144
	ds_read_b128 v[202:205], v215 offset:7168
	global_load_lds_dwordx4 v[154:155], off
	v_lshl_add_u64 v[154:155], s[94:95], 0, v[120:121]
	s_add_i32 m0, s23, 0xe000
	s_nop 0
	global_load_lds_dwordx4 v[154:155], off
	s_waitcnt vmcnt(8) lgkmcnt(0)
	s_setprio 1
	s_barrier
	v_mfma_f32_16x16x32_bf16 v[174:177], v[122:125], v[162:165], v[174:177]
	v_mfma_f32_16x16x32_bf16 v[166:169], v[130:133], v[162:165], v[166:169]
	v_mfma_f32_16x16x32_bf16 v[154:157], v[122:125], v[178:181], v[156:159]
	v_mfma_f32_16x16x32_bf16 v[116:119], v[130:133], v[178:181], v[116:119]
	v_mfma_f32_16x16x32_bf16 v[112:115], v[122:125], v[186:189], v[112:115]
	v_mfma_f32_16x16x32_bf16 v[108:111], v[130:133], v[186:189], v[108:111]
	v_mfma_f32_16x16x32_bf16 v[104:107], v[122:125], v[198:201], v[104:107]
	v_mfma_f32_16x16x32_bf16 v[100:103], v[130:133], v[198:201], v[100:103]
	v_mfma_f32_16x16x32_bf16 v[174:177], v[126:129], v[170:173], v[174:177]
	v_mfma_f32_16x16x32_bf16 v[166:169], v[134:137], v[170:173], v[166:169]
	v_mfma_f32_16x16x32_bf16 v[154:157], v[126:129], v[182:185], v[154:157]
	v_mfma_f32_16x16x32_bf16 v[116:119], v[134:137], v[182:185], v[116:119]
	v_mfma_f32_16x16x32_bf16 v[112:115], v[126:129], v[194:197], v[112:115]
	v_mfma_f32_16x16x32_bf16 v[108:111], v[134:137], v[194:197], v[108:111]
	v_mfma_f32_16x16x32_bf16 v[104:107], v[126:129], v[202:205], v[104:107]
	v_mfma_f32_16x16x32_bf16 v[100:103], v[134:137], v[202:205], v[100:103]
	v_mfma_f32_16x16x32_bf16 v[64:67], v[138:141], v[162:165], v[64:67]
	v_mfma_f32_16x16x32_bf16 v[60:63], v[146:149], v[162:165], v[60:63]
	v_mfma_f32_16x16x32_bf16 v[56:59], v[138:141], v[178:181], v[56:59]
	v_mfma_f32_16x16x32_bf16 v[52:55], v[146:149], v[178:181], v[52:55]
	v_mfma_f32_16x16x32_bf16 v[44:47], v[138:141], v[186:189], v[44:47]
	v_mfma_f32_16x16x32_bf16 v[40:43], v[146:149], v[186:189], v[40:43]
	v_mfma_f32_16x16x32_bf16 v[36:39], v[138:141], v[198:201], v[36:39]
	v_mfma_f32_16x16x32_bf16 v[32:35], v[146:149], v[198:201], v[32:35]
	v_mfma_f32_16x16x32_bf16 v[64:67], v[142:145], v[170:173], v[64:67]
	v_mfma_f32_16x16x32_bf16 v[60:63], v[150:153], v[170:173], v[60:63]
	v_mfma_f32_16x16x32_bf16 v[56:59], v[142:145], v[182:185], v[56:59]
	v_mfma_f32_16x16x32_bf16 v[52:55], v[150:153], v[182:185], v[52:55]
	v_mfma_f32_16x16x32_bf16 v[44:47], v[142:145], v[194:197], v[44:47]
	v_mfma_f32_16x16x32_bf16 v[40:43], v[150:153], v[194:197], v[40:43]
	v_mfma_f32_16x16x32_bf16 v[36:39], v[142:145], v[202:205], v[36:39]
	v_mfma_f32_16x16x32_bf16 v[32:35], v[150:153], v[202:205], v[32:35]
	s_barrier
	s_setprio 0
	s_add_i32 s80, s80, s88
	v_lshl_add_u64 v[190:191], s[4:5], 0, v[48:49]
	s_mov_b32 m0, s80
	ds_read_b128 v[162:165], v215 offset:16384
	ds_read_b128 v[170:173], v215 offset:17408
	ds_read_b128 v[178:181], v215 offset:18432
	ds_read_b128 v[182:185], v215 offset:19456
	ds_read_b128 v[186:189], v215 offset:20480
	ds_read_b128 v[194:197], v215 offset:21504
	ds_read_b128 v[198:201], v215 offset:22528
	ds_read_b128 v[202:205], v215 offset:23552
	global_load_lds_dwordx4 v[190:191], off
	s_add_i32 m0, s80, 0x2000
	s_add_u32 s94, s4, 0x10000
	v_lshl_add_u64 v[206:207], s[4:5], 0, v[160:161]
	s_addc_u32 s95, s5, 0
	s_add_i32 s80, s81, s88
	global_load_lds_dwordx4 v[206:207], off
	v_lshl_add_u64 v[158:159], s[94:95], 0, v[48:49]
	s_mov_b32 m0, s80
	v_lshl_add_u64 v[208:209], s[42:43], 0, v[50:51]
	global_load_lds_dwordx4 v[158:159], off
	v_lshl_add_u64 v[158:159], s[94:95], 0, v[160:161]
	s_add_i32 m0, s80, 0x2000
	v_lshl_add_u64 v[210:211], s[42:43], 0, v[120:121]
	global_load_lds_dwordx4 v[158:159], off
	s_mov_b32 m0, s23
	s_nop 0
	global_load_lds_dwordx4 v[208:209], off
	s_mov_b32 m0, s91
	s_nop 0
	global_load_lds_dwordx4 v[210:211], off
	s_waitcnt vmcnt(8) lgkmcnt(0)
	s_setprio 1
	s_barrier
	v_mfma_f32_16x16x32_bf16 v[96:99], v[122:125], v[162:165], v[96:99]
	v_mfma_f32_16x16x32_bf16 v[92:95], v[130:133], v[162:165], v[92:95]
	v_mfma_f32_16x16x32_bf16 v[88:91], v[122:125], v[178:181], v[88:91]
	v_mfma_f32_16x16x32_bf16 v[84:87], v[130:133], v[178:181], v[84:87]
	v_mfma_f32_16x16x32_bf16 v[80:83], v[122:125], v[186:189], v[80:83]
	v_mfma_f32_16x16x32_bf16 v[76:79], v[130:133], v[186:189], v[76:79]
	v_mfma_f32_16x16x32_bf16 v[72:75], v[122:125], v[198:201], v[72:75]
	v_mfma_f32_16x16x32_bf16 v[68:71], v[130:133], v[198:201], v[68:71]
	v_mfma_f32_16x16x32_bf16 v[96:99], v[126:129], v[170:173], v[96:99]
	v_mfma_f32_16x16x32_bf16 v[92:95], v[134:137], v[170:173], v[92:95]
	v_mfma_f32_16x16x32_bf16 v[88:91], v[126:129], v[182:185], v[88:91]
	v_mfma_f32_16x16x32_bf16 v[84:87], v[134:137], v[182:185], v[84:87]
	v_mfma_f32_16x16x32_bf16 v[80:83], v[126:129], v[194:197], v[80:83]
	v_mfma_f32_16x16x32_bf16 v[76:79], v[134:137], v[194:197], v[76:79]
	v_mfma_f32_16x16x32_bf16 v[72:75], v[126:129], v[202:205], v[72:75]
	v_mfma_f32_16x16x32_bf16 v[68:71], v[134:137], v[202:205], v[68:71]
	v_mfma_f32_16x16x32_bf16 v[28:31], v[138:141], v[162:165], v[28:31]
	v_mfma_f32_16x16x32_bf16 v[24:27], v[146:149], v[162:165], v[24:27]
	v_mfma_f32_16x16x32_bf16 v[20:23], v[138:141], v[178:181], v[20:23]
	v_mfma_f32_16x16x32_bf16 v[16:19], v[146:149], v[178:181], v[16:19]
	v_mfma_f32_16x16x32_bf16 v[12:15], v[138:141], v[186:189], v[12:15]
	v_mfma_f32_16x16x32_bf16 v[8:11], v[146:149], v[186:189], v[8:11]
	v_mfma_f32_16x16x32_bf16 v[4:7], v[138:141], v[198:201], v[4:7]
	v_mfma_f32_16x16x32_bf16 v[0:3], v[146:149], v[198:201], v[0:3]
	v_mfma_f32_16x16x32_bf16 v[28:31], v[142:145], v[170:173], v[28:31]
	v_mfma_f32_16x16x32_bf16 v[24:27], v[150:153], v[170:173], v[24:27]
	v_mfma_f32_16x16x32_bf16 v[20:23], v[142:145], v[182:185], v[20:23]
	v_mfma_f32_16x16x32_bf16 v[16:19], v[150:153], v[182:185], v[16:19]
	v_mfma_f32_16x16x32_bf16 v[12:15], v[142:145], v[194:197], v[12:15]
	v_mfma_f32_16x16x32_bf16 v[8:11], v[150:153], v[194:197], v[8:11]
	v_mfma_f32_16x16x32_bf16 v[4:7], v[142:145], v[202:205], v[4:7]
	v_mfma_f32_16x16x32_bf16 v[0:3], v[150:153], v[202:205], v[0:3]
	s_barrier
	s_setprio 0
	s_add_i32 s80, 0, 0x18000
	s_add_i32 s81, 0, 0x1c000
	v_add_u32_e32 v134, s80, v214
	v_add_u32_e32 v150, s81, v214
	ds_read_b128 v[122:125], v134
	ds_read_b128 v[126:129], v134 offset:1024
	ds_read_b128 v[130:133], v134 offset:2048
	ds_read_b128 v[134:137], v134 offset:3072
	ds_read_b128 v[138:141], v150
	ds_read_b128 v[142:145], v150 offset:1024
	ds_read_b128 v[146:149], v150 offset:2048
	ds_read_b128 v[150:153], v150 offset:3072
	s_add_u32 s42, s42, 0x40000
	s_addc_u32 s43, s43, 0
	s_mov_b32 m0, s38
	v_lshl_add_u64 v[158:159], s[42:43], 0, v[50:51]
	ds_read_b128 v[162:165], v215 offset:32768
	ds_read_b128 v[170:173], v215 offset:33792
	ds_read_b128 v[178:181], v215 offset:34816
	ds_read_b128 v[182:185], v215 offset:35840
	ds_read_b128 v[186:189], v215 offset:36864
	ds_read_b128 v[194:197], v215 offset:37888
	ds_read_b128 v[198:201], v215 offset:38912
	ds_read_b128 v[202:205], v215 offset:39936
	global_load_lds_dwordx4 v[158:159], off
	v_lshl_add_u64 v[158:159], s[42:43], 0, v[120:121]
	s_mov_b32 m0, s39
	s_nop 0
	global_load_lds_dwordx4 v[158:159], off
	s_waitcnt vmcnt(8) lgkmcnt(0)
	s_setprio 1
	s_barrier
	v_mfma_f32_16x16x32_bf16 v[174:177], v[122:125], v[162:165], v[174:177]
	v_mfma_f32_16x16x32_bf16 v[166:169], v[130:133], v[162:165], v[166:169]
	v_mfma_f32_16x16x32_bf16 v[154:157], v[122:125], v[178:181], v[154:157]
	v_mfma_f32_16x16x32_bf16 v[116:119], v[130:133], v[178:181], v[116:119]
	v_mfma_f32_16x16x32_bf16 v[112:115], v[122:125], v[186:189], v[112:115]
	v_mfma_f32_16x16x32_bf16 v[108:111], v[130:133], v[186:189], v[108:111]
	v_mfma_f32_16x16x32_bf16 v[104:107], v[122:125], v[198:201], v[104:107]
	v_mfma_f32_16x16x32_bf16 v[100:103], v[130:133], v[198:201], v[100:103]
	v_mfma_f32_16x16x32_bf16 v[174:177], v[126:129], v[170:173], v[174:177]
	v_mfma_f32_16x16x32_bf16 v[166:169], v[134:137], v[170:173], v[166:169]
	v_mfma_f32_16x16x32_bf16 v[156:159], v[126:129], v[182:185], v[154:157]
	v_mfma_f32_16x16x32_bf16 v[116:119], v[134:137], v[182:185], v[116:119]
	v_mfma_f32_16x16x32_bf16 v[112:115], v[126:129], v[194:197], v[112:115]
	v_mfma_f32_16x16x32_bf16 v[108:111], v[134:137], v[194:197], v[108:111]
	v_mfma_f32_16x16x32_bf16 v[104:107], v[126:129], v[202:205], v[104:107]
	v_mfma_f32_16x16x32_bf16 v[100:103], v[134:137], v[202:205], v[100:103]
	v_mfma_f32_16x16x32_bf16 v[64:67], v[138:141], v[162:165], v[64:67]
	v_mfma_f32_16x16x32_bf16 v[60:63], v[146:149], v[162:165], v[60:63]
	v_mfma_f32_16x16x32_bf16 v[56:59], v[138:141], v[178:181], v[56:59]
	v_mfma_f32_16x16x32_bf16 v[52:55], v[146:149], v[178:181], v[52:55]
	v_mfma_f32_16x16x32_bf16 v[44:47], v[138:141], v[186:189], v[44:47]
	v_mfma_f32_16x16x32_bf16 v[40:43], v[146:149], v[186:189], v[40:43]
	v_mfma_f32_16x16x32_bf16 v[36:39], v[138:141], v[198:201], v[36:39]
	v_mfma_f32_16x16x32_bf16 v[32:35], v[146:149], v[198:201], v[32:35]
	v_mfma_f32_16x16x32_bf16 v[64:67], v[142:145], v[170:173], v[64:67]
	v_mfma_f32_16x16x32_bf16 v[60:63], v[150:153], v[170:173], v[60:63]
	v_mfma_f32_16x16x32_bf16 v[56:59], v[142:145], v[182:185], v[56:59]
	v_mfma_f32_16x16x32_bf16 v[52:55], v[150:153], v[182:185], v[52:55]
	v_mfma_f32_16x16x32_bf16 v[44:47], v[142:145], v[194:197], v[44:47]
	v_mfma_f32_16x16x32_bf16 v[40:43], v[150:153], v[194:197], v[40:43]
	v_mfma_f32_16x16x32_bf16 v[36:39], v[142:145], v[202:205], v[36:39]
	v_mfma_f32_16x16x32_bf16 v[32:35], v[150:153], v[202:205], v[32:35]
	s_barrier
	s_setprio 0
	s_add_i32 s42, s80, s88
	v_lshl_add_u64 v[154:155], v[190:191], 0, s[14:15]
	s_mov_b32 m0, s42
	ds_read_b128 v[162:165], v215 offset:49152
	ds_read_b128 v[170:173], v215 offset:50176
	ds_read_b128 v[178:181], v215 offset:51200
	ds_read_b128 v[182:185], v215 offset:52224
	ds_read_b128 v[186:189], v215 offset:53248
	ds_read_b128 v[194:197], v215 offset:54272
	ds_read_b128 v[198:201], v215 offset:55296
	ds_read_b128 v[202:205], v215 offset:56320
	global_load_lds_dwordx4 v[154:155], off
	s_add_i32 m0, s42, 0x2000
	s_add_u32 s4, s4, 0x10080
	v_lshl_add_u64 v[154:155], v[206:207], 0, s[14:15]
	s_addc_u32 s5, s5, 0
	s_add_i32 s42, s81, s88
	global_load_lds_dwordx4 v[154:155], off
	v_lshl_add_u64 v[154:155], s[4:5], 0, v[48:49]
	s_mov_b32 m0, s42
	s_nop 0
	global_load_lds_dwordx4 v[154:155], off
	v_lshl_add_u64 v[154:155], s[4:5], 0, v[160:161]
	s_add_i32 m0, s42, 0x2000
	s_nop 0
	global_load_lds_dwordx4 v[154:155], off
	v_lshl_add_u64 v[154:155], v[208:209], 0, s[14:15]
	s_mov_b32 m0, s49
	s_nop 0
	global_load_lds_dwordx4 v[154:155], off
	v_lshl_add_u64 v[154:155], v[210:211], 0, s[14:15]
	s_mov_b32 m0, s52
	s_nop 0
	global_load_lds_dwordx4 v[154:155], off
	s_waitcnt vmcnt(8) lgkmcnt(0)
	s_setprio 1
	s_barrier
	v_mfma_f32_16x16x32_bf16 v[96:99], v[122:125], v[162:165], v[96:99]
	v_mfma_f32_16x16x32_bf16 v[92:95], v[130:133], v[162:165], v[92:95]
	v_mfma_f32_16x16x32_bf16 v[88:91], v[122:125], v[178:181], v[88:91]
	v_mfma_f32_16x16x32_bf16 v[84:87], v[130:133], v[178:181], v[84:87]
	v_mfma_f32_16x16x32_bf16 v[80:83], v[122:125], v[186:189], v[80:83]
	v_mfma_f32_16x16x32_bf16 v[76:79], v[130:133], v[186:189], v[76:79]
	v_mfma_f32_16x16x32_bf16 v[72:75], v[122:125], v[198:201], v[72:75]
	v_mfma_f32_16x16x32_bf16 v[68:71], v[130:133], v[198:201], v[68:71]
	v_mfma_f32_16x16x32_bf16 v[96:99], v[126:129], v[170:173], v[96:99]
	v_mfma_f32_16x16x32_bf16 v[92:95], v[134:137], v[170:173], v[92:95]
	v_mfma_f32_16x16x32_bf16 v[88:91], v[126:129], v[182:185], v[88:91]
	v_mfma_f32_16x16x32_bf16 v[84:87], v[134:137], v[182:185], v[84:87]
	v_mfma_f32_16x16x32_bf16 v[80:83], v[126:129], v[194:197], v[80:83]
	v_mfma_f32_16x16x32_bf16 v[76:79], v[134:137], v[194:197], v[76:79]
	v_mfma_f32_16x16x32_bf16 v[72:75], v[126:129], v[202:205], v[72:75]
	v_mfma_f32_16x16x32_bf16 v[68:71], v[134:137], v[202:205], v[68:71]
	v_mfma_f32_16x16x32_bf16 v[28:31], v[138:141], v[162:165], v[28:31]
	v_mfma_f32_16x16x32_bf16 v[24:27], v[146:149], v[162:165], v[24:27]
	v_mfma_f32_16x16x32_bf16 v[20:23], v[138:141], v[178:181], v[20:23]
	v_mfma_f32_16x16x32_bf16 v[16:19], v[146:149], v[178:181], v[16:19]
	v_mfma_f32_16x16x32_bf16 v[12:15], v[138:141], v[186:189], v[12:15]
	v_mfma_f32_16x16x32_bf16 v[8:11], v[146:149], v[186:189], v[8:11]
	v_mfma_f32_16x16x32_bf16 v[4:7], v[138:141], v[198:201], v[4:7]
	v_mfma_f32_16x16x32_bf16 v[0:3], v[146:149], v[198:201], v[0:3]
	v_mfma_f32_16x16x32_bf16 v[28:31], v[142:145], v[170:173], v[28:31]
	v_mfma_f32_16x16x32_bf16 v[24:27], v[150:153], v[170:173], v[24:27]
	v_mfma_f32_16x16x32_bf16 v[20:23], v[142:145], v[182:185], v[20:23]
	v_mfma_f32_16x16x32_bf16 v[16:19], v[150:153], v[182:185], v[16:19]
	v_mfma_f32_16x16x32_bf16 v[12:15], v[142:145], v[194:197], v[12:15]
	v_mfma_f32_16x16x32_bf16 v[8:11], v[150:153], v[194:197], v[8:11]
	v_mfma_f32_16x16x32_bf16 v[4:7], v[142:145], v[202:205], v[4:7]
	v_mfma_f32_16x16x32_bf16 v[0:3], v[150:153], v[202:205], v[0:3]
	s_barrier
	s_setprio 0
	s_cmp_lg_u32 s19, 0
	s_mov_b32 s19, 2
	s_cbranch_scc0 .LBB0_696
	s_and_b64 vcc, exec, s[68:69]
	s_cbranch_vccz .LBB0_699
	s_barrier

.LBB0_786:
.LBB0_787:
	s_add_i32 s9, 0, 0x10000
	s_add_i32 s19, 0, 0x14000
	v_add_u32_e32 v12, s9, v175
	v_add_u32_e32 v28, s19, v175
	ds_read_b128 v[0:3], v12
	ds_read_b128 v[4:7], v12 offset:1024
	ds_read_b128 v[8:11], v12 offset:2048
	ds_read_b128 v[12:15], v12 offset:3072
	ds_read_b128 v[16:19], v28
	ds_read_b128 v[20:23], v28 offset:1024
	ds_read_b128 v[24:27], v28 offset:2048
	ds_read_b128 v[28:31], v28 offset:3072
	s_add_u32 s36, s24, 0x40080
	s_addc_u32 s37, s25, 0
	v_lshl_add_u64 v[64:65], s[36:37], 0, v[122:123]
	s_add_i32 m0, s88, 0xc000
	ds_read_b128 v[32:35], v179
	ds_read_b128 v[36:39], v179 offset:1024
	ds_read_b128 v[40:43], v179 offset:2048
	ds_read_b128 v[44:47], v179 offset:3072
	ds_read_b128 v[48:51], v179 offset:4096
	ds_read_b128 v[52:55], v179 offset:5120
	ds_read_b128 v[56:59], v179 offset:6144
	ds_read_b128 v[60:63], v179 offset:7168
	global_load_lds_dwordx4 v[64:65], off
	v_lshl_add_u64 v[64:65], s[36:37], 0, v[124:125]
	s_add_i32 m0, s88, 0xe000
	s_nop 0
	global_load_lds_dwordx4 v[64:65], off
	s_waitcnt vmcnt(32) lgkmcnt(0)
	s_setprio 1
	s_barrier
	v_mfma_f32_16x16x32_bf16 v[64:67], v[0:3], v[32:35], 0
	v_mfma_f32_16x16x32_bf16 v[68:71], v[8:11], v[32:35], 0
	v_mfma_f32_16x16x32_bf16 v[72:75], v[0:3], v[40:43], 0
	v_mfma_f32_16x16x32_bf16 v[76:79], v[8:11], v[40:43], 0
	v_mfma_f32_16x16x32_bf16 v[80:83], v[0:3], v[48:51], 0
	v_mfma_f32_16x16x32_bf16 v[84:87], v[8:11], v[48:51], 0
	v_mfma_f32_16x16x32_bf16 v[88:91], v[0:3], v[56:59], 0
	v_mfma_f32_16x16x32_bf16 v[92:95], v[8:11], v[56:59], 0
	v_mfma_f32_16x16x32_bf16 v[116:119], v[4:7], v[36:39], v[64:67]
	v_mfma_f32_16x16x32_bf16 v[68:71], v[12:15], v[36:39], v[68:71]
	v_mfma_f32_16x16x32_bf16 v[72:75], v[4:7], v[44:47], v[72:75]
	v_mfma_f32_16x16x32_bf16 v[76:79], v[12:15], v[44:47], v[76:79]
	v_mfma_f32_16x16x32_bf16 v[80:83], v[4:7], v[52:55], v[80:83]
	v_mfma_f32_16x16x32_bf16 v[84:87], v[12:15], v[52:55], v[84:87]
	v_mfma_f32_16x16x32_bf16 v[88:91], v[4:7], v[60:63], v[88:91]
	v_mfma_f32_16x16x32_bf16 v[92:95], v[12:15], v[60:63], v[92:95]
	v_mfma_f32_16x16x32_bf16 v[96:99], v[16:19], v[32:35], 0
	v_mfma_f32_16x16x32_bf16 v[32:35], v[24:27], v[32:35], 0
	v_mfma_f32_16x16x32_bf16 v[126:129], v[20:23], v[36:39], v[96:99]
	v_mfma_f32_16x16x32_bf16 v[32:35], v[28:31], v[36:39], v[32:35]
	v_mfma_f32_16x16x32_bf16 v[36:39], v[16:19], v[40:43], 0
	v_mfma_f32_16x16x32_bf16 v[40:43], v[24:27], v[40:43], 0
	v_mfma_f32_16x16x32_bf16 v[36:39], v[20:23], v[44:47], v[36:39]
	v_mfma_f32_16x16x32_bf16 v[40:43], v[28:31], v[44:47], v[40:43]
	v_mfma_f32_16x16x32_bf16 v[44:47], v[16:19], v[48:51], 0
	v_mfma_f32_16x16x32_bf16 v[48:51], v[24:27], v[48:51], 0
	v_mfma_f32_16x16x32_bf16 v[130:133], v[28:31], v[52:55], v[48:51]
	v_mfma_f32_16x16x32_bf16 v[48:51], v[16:19], v[56:59], 0
	v_mfma_f32_16x16x32_bf16 v[44:47], v[20:23], v[52:55], v[44:47]
	v_mfma_f32_16x16x32_bf16 v[134:137], v[20:23], v[60:63], v[48:51]
	v_mfma_f32_16x16x32_bf16 v[48:51], v[24:27], v[56:59], 0
	v_mfma_f32_16x16x32_bf16 v[138:141], v[28:31], v[60:63], v[48:51]
	s_barrier
	s_setprio 0
	v_lshl_add_u64 v[158:159], s[22:23], 0, v[120:121]
	s_add_i32 s9, s9, s87
	v_lshl_add_u64 v[112:113], v[158:159], 0, s[16:17]
	s_mov_b32 m0, s9
	s_nop 0
	ds_read_b128 v[48:51], v179 offset:16384
	ds_read_b128 v[52:55], v179 offset:17408
	ds_read_b128 v[56:59], v179 offset:18432
	ds_read_b128 v[60:63], v179 offset:19456
	ds_read_b128 v[96:99], v179 offset:20480
	ds_read_b128 v[100:103], v179 offset:21504
	ds_read_b128 v[104:107], v179 offset:22528
	ds_read_b128 v[108:111], v179 offset:23552
	global_load_lds_dwordx4 v[112:113], off
	s_add_i32 m0, s9, 0x2000
	v_lshl_add_u64 v[176:177], s[22:23], 0, v[160:161]
	s_add_u32 s36, s22, 0x40100
	v_lshl_add_u64 v[112:113], v[176:177], 0, s[16:17]
	s_addc_u32 s37, s23, 0
	s_add_i32 s9, s19, s87
	global_load_lds_dwordx4 v[112:113], off
	v_lshl_add_u64 v[112:113], s[36:37], 0, v[120:121]
	s_mov_b32 m0, s9
	v_lshl_add_u64 v[188:189], s[24:25], 0, v[122:123]
	global_load_lds_dwordx4 v[112:113], off
	v_lshl_add_u64 v[112:113], s[36:37], 0, v[160:161]
	s_add_i32 m0, s9, 0x2000
	v_lshl_add_u64 v[190:191], s[24:25], 0, v[124:125]
	global_load_lds_dwordx4 v[112:113], off
	v_lshl_add_u64 v[112:113], v[188:189], 0, s[16:17]
	s_mov_b32 m0, s88
	s_nop 0
	global_load_lds_dwordx4 v[112:113], off
	v_lshl_add_u64 v[112:113], v[190:191], 0, s[16:17]
	s_mov_b32 m0, s89
	s_nop 0
	global_load_lds_dwordx4 v[112:113], off
	s_waitcnt vmcnt(32) lgkmcnt(0)
	s_setprio 1
	s_barrier
	v_mfma_f32_16x16x32_bf16 v[112:115], v[0:3], v[48:51], 0
	v_mfma_f32_16x16x32_bf16 v[142:145], v[4:7], v[52:55], v[112:115]
	v_mfma_f32_16x16x32_bf16 v[112:115], v[8:11], v[48:51], 0
	v_mfma_f32_16x16x32_bf16 v[146:149], v[12:15], v[52:55], v[112:115]
	v_mfma_f32_16x16x32_bf16 v[112:115], v[0:3], v[56:59], 0
	v_mfma_f32_16x16x32_bf16 v[150:153], v[4:7], v[60:63], v[112:115]
	v_mfma_f32_16x16x32_bf16 v[112:115], v[8:11], v[56:59], 0
	v_mfma_f32_16x16x32_bf16 v[154:157], v[12:15], v[60:63], v[112:115]
	v_mfma_f32_16x16x32_bf16 v[112:115], v[0:3], v[96:99], 0
	v_mfma_f32_16x16x32_bf16 v[0:3], v[0:3], v[104:107], 0
	v_mfma_f32_16x16x32_bf16 v[162:165], v[4:7], v[100:103], v[112:115]
	v_mfma_f32_16x16x32_bf16 v[0:3], v[4:7], v[108:111], v[0:3]
	v_mfma_f32_16x16x32_bf16 v[4:7], v[8:11], v[104:107], 0
	v_mfma_f32_16x16x32_bf16 v[112:115], v[8:11], v[96:99], 0
	v_mfma_f32_16x16x32_bf16 v[4:7], v[12:15], v[108:111], v[4:7]
	v_mfma_f32_16x16x32_bf16 v[166:169], v[12:15], v[100:103], v[112:115]
	v_mfma_f32_16x16x32_bf16 v[12:15], v[24:27], v[48:51], 0
	v_mfma_f32_16x16x32_bf16 v[170:173], v[28:31], v[52:55], v[12:15]
	v_mfma_f32_16x16x32_bf16 v[12:15], v[16:19], v[56:59], 0
	v_mfma_f32_16x16x32_bf16 v[180:183], v[20:23], v[60:63], v[12:15]
	v_mfma_f32_16x16x32_bf16 v[12:15], v[24:27], v[56:59], 0
	v_mfma_f32_16x16x32_bf16 v[184:187], v[28:31], v[60:63], v[12:15]
	v_mfma_f32_16x16x32_bf16 v[12:15], v[16:19], v[96:99], 0
	v_mfma_f32_16x16x32_bf16 v[194:197], v[20:23], v[100:103], v[12:15]
	v_mfma_f32_16x16x32_bf16 v[12:15], v[24:27], v[96:99], 0
	v_mfma_f32_16x16x32_bf16 v[8:11], v[16:19], v[48:51], 0
	v_mfma_f32_16x16x32_bf16 v[198:201], v[28:31], v[100:103], v[12:15]
	v_mfma_f32_16x16x32_bf16 v[12:15], v[16:19], v[104:107], 0
	v_mfma_f32_16x16x32_bf16 v[8:11], v[20:23], v[52:55], v[8:11]
	v_mfma_f32_16x16x32_bf16 v[202:205], v[20:23], v[108:111], v[12:15]
	v_mfma_f32_16x16x32_bf16 v[12:15], v[24:27], v[104:107], 0
	v_mfma_f32_16x16x32_bf16 v[206:209], v[28:31], v[108:111], v[12:15]
	s_barrier
	s_setprio 0
	s_add_i32 s9, 0, 0x18000
	s_nop 3
	v_add_u32_e32 v12, s9, v175
	s_add_i32 s19, 0, 0x1c000
	ds_read_b128 v[16:19], v12
	ds_read_b128 v[24:27], v12 offset:1024
	ds_read_b128 v[28:31], v12 offset:2048
	ds_read_b128 v[210:213], v12 offset:3072
	v_add_u32_e32 v12, s19, v175
	ds_read_b128 v[214:217], v12
	ds_read_b128 v[218:221], v12 offset:1024
	ds_read_b128 v[222:225], v12 offset:2048
	ds_read_b128 v[226:229], v12 offset:3072
	s_add_u32 s36, s24, 0x40100
	s_addc_u32 s37, s25, 0
	s_mov_b32 m0, s90
	v_lshl_add_u64 v[12:13], s[36:37], 0, v[122:123]
	ds_read_b128 v[48:51], v179 offset:32768
	ds_read_b128 v[52:55], v179 offset:33792
	ds_read_b128 v[234:237], v179 offset:34816
	v_mov_b32_e32 v174, v192
	v_mov_b32_e32 v192, v250
	v_mov_b32_e32 v66, v253
	ds_read_b128 v[250:253], v179 offset:35840
	ds_read_b128 v[238:241], v179 offset:36864
	ds_read_b128 v[242:245], v179 offset:37888
	ds_read_b128 v[230:233], v179 offset:38912
	ds_read_b128 v[246:249], v179 offset:39936
	global_load_lds_dwordx4 v[12:13], off
	v_lshl_add_u64 v[12:13], s[36:37], 0, v[124:125]
	s_mov_b32 m0, s91
	s_nop 0
	global_load_lds_dwordx4 v[12:13], off
	s_waitcnt vmcnt(8) lgkmcnt(0)
	s_setprio 1
	s_barrier
	v_mfma_f32_16x16x32_bf16 v[56:59], v[16:19], v[234:237], v[72:75]
	v_mfma_f32_16x16x32_bf16 v[12:15], v[16:19], v[48:51], v[116:119]
	v_mfma_f32_16x16x32_bf16 v[116:119], v[24:27], v[250:253], v[56:59]
	v_mfma_f32_16x16x32_bf16 v[56:59], v[28:31], v[234:237], v[76:79]
	v_mfma_f32_16x16x32_bf16 v[112:115], v[210:213], v[250:253], v[56:59]
	v_mfma_f32_16x16x32_bf16 v[56:59], v[16:19], v[238:241], v[80:83]
	v_mfma_f32_16x16x32_bf16 v[104:107], v[24:27], v[242:245], v[56:59]
	v_mfma_f32_16x16x32_bf16 v[56:59], v[28:31], v[238:241], v[84:87]
	v_mfma_f32_16x16x32_bf16 v[108:111], v[210:213], v[242:245], v[56:59]
	v_mfma_f32_16x16x32_bf16 v[56:59], v[16:19], v[230:233], v[88:91]
	v_mfma_f32_16x16x32_bf16 v[20:23], v[24:27], v[52:55], v[12:15]
	v_mfma_f32_16x16x32_bf16 v[12:15], v[28:31], v[48:51], v[68:71]
	v_mfma_f32_16x16x32_bf16 v[96:99], v[24:27], v[246:249], v[56:59]
	v_mfma_f32_16x16x32_bf16 v[56:59], v[28:31], v[230:233], v[92:95]
	v_mfma_f32_16x16x32_bf16 v[12:15], v[210:213], v[52:55], v[12:15]
	v_mfma_f32_16x16x32_bf16 v[100:103], v[210:213], v[246:249], v[56:59]
	v_mfma_f32_16x16x32_bf16 v[56:59], v[214:217], v[48:51], v[126:129]
	v_mfma_f32_16x16x32_bf16 v[32:35], v[222:225], v[48:51], v[32:35]
	v_mfma_f32_16x16x32_bf16 v[60:63], v[218:221], v[52:55], v[56:59]
	v_mfma_f32_16x16x32_bf16 v[56:59], v[226:229], v[52:55], v[32:35]
	v_mfma_f32_16x16x32_bf16 v[32:35], v[214:217], v[234:237], v[36:39]
	v_mfma_f32_16x16x32_bf16 v[52:55], v[218:221], v[250:253], v[32:35]
	v_mfma_f32_16x16x32_bf16 v[32:35], v[222:225], v[234:237], v[40:43]
	v_mfma_f32_16x16x32_bf16 v[48:51], v[226:229], v[250:253], v[32:35]
	v_mov_b32_e32 v253, v66
	v_mov_b32_e32 v250, v192
	v_mov_b32_e32 v192, v174
	v_mfma_f32_16x16x32_bf16 v[32:35], v[214:217], v[238:241], v[44:47]
	v_mfma_f32_16x16x32_bf16 v[44:47], v[218:221], v[242:245], v[32:35]
	v_mfma_f32_16x16x32_bf16 v[32:35], v[222:225], v[238:241], v[130:133]
	v_mfma_f32_16x16x32_bf16 v[40:43], v[226:229], v[242:245], v[32:35]
	v_mfma_f32_16x16x32_bf16 v[32:35], v[214:217], v[230:233], v[134:137]
	v_mfma_f32_16x16x32_bf16 v[36:39], v[218:221], v[246:249], v[32:35]
	v_mfma_f32_16x16x32_bf16 v[32:35], v[222:225], v[230:233], v[138:141]
	v_mfma_f32_16x16x32_bf16 v[32:35], v[226:229], v[246:249], v[32:35]
	v_mov_b32_e32 v247, 0x77
	v_mov_b32_e32 v246, 0x7c
	v_mov_b32_e32 v248, 0x260
	s_setprio 0
	s_barrier
	s_mov_b64 s[40:41], 0x180
	s_add_i32 s9, s9, s87
	v_lshl_add_u64 v[64:65], v[158:159], 0, s[40:41]
	s_mov_b32 m0, s9
	ds_read_b128 v[126:129], v179 offset:49152
	ds_read_b128 v[130:133], v179 offset:50176
	ds_read_b128 v[134:137], v179 offset:51200
	ds_read_b128 v[138:141], v179 offset:52224
	ds_read_b128 v[230:233], v179 offset:53248
	ds_read_b128 v[234:237], v179 offset:54272
	ds_read_b128 v[238:241], v179 offset:55296
	ds_read_b128 v[242:245], v179 offset:56320
	global_load_lds_dwordx4 v[64:65], off
	s_add_i32 m0, s9, 0x2000
	s_add_u32 s36, s22, 0x40180
	v_lshl_add_u64 v[64:65], v[176:177], 0, s[40:41]
	s_addc_u32 s37, s23, 0
	s_add_i32 s9, s19, s87
	global_load_lds_dwordx4 v[64:65], off
	v_lshl_add_u64 v[64:65], s[36:37], 0, v[120:121]
	s_mov_b32 m0, s9
	s_nop 0
	global_load_lds_dwordx4 v[64:65], off
	v_lshl_add_u64 v[64:65], s[36:37], 0, v[160:161]
	s_add_i32 m0, s9, 0x2000
	s_nop 0
	global_load_lds_dwordx4 v[64:65], off
	v_lshl_add_u64 v[64:65], v[188:189], 0, s[40:41]
	s_mov_b32 m0, s63
	s_nop 0
	global_load_lds_dwordx4 v[64:65], off
	v_lshl_add_u64 v[64:65], v[190:191], 0, s[40:41]
	s_mov_b32 m0, s64
	s_nop 0
	global_load_lds_dwordx4 v[64:65], off
	s_waitcnt vmcnt(8) lgkmcnt(0)
	s_setprio 1
	s_barrier
	v_mfma_f32_16x16x32_bf16 v[64:67], v[16:19], v[126:129], v[142:145]
	v_mfma_f32_16x16x32_bf16 v[88:91], v[24:27], v[130:133], v[64:67]
	v_mfma_f32_16x16x32_bf16 v[64:67], v[28:31], v[126:129], v[146:149]
	v_mfma_f32_16x16x32_bf16 v[92:95], v[210:213], v[130:133], v[64:67]
	v_mfma_f32_16x16x32_bf16 v[64:67], v[16:19], v[134:137], v[150:153]
	v_mfma_f32_16x16x32_bf16 v[80:83], v[24:27], v[138:141], v[64:67]
	v_mfma_f32_16x16x32_bf16 v[64:67], v[28:31], v[134:137], v[154:157]
	v_mfma_f32_16x16x32_bf16 v[84:87], v[210:213], v[138:141], v[64:67]
	v_mfma_f32_16x16x32_bf16 v[64:67], v[16:19], v[230:233], v[162:165]
	v_mfma_f32_16x16x32_bf16 v[72:75], v[24:27], v[234:237], v[64:67]
	v_mfma_f32_16x16x32_bf16 v[64:67], v[28:31], v[230:233], v[166:169]
	v_mfma_f32_16x16x32_bf16 v[0:3], v[16:19], v[238:241], v[0:3]
	v_mfma_f32_16x16x32_bf16 v[76:79], v[210:213], v[234:237], v[64:67]
	v_mfma_f32_16x16x32_bf16 v[64:67], v[24:27], v[242:245], v[0:3]
	v_mfma_f32_16x16x32_bf16 v[0:3], v[28:31], v[238:241], v[4:7]
	v_mfma_f32_16x16x32_bf16 v[68:71], v[210:213], v[242:245], v[0:3]
	v_mfma_f32_16x16x32_bf16 v[0:3], v[214:217], v[126:129], v[8:11]
	v_mfma_f32_16x16x32_bf16 v[28:31], v[218:221], v[130:133], v[0:3]
	v_mfma_f32_16x16x32_bf16 v[0:3], v[222:225], v[126:129], v[170:173]
	v_mfma_f32_16x16x32_bf16 v[24:27], v[226:229], v[130:133], v[0:3]
	v_mfma_f32_16x16x32_bf16 v[0:3], v[214:217], v[134:137], v[180:183]
	v_mfma_f32_16x16x32_bf16 v[16:19], v[218:221], v[138:141], v[0:3]
	v_mfma_f32_16x16x32_bf16 v[0:3], v[222:225], v[134:137], v[184:187]
	v_mfma_f32_16x16x32_bf16 v[126:129], v[214:217], v[238:241], v[202:205]
	v_mfma_f32_16x16x32_bf16 v[8:11], v[226:229], v[138:141], v[0:3]
	v_mfma_f32_16x16x32_bf16 v[0:3], v[214:217], v[230:233], v[194:197]
	v_mfma_f32_16x16x32_bf16 v[4:7], v[222:225], v[230:233], v[198:201]
	v_mfma_f32_16x16x32_bf16 v[132:135], v[218:221], v[242:245], v[126:129]
	v_mfma_f32_16x16x32_bf16 v[126:129], v[222:225], v[238:241], v[206:209]
	v_mov_b32_e32 v241, 0x7f
	v_mfma_f32_16x16x32_bf16 v[0:3], v[218:221], v[234:237], v[0:3]
	v_mfma_f32_16x16x32_bf16 v[4:7], v[226:229], v[234:237], v[4:7]
	v_mfma_f32_16x16x32_bf16 v[128:131], v[226:229], v[242:245], v[126:129]
	v_mov_b32_e32 v245, 0x7d
	v_mov_b32_e32 v244, 0x7e
	v_mov_b64_e32 v[242:243], 0x400
	s_setprio 0
	s_barrier
	s_mov_b32 s40, 2

.LBB0_789:
	s_add_u32 s24, s43, s92
	s_addc_u32 s25, s69, 0
	s_add_u32 s94, s81, s92
	s_addc_u32 s95, vcc_lo, 0
	s_add_i32 vcc_hi, 0, 0x10000
	s_cmp_eq_u32 s92, s22
	s_cselect_b32 s41, s9, s25
	s_cselect_b32 s40, s19, s24
	s_cselect_b32 s25, s36, s95
	s_cselect_b32 s24, s37, s94
	s_add_i32 s80, 0, 0x14000
	v_add_u32_e32 v150, vcc_hi, v175
	v_add_u32_e32 v158, s80, v175
	ds_read_b128 v[138:141], v150
	ds_read_b128 v[142:145], v150 offset:1024
	ds_read_b128 v[146:149], v150 offset:2048
	ds_read_b128 v[150:153], v150 offset:3072
	ds_read_b128 v[154:157], v158
	ds_read_b128 v[162:165], v158 offset:1024
	ds_read_b128 v[166:169], v158 offset:2048
	ds_read_b128 v[170:173], v158 offset:3072
	v_lshl_add_u64 v[158:159], v[126:127], 0, s[92:93]
	s_add_i32 m0, s88, 0xc000
	ds_read_b128 v[180:183], v179
	ds_read_b128 v[184:187], v179 offset:1024
	ds_read_b128 v[194:197], v179 offset:2048
	ds_read_b128 v[198:201], v179 offset:3072
	ds_read_b128 v[202:205], v179 offset:4096
	ds_read_b128 v[206:209], v179 offset:5120
	ds_read_b128 v[210:213], v179 offset:6144
	ds_read_b128 v[214:217], v179 offset:7168
	global_load_lds_dwordx4 v[158:159], off
	v_lshl_add_u64 v[158:159], v[136:137], 0, s[92:93]
	s_add_i32 m0, s88, 0xe000
	s_nop 0
	global_load_lds_dwordx4 v[158:159], off
	s_waitcnt vmcnt(8) lgkmcnt(0)
	s_setprio 1
	s_barrier
	v_mfma_f32_16x16x32_bf16 v[20:23], v[138:141], v[180:183], v[20:23]
	v_mfma_f32_16x16x32_bf16 v[12:15], v[146:149], v[180:183], v[12:15]
	v_mfma_f32_16x16x32_bf16 v[116:119], v[138:141], v[194:197], v[116:119]
	v_mfma_f32_16x16x32_bf16 v[112:115], v[146:149], v[194:197], v[112:115]
	v_mfma_f32_16x16x32_bf16 v[104:107], v[138:141], v[202:205], v[104:107]
	v_mfma_f32_16x16x32_bf16 v[108:111], v[146:149], v[202:205], v[108:111]
	v_mfma_f32_16x16x32_bf16 v[96:99], v[138:141], v[210:213], v[96:99]
	v_mfma_f32_16x16x32_bf16 v[100:103], v[146:149], v[210:213], v[100:103]
	v_mfma_f32_16x16x32_bf16 v[20:23], v[142:145], v[184:187], v[20:23]
	v_mfma_f32_16x16x32_bf16 v[12:15], v[150:153], v[184:187], v[12:15]
	v_mfma_f32_16x16x32_bf16 v[116:119], v[142:145], v[198:201], v[116:119]
	v_mfma_f32_16x16x32_bf16 v[112:115], v[150:153], v[198:201], v[112:115]
	v_mfma_f32_16x16x32_bf16 v[104:107], v[142:145], v[206:209], v[104:107]
	v_mfma_f32_16x16x32_bf16 v[108:111], v[150:153], v[206:209], v[108:111]
	v_mfma_f32_16x16x32_bf16 v[96:99], v[142:145], v[214:217], v[96:99]
	v_mfma_f32_16x16x32_bf16 v[100:103], v[150:153], v[214:217], v[100:103]
	v_mfma_f32_16x16x32_bf16 v[60:63], v[154:157], v[180:183], v[60:63]
	v_mfma_f32_16x16x32_bf16 v[56:59], v[166:169], v[180:183], v[56:59]
	v_mfma_f32_16x16x32_bf16 v[52:55], v[154:157], v[194:197], v[52:55]
	v_mfma_f32_16x16x32_bf16 v[48:51], v[166:169], v[194:197], v[48:51]
	v_mfma_f32_16x16x32_bf16 v[44:47], v[154:157], v[202:205], v[44:47]
	v_mfma_f32_16x16x32_bf16 v[40:43], v[166:169], v[202:205], v[40:43]
	v_mfma_f32_16x16x32_bf16 v[36:39], v[154:157], v[210:213], v[36:39]
	v_mfma_f32_16x16x32_bf16 v[32:35], v[166:169], v[210:213], v[32:35]
	v_mfma_f32_16x16x32_bf16 v[60:63], v[162:165], v[184:187], v[60:63]
	v_mfma_f32_16x16x32_bf16 v[56:59], v[170:173], v[184:187], v[56:59]
	v_mfma_f32_16x16x32_bf16 v[52:55], v[162:165], v[198:201], v[52:55]
	v_mfma_f32_16x16x32_bf16 v[48:51], v[170:173], v[198:201], v[48:51]
	v_mfma_f32_16x16x32_bf16 v[44:47], v[162:165], v[206:209], v[44:47]
	v_mfma_f32_16x16x32_bf16 v[40:43], v[170:173], v[206:209], v[40:43]
	v_mfma_f32_16x16x32_bf16 v[36:39], v[162:165], v[214:217], v[36:39]
	v_mfma_f32_16x16x32_bf16 v[32:35], v[170:173], v[214:217], v[32:35]
	s_barrier
	s_setprio 0
	s_add_i32 s94, vcc_hi, s87
	v_lshl_add_u64 v[158:159], s[24:25], 0, v[120:121]
	s_mov_b32 m0, s94
	ds_read_b128 v[180:183], v179 offset:16384
	ds_read_b128 v[184:187], v179 offset:17408
	ds_read_b128 v[194:197], v179 offset:18432
	ds_read_b128 v[198:201], v179 offset:19456
	ds_read_b128 v[202:205], v179 offset:20480
	ds_read_b128 v[206:209], v179 offset:21504
	ds_read_b128 v[210:213], v179 offset:22528
	ds_read_b128 v[214:217], v179 offset:23552
	global_load_lds_dwordx4 v[158:159], off
	s_add_i32 m0, s94, 0x2000
	s_add_u32 s94, s24, 0x40000
	v_lshl_add_u64 v[176:177], s[24:25], 0, v[160:161]
	s_addc_u32 s95, s25, 0
	s_add_i32 s80, s80, s87
	global_load_lds_dwordx4 v[176:177], off
	v_lshl_add_u64 v[188:189], s[94:95], 0, v[120:121]
	s_mov_b32 m0, s80
	v_lshl_add_u64 v[190:191], s[40:41], 0, v[124:125]
	global_load_lds_dwordx4 v[188:189], off
	v_lshl_add_u64 v[188:189], s[94:95], 0, v[160:161]
	s_add_i32 m0, s80, 0x2000
	s_nop 0
	global_load_lds_dwordx4 v[188:189], off
	v_lshl_add_u64 v[188:189], s[40:41], 0, v[122:123]
	s_mov_b32 m0, s88
	s_nop 0
	global_load_lds_dwordx4 v[188:189], off
	s_mov_b32 m0, s89
	s_nop 0
	global_load_lds_dwordx4 v[190:191], off
	s_waitcnt vmcnt(8) lgkmcnt(0)
	s_setprio 1
	s_barrier
	v_mfma_f32_16x16x32_bf16 v[88:91], v[138:141], v[180:183], v[88:91]
	v_mfma_f32_16x16x32_bf16 v[92:95], v[146:149], v[180:183], v[92:95]
	v_mfma_f32_16x16x32_bf16 v[80:83], v[138:141], v[194:197], v[80:83]
	v_mfma_f32_16x16x32_bf16 v[84:87], v[146:149], v[194:197], v[84:87]
	v_mfma_f32_16x16x32_bf16 v[72:75], v[138:141], v[202:205], v[72:75]
	v_mfma_f32_16x16x32_bf16 v[76:79], v[146:149], v[202:205], v[76:79]
	v_mfma_f32_16x16x32_bf16 v[64:67], v[138:141], v[210:213], v[64:67]
	v_mfma_f32_16x16x32_bf16 v[68:71], v[146:149], v[210:213], v[68:71]
	v_mfma_f32_16x16x32_bf16 v[88:91], v[142:145], v[184:187], v[88:91]
	v_mfma_f32_16x16x32_bf16 v[92:95], v[150:153], v[184:187], v[92:95]
	v_mfma_f32_16x16x32_bf16 v[80:83], v[142:145], v[198:201], v[80:83]
	v_mfma_f32_16x16x32_bf16 v[84:87], v[150:153], v[198:201], v[84:87]
	v_mfma_f32_16x16x32_bf16 v[72:75], v[142:145], v[206:209], v[72:75]
	v_mfma_f32_16x16x32_bf16 v[76:79], v[150:153], v[206:209], v[76:79]
	v_mfma_f32_16x16x32_bf16 v[64:67], v[142:145], v[214:217], v[64:67]
	v_mfma_f32_16x16x32_bf16 v[68:71], v[150:153], v[214:217], v[68:71]
	v_mfma_f32_16x16x32_bf16 v[28:31], v[154:157], v[180:183], v[28:31]
	v_mfma_f32_16x16x32_bf16 v[24:27], v[166:169], v[180:183], v[24:27]
	v_mfma_f32_16x16x32_bf16 v[16:19], v[154:157], v[194:197], v[16:19]
	v_mfma_f32_16x16x32_bf16 v[8:11], v[166:169], v[194:197], v[8:11]
	v_mfma_f32_16x16x32_bf16 v[0:3], v[154:157], v[202:205], v[0:3]
	v_mfma_f32_16x16x32_bf16 v[4:7], v[166:169], v[202:205], v[4:7]
	v_mfma_f32_16x16x32_bf16 v[132:135], v[154:157], v[210:213], v[132:135]
	v_mfma_f32_16x16x32_bf16 v[128:131], v[166:169], v[210:213], v[128:131]
	v_mfma_f32_16x16x32_bf16 v[28:31], v[162:165], v[184:187], v[28:31]
	v_mfma_f32_16x16x32_bf16 v[24:27], v[170:173], v[184:187], v[24:27]
	v_mfma_f32_16x16x32_bf16 v[16:19], v[162:165], v[198:201], v[16:19]
	v_mfma_f32_16x16x32_bf16 v[8:11], v[170:173], v[198:201], v[8:11]
	v_mfma_f32_16x16x32_bf16 v[0:3], v[162:165], v[206:209], v[0:3]
	v_mfma_f32_16x16x32_bf16 v[4:7], v[170:173], v[206:209], v[4:7]
	v_mfma_f32_16x16x32_bf16 v[132:135], v[162:165], v[214:217], v[132:135]
	v_mfma_f32_16x16x32_bf16 v[128:131], v[170:173], v[214:217], v[128:131]
	s_barrier
	s_setprio 0
	s_add_i32 s80, 0, 0x18000
	s_add_i32 s94, 0, 0x1c000
	v_add_u32_e32 v150, s80, v175
	v_add_u32_e32 v170, s94, v175
	ds_read_b128 v[138:141], v150
	ds_read_b128 v[142:145], v150 offset:1024
	ds_read_b128 v[146:149], v150 offset:2048
	ds_read_b128 v[150:153], v150 offset:3072
	ds_read_b128 v[154:157], v170
	ds_read_b128 v[162:165], v170 offset:1024
	ds_read_b128 v[166:169], v170 offset:2048
	ds_read_b128 v[170:173], v170 offset:3072
	s_add_u32 s40, s40, 0x40000
	s_addc_u32 s41, s41, 0
	s_mov_b32 m0, s90
	v_lshl_add_u64 v[218:219], s[40:41], 0, v[122:123]
	ds_read_b128 v[180:183], v179 offset:32768
	ds_read_b128 v[184:187], v179 offset:33792
	ds_read_b128 v[194:197], v179 offset:34816
	ds_read_b128 v[198:201], v179 offset:35840
	ds_read_b128 v[202:205], v179 offset:36864
	ds_read_b128 v[206:209], v179 offset:37888
	ds_read_b128 v[210:213], v179 offset:38912
	ds_read_b128 v[214:217], v179 offset:39936
	global_load_lds_dwordx4 v[218:219], off
	v_lshl_add_u64 v[218:219], s[40:41], 0, v[124:125]
	s_mov_b32 m0, s91
	s_nop 0
	global_load_lds_dwordx4 v[218:219], off
	s_waitcnt vmcnt(8) lgkmcnt(0)
	s_setprio 1
	s_barrier
	v_mfma_f32_16x16x32_bf16 v[20:23], v[138:141], v[180:183], v[20:23]
	v_mfma_f32_16x16x32_bf16 v[12:15], v[146:149], v[180:183], v[12:15]
	v_mfma_f32_16x16x32_bf16 v[116:119], v[138:141], v[194:197], v[116:119]
	v_mfma_f32_16x16x32_bf16 v[112:115], v[146:149], v[194:197], v[112:115]
	v_mfma_f32_16x16x32_bf16 v[104:107], v[138:141], v[202:205], v[104:107]
	v_mfma_f32_16x16x32_bf16 v[108:111], v[146:149], v[202:205], v[108:111]
	v_mfma_f32_16x16x32_bf16 v[96:99], v[138:141], v[210:213], v[96:99]
	v_mfma_f32_16x16x32_bf16 v[100:103], v[146:149], v[210:213], v[100:103]
	v_mfma_f32_16x16x32_bf16 v[20:23], v[142:145], v[184:187], v[20:23]
	v_mfma_f32_16x16x32_bf16 v[12:15], v[150:153], v[184:187], v[12:15]
	v_mfma_f32_16x16x32_bf16 v[116:119], v[142:145], v[198:201], v[116:119]
	v_mfma_f32_16x16x32_bf16 v[112:115], v[150:153], v[198:201], v[112:115]
	v_mfma_f32_16x16x32_bf16 v[104:107], v[142:145], v[206:209], v[104:107]
	v_mfma_f32_16x16x32_bf16 v[108:111], v[150:153], v[206:209], v[108:111]
	v_mfma_f32_16x16x32_bf16 v[96:99], v[142:145], v[214:217], v[96:99]
	v_mfma_f32_16x16x32_bf16 v[100:103], v[150:153], v[214:217], v[100:103]
	v_mfma_f32_16x16x32_bf16 v[60:63], v[154:157], v[180:183], v[60:63]
	v_mfma_f32_16x16x32_bf16 v[56:59], v[166:169], v[180:183], v[56:59]
	v_mfma_f32_16x16x32_bf16 v[52:55], v[154:157], v[194:197], v[52:55]
	v_mfma_f32_16x16x32_bf16 v[48:51], v[166:169], v[194:197], v[48:51]
	v_mfma_f32_16x16x32_bf16 v[44:47], v[154:157], v[202:205], v[44:47]
	v_mfma_f32_16x16x32_bf16 v[40:43], v[166:169], v[202:205], v[40:43]
	v_mfma_f32_16x16x32_bf16 v[36:39], v[154:157], v[210:213], v[36:39]
	v_mfma_f32_16x16x32_bf16 v[32:35], v[166:169], v[210:213], v[32:35]
	v_mfma_f32_16x16x32_bf16 v[60:63], v[162:165], v[184:187], v[60:63]
	v_mfma_f32_16x16x32_bf16 v[56:59], v[170:173], v[184:187], v[56:59]
	v_mfma_f32_16x16x32_bf16 v[52:55], v[162:165], v[198:201], v[52:55]
	v_mfma_f32_16x16x32_bf16 v[48:51], v[170:173], v[198:201], v[48:51]
	v_mfma_f32_16x16x32_bf16 v[44:47], v[162:165], v[206:209], v[44:47]
	v_mfma_f32_16x16x32_bf16 v[40:43], v[170:173], v[206:209], v[40:43]
	v_mfma_f32_16x16x32_bf16 v[36:39], v[162:165], v[214:217], v[36:39]
	v_mfma_f32_16x16x32_bf16 v[32:35], v[170:173], v[214:217], v[32:35]
	s_barrier
	s_setprio 0
	s_add_i32 s40, s80, s87
	v_lshl_add_u64 v[158:159], v[158:159], 0, s[14:15]
	s_mov_b32 m0, s40
	ds_read_b128 v[180:183], v179 offset:49152
	ds_read_b128 v[184:187], v179 offset:50176
	ds_read_b128 v[194:197], v179 offset:51200
	ds_read_b128 v[198:201], v179 offset:52224
	ds_read_b128 v[202:205], v179 offset:53248
	ds_read_b128 v[206:209], v179 offset:54272
	ds_read_b128 v[210:213], v179 offset:55296
	ds_read_b128 v[214:217], v179 offset:56320
	global_load_lds_dwordx4 v[158:159], off
	s_add_i32 m0, s40, 0x2000
	s_add_u32 s24, s24, 0x40080
	v_lshl_add_u64 v[158:159], v[176:177], 0, s[14:15]
	s_addc_u32 s25, s25, 0
	s_add_i32 s40, s94, s87
	global_load_lds_dwordx4 v[158:159], off
	v_lshl_add_u64 v[158:159], s[24:25], 0, v[120:121]
	s_mov_b32 m0, s40
	s_nop 0
	global_load_lds_dwordx4 v[158:159], off
	v_lshl_add_u64 v[158:159], s[24:25], 0, v[160:161]
	s_add_i32 m0, s40, 0x2000
	s_nop 0
	global_load_lds_dwordx4 v[158:159], off
	v_lshl_add_u64 v[158:159], v[188:189], 0, s[14:15]
	s_mov_b32 m0, s63
	s_nop 0
	global_load_lds_dwordx4 v[158:159], off
	v_lshl_add_u64 v[158:159], v[190:191], 0, s[14:15]
	s_mov_b32 m0, s64
	s_nop 0
	global_load_lds_dwordx4 v[158:159], off
	s_waitcnt vmcnt(8) lgkmcnt(0)
	s_setprio 1
	s_barrier
	v_mfma_f32_16x16x32_bf16 v[88:91], v[138:141], v[180:183], v[88:91]
	v_mfma_f32_16x16x32_bf16 v[92:95], v[146:149], v[180:183], v[92:95]
	v_mfma_f32_16x16x32_bf16 v[80:83], v[138:141], v[194:197], v[80:83]
	v_mfma_f32_16x16x32_bf16 v[84:87], v[146:149], v[194:197], v[84:87]
	v_mfma_f32_16x16x32_bf16 v[72:75], v[138:141], v[202:205], v[72:75]
	v_mfma_f32_16x16x32_bf16 v[76:79], v[146:149], v[202:205], v[76:79]
	v_mfma_f32_16x16x32_bf16 v[64:67], v[138:141], v[210:213], v[64:67]
	v_mfma_f32_16x16x32_bf16 v[68:71], v[146:149], v[210:213], v[68:71]
	v_mfma_f32_16x16x32_bf16 v[88:91], v[142:145], v[184:187], v[88:91]
	v_mfma_f32_16x16x32_bf16 v[92:95], v[150:153], v[184:187], v[92:95]
	v_mfma_f32_16x16x32_bf16 v[80:83], v[142:145], v[198:201], v[80:83]
	v_mfma_f32_16x16x32_bf16 v[84:87], v[150:153], v[198:201], v[84:87]
	v_mfma_f32_16x16x32_bf16 v[72:75], v[142:145], v[206:209], v[72:75]
	v_mfma_f32_16x16x32_bf16 v[76:79], v[150:153], v[206:209], v[76:79]
	v_mfma_f32_16x16x32_bf16 v[64:67], v[142:145], v[214:217], v[64:67]
	v_mfma_f32_16x16x32_bf16 v[68:71], v[150:153], v[214:217], v[68:71]
	v_mfma_f32_16x16x32_bf16 v[28:31], v[154:157], v[180:183], v[28:31]
	v_mfma_f32_16x16x32_bf16 v[24:27], v[166:169], v[180:183], v[24:27]
	v_mfma_f32_16x16x32_bf16 v[16:19], v[154:157], v[194:197], v[16:19]
	v_mfma_f32_16x16x32_bf16 v[8:11], v[166:169], v[194:197], v[8:11]
	v_mfma_f32_16x16x32_bf16 v[0:3], v[154:157], v[202:205], v[0:3]
	v_mfma_f32_16x16x32_bf16 v[4:7], v[166:169], v[202:205], v[4:7]
	v_mfma_f32_16x16x32_bf16 v[132:135], v[154:157], v[210:213], v[132:135]
	v_mfma_f32_16x16x32_bf16 v[128:131], v[166:169], v[210:213], v[128:131]
	v_mfma_f32_16x16x32_bf16 v[28:31], v[162:165], v[184:187], v[28:31]
	v_mfma_f32_16x16x32_bf16 v[24:27], v[170:173], v[184:187], v[24:27]
	v_mfma_f32_16x16x32_bf16 v[16:19], v[162:165], v[198:201], v[16:19]
	v_mfma_f32_16x16x32_bf16 v[8:11], v[170:173], v[198:201], v[8:11]
	v_mfma_f32_16x16x32_bf16 v[0:3], v[162:165], v[206:209], v[0:3]
	v_mfma_f32_16x16x32_bf16 v[4:7], v[170:173], v[206:209], v[4:7]
	v_mfma_f32_16x16x32_bf16 v[132:135], v[162:165], v[214:217], v[132:135]
	v_mfma_f32_16x16x32_bf16 v[128:131], v[170:173], v[214:217], v[128:131]
	s_barrier
	s_setprio 0
	s_add_i32 s42, s42, 2
	s_add_u32 s43, s43, 0x100
	s_addc_u32 s69, s69, 0
	s_add_u32 s81, s81, 0x100
	s_addc_u32 vcc_lo, vcc_lo, 0
	s_add_u32 s22, s22, 0xffffff00
	s_addc_u32 s23, s23, -1
	v_lshl_add_u64 v[126:127], v[126:127], 0, s[16:17]
	s_cmp_gt_u32 s42, 13
	v_lshl_add_u64 v[136:137], v[136:137], 0, s[16:17]
	s_cbranch_scc0 .LBB0_789
	s_and_b64 vcc, exec, s[44:45]
	s_cbranch_vccz .LBB0_792
	s_barrier

.LBB0_1211:
.LBB0_1212:
	s_add_i32 s19, 0, 0x10000
	s_add_i32 s36, 0, 0x14000
	v_add_u32_e32 v12, s19, v203
	v_add_u32_e32 v28, s36, v203
	ds_read_b128 v[0:3], v12
	ds_read_b128 v[4:7], v12 offset:1024
	ds_read_b128 v[8:11], v12 offset:2048
	ds_read_b128 v[12:15], v12 offset:3072
	ds_read_b128 v[16:19], v28
	ds_read_b128 v[20:23], v28 offset:1024
	ds_read_b128 v[24:27], v28 offset:2048
	ds_read_b128 v[28:31], v28 offset:3072
	s_add_u32 s4, s40, 0x40080
	s_addc_u32 s5, s41, 0
	v_lshl_add_u64 v[64:65], s[4:5], 0, v[130:131]
	s_add_i32 m0, s23, 0xc000
	ds_read_b128 v[32:35], v204
	ds_read_b128 v[36:39], v204 offset:1024
	ds_read_b128 v[40:43], v204 offset:2048
	ds_read_b128 v[44:47], v204 offset:3072
	ds_read_b128 v[48:51], v204 offset:4096
	ds_read_b128 v[52:55], v204 offset:5120
	ds_read_b128 v[56:59], v204 offset:6144
	ds_read_b128 v[60:63], v204 offset:7168
	global_load_lds_dwordx4 v[64:65], off
	v_lshl_add_u64 v[64:65], s[4:5], 0, v[132:133]
	s_add_i32 m0, s23, 0xe000
	s_nop 0
	global_load_lds_dwordx4 v[64:65], off
	s_waitcnt vmcnt(40) lgkmcnt(0)
	s_setprio 1
	s_barrier
	v_mfma_f32_16x16x32_bf16 v[64:67], v[0:3], v[32:35], 0
	v_mfma_f32_16x16x32_bf16 v[68:71], v[8:11], v[32:35], 0
	v_mfma_f32_16x16x32_bf16 v[72:75], v[0:3], v[40:43], 0
	v_mfma_f32_16x16x32_bf16 v[76:79], v[8:11], v[40:43], 0
	v_mfma_f32_16x16x32_bf16 v[80:83], v[0:3], v[48:51], 0
	v_mfma_f32_16x16x32_bf16 v[84:87], v[8:11], v[48:51], 0
	v_mfma_f32_16x16x32_bf16 v[88:91], v[0:3], v[56:59], 0
	v_mfma_f32_16x16x32_bf16 v[92:95], v[8:11], v[56:59], 0
	v_mfma_f32_16x16x32_bf16 v[64:67], v[4:7], v[36:39], v[64:67]
	v_mfma_f32_16x16x32_bf16 v[68:71], v[12:15], v[36:39], v[68:71]
	v_mfma_f32_16x16x32_bf16 v[72:75], v[4:7], v[44:47], v[72:75]
	v_mfma_f32_16x16x32_bf16 v[76:79], v[12:15], v[44:47], v[76:79]
	v_mfma_f32_16x16x32_bf16 v[80:83], v[4:7], v[52:55], v[80:83]
	v_mfma_f32_16x16x32_bf16 v[84:87], v[12:15], v[52:55], v[84:87]
	v_mfma_f32_16x16x32_bf16 v[88:91], v[4:7], v[60:63], v[88:91]
	v_mfma_f32_16x16x32_bf16 v[92:95], v[12:15], v[60:63], v[92:95]
	v_mfma_f32_16x16x32_bf16 v[96:99], v[16:19], v[32:35], 0
	v_mfma_f32_16x16x32_bf16 v[32:35], v[24:27], v[32:35], 0
	v_mfma_f32_16x16x32_bf16 v[96:99], v[20:23], v[36:39], v[96:99]
	v_mfma_f32_16x16x32_bf16 v[32:35], v[28:31], v[36:39], v[32:35]
	v_mfma_f32_16x16x32_bf16 v[36:39], v[16:19], v[40:43], 0
	v_mfma_f32_16x16x32_bf16 v[40:43], v[24:27], v[40:43], 0
	v_mfma_f32_16x16x32_bf16 v[36:39], v[20:23], v[44:47], v[36:39]
	v_mfma_f32_16x16x32_bf16 v[40:43], v[28:31], v[44:47], v[40:43]
	v_mfma_f32_16x16x32_bf16 v[44:47], v[16:19], v[48:51], 0
	v_mfma_f32_16x16x32_bf16 v[48:51], v[24:27], v[48:51], 0
	v_mfma_f32_16x16x32_bf16 v[100:103], v[28:31], v[52:55], v[48:51]
	v_mfma_f32_16x16x32_bf16 v[48:51], v[16:19], v[56:59], 0
	v_mfma_f32_16x16x32_bf16 v[104:107], v[20:23], v[60:63], v[48:51]
	v_mfma_f32_16x16x32_bf16 v[48:51], v[24:27], v[56:59], 0
	v_mfma_f32_16x16x32_bf16 v[44:47], v[20:23], v[52:55], v[44:47]
	v_mfma_f32_16x16x32_bf16 v[108:111], v[28:31], v[60:63], v[48:51]
	s_barrier
	s_setprio 0
	v_lshl_add_u64 v[158:159], s[24:25], 0, v[128:129]
	s_add_i32 s4, s19, s74
	v_lshl_add_u64 v[134:135], v[158:159], 0, s[16:17]
	s_mov_b32 m0, s4
	ds_read_b128 v[48:51], v204 offset:16384
	ds_read_b128 v[52:55], v204 offset:17408
	ds_read_b128 v[56:59], v204 offset:18432
	ds_read_b128 v[60:63], v204 offset:19456
	ds_read_b128 v[112:115], v204 offset:20480
	ds_read_b128 v[116:119], v204 offset:21504
	ds_read_b128 v[120:123], v204 offset:22528
	ds_read_b128 v[124:127], v204 offset:23552
	global_load_lds_dwordx4 v[134:135], off
	s_add_i32 m0, s4, 0x2000
	v_lshl_add_u64 v[188:189], s[24:25], 0, v[160:161]
	s_add_u32 s4, s24, 0x40100
	v_lshl_add_u64 v[134:135], v[188:189], 0, s[16:17]
	s_addc_u32 s5, s25, 0
	s_add_i32 s19, s36, s74
	global_load_lds_dwordx4 v[134:135], off
	v_lshl_add_u64 v[134:135], s[4:5], 0, v[128:129]
	s_mov_b32 m0, s19
	v_lshl_add_u64 v[190:191], s[40:41], 0, v[130:131]
	global_load_lds_dwordx4 v[134:135], off
	v_lshl_add_u64 v[134:135], s[4:5], 0, v[160:161]
	s_add_i32 m0, s19, 0x2000
	v_mov_b32_e32 v202, v250
	global_load_lds_dwordx4 v[134:135], off
	v_lshl_add_u64 v[134:135], v[190:191], 0, s[16:17]
	s_mov_b32 m0, s23
	v_lshl_add_u64 v[250:251], s[40:41], 0, v[132:133]
	global_load_lds_dwordx4 v[134:135], off
	v_lshl_add_u64 v[134:135], v[250:251], 0, s[16:17]
	s_mov_b32 m0, s77
	s_nop 0
	global_load_lds_dwordx4 v[134:135], off
	s_waitcnt vmcnt(40) lgkmcnt(0)
	s_setprio 1
	s_barrier
	v_mfma_f32_16x16x32_bf16 v[134:137], v[0:3], v[48:51], 0
	v_mfma_f32_16x16x32_bf16 v[142:145], v[0:3], v[56:59], 0
	v_mfma_f32_16x16x32_bf16 v[150:153], v[0:3], v[112:115], 0
	v_mfma_f32_16x16x32_bf16 v[0:3], v[0:3], v[120:123], 0
	v_mfma_f32_16x16x32_bf16 v[134:137], v[4:7], v[52:55], v[134:137]
	v_mfma_f32_16x16x32_bf16 v[142:145], v[4:7], v[60:63], v[142:145]
	v_mfma_f32_16x16x32_bf16 v[150:153], v[4:7], v[116:119], v[150:153]
	v_mfma_f32_16x16x32_bf16 v[0:3], v[4:7], v[124:127], v[0:3]
	v_mfma_f32_16x16x32_bf16 v[4:7], v[8:11], v[120:123], 0
	v_mfma_f32_16x16x32_bf16 v[138:141], v[8:11], v[48:51], 0
	v_mfma_f32_16x16x32_bf16 v[146:149], v[8:11], v[56:59], 0
	v_mfma_f32_16x16x32_bf16 v[154:157], v[8:11], v[112:115], 0
	v_mfma_f32_16x16x32_bf16 v[4:7], v[12:15], v[124:127], v[4:7]
	v_mfma_f32_16x16x32_bf16 v[138:141], v[12:15], v[52:55], v[138:141]
	v_mfma_f32_16x16x32_bf16 v[146:149], v[12:15], v[60:63], v[146:149]
	v_mfma_f32_16x16x32_bf16 v[154:157], v[12:15], v[116:119], v[154:157]
	v_mfma_f32_16x16x32_bf16 v[8:11], v[16:19], v[48:51], 0
	v_mfma_f32_16x16x32_bf16 v[12:15], v[24:27], v[48:51], 0
	v_mfma_f32_16x16x32_bf16 v[48:51], v[16:19], v[56:59], 0
	v_mfma_f32_16x16x32_bf16 v[162:165], v[20:23], v[60:63], v[48:51]
	v_mfma_f32_16x16x32_bf16 v[48:51], v[24:27], v[56:59], 0
	v_mfma_f32_16x16x32_bf16 v[166:169], v[28:31], v[60:63], v[48:51]
	v_mfma_f32_16x16x32_bf16 v[48:51], v[16:19], v[112:115], 0
	v_mfma_f32_16x16x32_bf16 v[16:19], v[16:19], v[120:123], 0
	v_mfma_f32_16x16x32_bf16 v[8:11], v[20:23], v[52:55], v[8:11]
	v_mfma_f32_16x16x32_bf16 v[12:15], v[28:31], v[52:55], v[12:15]
	v_mfma_f32_16x16x32_bf16 v[170:173], v[20:23], v[116:119], v[48:51]
	v_mfma_f32_16x16x32_bf16 v[48:51], v[24:27], v[112:115], 0
	v_mfma_f32_16x16x32_bf16 v[180:183], v[20:23], v[124:127], v[16:19]
	v_mfma_f32_16x16x32_bf16 v[16:19], v[24:27], v[120:123], 0
	v_mfma_f32_16x16x32_bf16 v[174:177], v[28:31], v[116:119], v[48:51]
	v_mfma_f32_16x16x32_bf16 v[184:187], v[28:31], v[124:127], v[16:19]
	s_barrier
	s_setprio 0
	s_add_i32 s19, 0, 0x18000
	v_add_u32_e32 v28, s19, v203
	s_add_i32 s36, 0, 0x1c000
	s_nop 0
	ds_read_b128 v[16:19], v28
	ds_read_b128 v[20:23], v28 offset:1024
	ds_read_b128 v[24:27], v28 offset:2048
	ds_read_b128 v[194:197], v28 offset:3072
	v_add_u32_e32 v28, s36, v203
	ds_read_b128 v[198:201], v28
	ds_read_b128 v[206:209], v28 offset:1024
	ds_read_b128 v[210:213], v28 offset:2048
	ds_read_b128 v[214:217], v28 offset:3072
	s_add_u32 s4, s40, 0x40100
	s_addc_u32 s5, s41, 0
	s_mov_b32 m0, s78
	v_lshl_add_u64 v[48:49], s[4:5], 0, v[130:131]
	ds_read_b128 v[28:31], v204 offset:32768
	ds_read_b128 v[52:55], v204 offset:33792
	ds_read_b128 v[218:221], v204 offset:34816
	ds_read_b128 v[222:225], v204 offset:35840
	ds_read_b128 v[226:229], v204 offset:36864
	ds_read_b128 v[230:233], v204 offset:37888
	ds_read_b128 v[234:237], v204 offset:38912
	ds_read_b128 v[238:241], v204 offset:39936
	global_load_lds_dwordx4 v[48:49], off
	v_lshl_add_u64 v[48:49], s[4:5], 0, v[132:133]
	s_mov_b32 m0, s79
	s_nop 0
	global_load_lds_dwordx4 v[48:49], off
	s_waitcnt vmcnt(8) lgkmcnt(0)
	s_setprio 1
	s_barrier
	v_mfma_f32_16x16x32_bf16 v[56:59], v[16:19], v[218:221], v[72:75]
	v_mfma_f32_16x16x32_bf16 v[48:51], v[16:19], v[28:31], v[64:67]
	v_mfma_f32_16x16x32_bf16 v[120:123], v[20:23], v[222:225], v[56:59]
	v_mfma_f32_16x16x32_bf16 v[56:59], v[24:27], v[218:221], v[76:79]
	v_mfma_f32_16x16x32_bf16 v[124:127], v[20:23], v[52:55], v[48:51]
	v_mfma_f32_16x16x32_bf16 v[48:51], v[24:27], v[28:31], v[68:71]
	v_mfma_f32_16x16x32_bf16 v[68:71], v[194:197], v[222:225], v[56:59]
	v_mfma_f32_16x16x32_bf16 v[56:59], v[16:19], v[226:229], v[80:83]
	v_mfma_f32_16x16x32_bf16 v[116:119], v[20:23], v[230:233], v[56:59]
	v_mfma_f32_16x16x32_bf16 v[56:59], v[24:27], v[226:229], v[84:87]
	v_mfma_f32_16x16x32_bf16 v[72:75], v[194:197], v[230:233], v[56:59]
	v_mfma_f32_16x16x32_bf16 v[56:59], v[16:19], v[234:237], v[88:91]
	v_mfma_f32_16x16x32_bf16 v[112:115], v[20:23], v[238:241], v[56:59]
	v_mfma_f32_16x16x32_bf16 v[56:59], v[24:27], v[234:237], v[92:95]
	v_mfma_f32_16x16x32_bf16 v[48:51], v[194:197], v[52:55], v[48:51]
	v_mfma_f32_16x16x32_bf16 v[92:95], v[194:197], v[238:241], v[56:59]
	v_mfma_f32_16x16x32_bf16 v[56:59], v[198:201], v[28:31], v[96:99]
	v_mfma_f32_16x16x32_bf16 v[28:31], v[210:213], v[28:31], v[32:35]
	v_mfma_f32_16x16x32_bf16 v[60:63], v[214:217], v[52:55], v[28:31]
	v_mfma_f32_16x16x32_bf16 v[28:31], v[198:201], v[218:221], v[36:39]
	v_mfma_f32_16x16x32_bf16 v[64:67], v[206:209], v[52:55], v[56:59]
	v_mfma_f32_16x16x32_bf16 v[56:59], v[206:209], v[222:225], v[28:31]
	v_mfma_f32_16x16x32_bf16 v[28:31], v[210:213], v[218:221], v[40:43]
	v_mfma_f32_16x16x32_bf16 v[52:55], v[214:217], v[222:225], v[28:31]
	v_mfma_f32_16x16x32_bf16 v[28:31], v[198:201], v[226:229], v[44:47]
	v_mfma_f32_16x16x32_bf16 v[44:47], v[206:209], v[230:233], v[28:31]
	v_mfma_f32_16x16x32_bf16 v[28:31], v[210:213], v[226:229], v[100:103]
	v_mfma_f32_16x16x32_bf16 v[40:43], v[214:217], v[230:233], v[28:31]
	v_mfma_f32_16x16x32_bf16 v[28:31], v[198:201], v[234:237], v[104:107]
	v_mfma_f32_16x16x32_bf16 v[36:39], v[206:209], v[238:241], v[28:31]
	v_mfma_f32_16x16x32_bf16 v[28:31], v[210:213], v[234:237], v[108:111]
	v_mfma_f32_16x16x32_bf16 v[28:31], v[214:217], v[238:241], v[28:31]
	s_barrier
	s_setprio 0
	s_mov_b64 s[66:67], 0x180
	s_add_i32 s4, s19, s74
	v_lshl_add_u64 v[32:33], v[158:159], 0, s[66:67]
	s_mov_b32 m0, s4
	ds_read_b128 v[218:221], v204 offset:49152
	ds_read_b128 v[222:225], v204 offset:50176
	ds_read_b128 v[226:229], v204 offset:51200
	ds_read_b128 v[230:233], v204 offset:52224
	ds_read_b128 v[234:237], v204 offset:53248
	ds_read_b128 v[238:241], v204 offset:54272
	ds_read_b128 v[242:245], v204 offset:55296
	ds_read_b128 v[246:249], v204 offset:56320
	global_load_lds_dwordx4 v[32:33], off
	s_add_i32 m0, s4, 0x2000
	s_add_u32 s4, s24, 0x40180
	v_lshl_add_u64 v[32:33], v[188:189], 0, s[66:67]
	s_addc_u32 s5, s25, 0
	s_add_i32 s19, s36, s74
	global_load_lds_dwordx4 v[32:33], off
	v_lshl_add_u64 v[32:33], s[4:5], 0, v[128:129]
	s_mov_b32 m0, s19
	s_nop 0
	global_load_lds_dwordx4 v[32:33], off
	v_lshl_add_u64 v[32:33], s[4:5], 0, v[160:161]
	s_add_i32 m0, s19, 0x2000
	s_nop 0
	global_load_lds_dwordx4 v[32:33], off
	v_lshl_add_u64 v[32:33], v[190:191], 0, s[66:67]
	s_mov_b32 m0, s83
	s_nop 0
	global_load_lds_dwordx4 v[32:33], off
	v_lshl_add_u64 v[32:33], v[250:251], 0, s[66:67]
	s_mov_b32 m0, s84
	v_mov_b32_e32 v250, v202
	global_load_lds_dwordx4 v[32:33], off
	s_waitcnt vmcnt(8) lgkmcnt(0)
	s_setprio 1
	s_barrier
	v_mfma_f32_16x16x32_bf16 v[32:35], v[16:19], v[218:221], v[134:137]
	v_mfma_f32_16x16x32_bf16 v[108:111], v[20:23], v[222:225], v[32:35]
	v_mfma_f32_16x16x32_bf16 v[32:35], v[24:27], v[218:221], v[138:141]
	v_mfma_f32_16x16x32_bf16 v[104:107], v[194:197], v[222:225], v[32:35]
	v_mfma_f32_16x16x32_bf16 v[32:35], v[16:19], v[226:229], v[142:145]
	v_mfma_f32_16x16x32_bf16 v[100:103], v[20:23], v[230:233], v[32:35]
	v_mfma_f32_16x16x32_bf16 v[32:35], v[24:27], v[226:229], v[146:149]
	v_mfma_f32_16x16x32_bf16 v[96:99], v[194:197], v[230:233], v[32:35]
	v_mfma_f32_16x16x32_bf16 v[32:35], v[16:19], v[234:237], v[150:153]
	v_mfma_f32_16x16x32_bf16 v[0:3], v[16:19], v[242:245], v[0:3]
	v_mfma_f32_16x16x32_bf16 v[80:83], v[20:23], v[238:241], v[32:35]
	v_mfma_f32_16x16x32_bf16 v[32:35], v[24:27], v[234:237], v[154:157]
	v_mfma_f32_16x16x32_bf16 v[88:91], v[20:23], v[246:249], v[0:3]
	v_mfma_f32_16x16x32_bf16 v[0:3], v[24:27], v[242:245], v[4:7]
	v_mfma_f32_16x16x32_bf16 v[76:79], v[194:197], v[238:241], v[32:35]
	v_mfma_f32_16x16x32_bf16 v[84:87], v[194:197], v[246:249], v[0:3]
	v_mfma_f32_16x16x32_bf16 v[0:3], v[198:201], v[218:221], v[8:11]
	v_mfma_f32_16x16x32_bf16 v[32:35], v[206:209], v[222:225], v[0:3]
	v_mfma_f32_16x16x32_bf16 v[0:3], v[210:213], v[218:221], v[12:15]
	v_mfma_f32_16x16x32_bf16 v[24:27], v[214:217], v[222:225], v[0:3]
	v_mfma_f32_16x16x32_bf16 v[0:3], v[198:201], v[226:229], v[162:165]
	v_mfma_f32_16x16x32_bf16 v[20:23], v[206:209], v[230:233], v[0:3]
	v_mfma_f32_16x16x32_bf16 v[0:3], v[210:213], v[226:229], v[166:169]
	v_mfma_f32_16x16x32_bf16 v[16:19], v[214:217], v[230:233], v[0:3]
	v_mfma_f32_16x16x32_bf16 v[0:3], v[198:201], v[234:237], v[170:173]
	v_mfma_f32_16x16x32_bf16 v[12:15], v[206:209], v[238:241], v[0:3]
	v_mfma_f32_16x16x32_bf16 v[0:3], v[210:213], v[234:237], v[174:177]
	v_mfma_f32_16x16x32_bf16 v[8:11], v[214:217], v[238:241], v[0:3]
	v_mov_b32_e32 v241, 0x7f
	v_mfma_f32_16x16x32_bf16 v[0:3], v[198:201], v[242:245], v[180:183]
	v_mfma_f32_16x16x32_bf16 v[4:7], v[206:209], v[246:249], v[0:3]
	v_mfma_f32_16x16x32_bf16 v[0:3], v[210:213], v[242:245], v[184:187]
	v_mov_b32_e32 v245, 0x7d
	v_mov_b32_e32 v244, 0x7e
	v_mov_b64_e32 v[242:243], 0x400
	v_mfma_f32_16x16x32_bf16 v[0:3], v[214:217], v[246:249], v[0:3]
	v_mov_b32_e32 v247, 0x77
	v_mov_b32_e32 v246, 0x7c
	v_mov_b32_e32 v248, 0x260
	s_setprio 0
	s_barrier
	s_mov_b32 s4, 2

.LBB0_1214:
	s_add_u32 s24, s90, s92
	s_addc_u32 s25, s91, 0
	s_add_u32 s80, vcc_lo, s92
	s_addc_u32 s94, vcc_hi, 0
	s_add_i32 s95, 0, 0x10000
	s_cmp_eq_u32 s92, s4
	s_cselect_b32 s41, s19, s25
	s_cselect_b32 s40, s36, s24
	s_cselect_b32 s25, s37, s94
	s_cselect_b32 s24, s63, s80
	s_add_i32 s80, 0, 0x14000
	v_add_u32_e32 v150, s95, v203
	v_add_u32_e32 v158, s80, v203
	ds_read_b128 v[138:141], v150
	ds_read_b128 v[142:145], v150 offset:1024
	ds_read_b128 v[146:149], v150 offset:2048
	ds_read_b128 v[150:153], v150 offset:3072
	ds_read_b128 v[154:157], v158
	ds_read_b128 v[162:165], v158 offset:1024
	ds_read_b128 v[166:169], v158 offset:2048
	ds_read_b128 v[170:173], v158 offset:3072
	v_lshl_add_u64 v[158:159], v[134:135], 0, s[92:93]
	s_add_i32 m0, s23, 0xc000
	ds_read_b128 v[174:177], v204
	ds_read_b128 v[180:183], v204 offset:1024
	ds_read_b128 v[184:187], v204 offset:2048
	ds_read_b128 v[194:197], v204 offset:3072
	ds_read_b128 v[198:201], v204 offset:4096
	ds_read_b128 v[206:209], v204 offset:5120
	ds_read_b128 v[210:213], v204 offset:6144
	ds_read_b128 v[214:217], v204 offset:7168
	global_load_lds_dwordx4 v[158:159], off
	v_lshl_add_u64 v[158:159], v[136:137], 0, s[92:93]
	s_add_i32 m0, s23, 0xe000
	s_nop 0
	global_load_lds_dwordx4 v[158:159], off
	s_waitcnt vmcnt(8) lgkmcnt(0)
	s_setprio 1
	s_barrier
	v_mfma_f32_16x16x32_bf16 v[124:127], v[138:141], v[174:177], v[124:127]
	v_mfma_f32_16x16x32_bf16 v[48:51], v[146:149], v[174:177], v[48:51]
	v_mfma_f32_16x16x32_bf16 v[120:123], v[138:141], v[184:187], v[120:123]
	v_mfma_f32_16x16x32_bf16 v[68:71], v[146:149], v[184:187], v[68:71]
	v_mfma_f32_16x16x32_bf16 v[116:119], v[138:141], v[198:201], v[116:119]
	v_mfma_f32_16x16x32_bf16 v[72:75], v[146:149], v[198:201], v[72:75]
	v_mfma_f32_16x16x32_bf16 v[112:115], v[138:141], v[210:213], v[112:115]
	v_mfma_f32_16x16x32_bf16 v[92:95], v[146:149], v[210:213], v[92:95]
	v_mfma_f32_16x16x32_bf16 v[124:127], v[142:145], v[180:183], v[124:127]
	v_mfma_f32_16x16x32_bf16 v[48:51], v[150:153], v[180:183], v[48:51]
	v_mfma_f32_16x16x32_bf16 v[120:123], v[142:145], v[194:197], v[120:123]
	v_mfma_f32_16x16x32_bf16 v[68:71], v[150:153], v[194:197], v[68:71]
	v_mfma_f32_16x16x32_bf16 v[116:119], v[142:145], v[206:209], v[116:119]
	v_mfma_f32_16x16x32_bf16 v[72:75], v[150:153], v[206:209], v[72:75]
	v_mfma_f32_16x16x32_bf16 v[112:115], v[142:145], v[214:217], v[112:115]
	v_mfma_f32_16x16x32_bf16 v[92:95], v[150:153], v[214:217], v[92:95]
	v_mfma_f32_16x16x32_bf16 v[64:67], v[154:157], v[174:177], v[64:67]
	v_mfma_f32_16x16x32_bf16 v[60:63], v[166:169], v[174:177], v[60:63]
	v_mfma_f32_16x16x32_bf16 v[56:59], v[154:157], v[184:187], v[56:59]
	v_mfma_f32_16x16x32_bf16 v[52:55], v[166:169], v[184:187], v[52:55]
	v_mfma_f32_16x16x32_bf16 v[44:47], v[154:157], v[198:201], v[44:47]
	v_mfma_f32_16x16x32_bf16 v[40:43], v[166:169], v[198:201], v[40:43]
	v_mfma_f32_16x16x32_bf16 v[36:39], v[154:157], v[210:213], v[36:39]
	v_mfma_f32_16x16x32_bf16 v[28:31], v[166:169], v[210:213], v[28:31]
	v_mfma_f32_16x16x32_bf16 v[64:67], v[162:165], v[180:183], v[64:67]
	v_mfma_f32_16x16x32_bf16 v[60:63], v[170:173], v[180:183], v[60:63]
	v_mfma_f32_16x16x32_bf16 v[56:59], v[162:165], v[194:197], v[56:59]
	v_mfma_f32_16x16x32_bf16 v[52:55], v[170:173], v[194:197], v[52:55]
	v_mfma_f32_16x16x32_bf16 v[44:47], v[162:165], v[206:209], v[44:47]
	v_mfma_f32_16x16x32_bf16 v[40:43], v[170:173], v[206:209], v[40:43]
	v_mfma_f32_16x16x32_bf16 v[36:39], v[162:165], v[214:217], v[36:39]
	v_mfma_f32_16x16x32_bf16 v[28:31], v[170:173], v[214:217], v[28:31]
	s_barrier
	s_setprio 0
	s_add_i32 s94, s95, s74
	v_lshl_add_u64 v[158:159], s[24:25], 0, v[128:129]
	s_mov_b32 m0, s94
	ds_read_b128 v[174:177], v204 offset:16384
	ds_read_b128 v[180:183], v204 offset:17408
	ds_read_b128 v[184:187], v204 offset:18432
	ds_read_b128 v[194:197], v204 offset:19456
	ds_read_b128 v[198:201], v204 offset:20480
	ds_read_b128 v[206:209], v204 offset:21504
	ds_read_b128 v[210:213], v204 offset:22528
	ds_read_b128 v[214:217], v204 offset:23552
	global_load_lds_dwordx4 v[158:159], off
	s_add_i32 m0, s94, 0x2000
	s_add_u32 s94, s24, 0x40000
	v_lshl_add_u64 v[188:189], s[24:25], 0, v[160:161]
	s_addc_u32 s95, s25, 0
	s_add_i32 s80, s80, s74
	global_load_lds_dwordx4 v[188:189], off
	v_lshl_add_u64 v[190:191], s[94:95], 0, v[128:129]
	s_mov_b32 m0, s80
	v_lshl_add_u64 v[218:219], s[40:41], 0, v[132:133]
	global_load_lds_dwordx4 v[190:191], off
	v_lshl_add_u64 v[190:191], s[94:95], 0, v[160:161]
	s_add_i32 m0, s80, 0x2000
	s_nop 0
	global_load_lds_dwordx4 v[190:191], off
	v_lshl_add_u64 v[190:191], s[40:41], 0, v[130:131]
	s_mov_b32 m0, s23
	s_nop 0
	global_load_lds_dwordx4 v[190:191], off
	s_mov_b32 m0, s77
	s_nop 0
	global_load_lds_dwordx4 v[218:219], off
	s_waitcnt vmcnt(8) lgkmcnt(0)
	s_setprio 1
	s_barrier
	v_mfma_f32_16x16x32_bf16 v[108:111], v[138:141], v[174:177], v[108:111]
	v_mfma_f32_16x16x32_bf16 v[104:107], v[146:149], v[174:177], v[104:107]
	v_mfma_f32_16x16x32_bf16 v[100:103], v[138:141], v[184:187], v[100:103]
	v_mfma_f32_16x16x32_bf16 v[96:99], v[146:149], v[184:187], v[96:99]
	v_mfma_f32_16x16x32_bf16 v[80:83], v[138:141], v[198:201], v[80:83]
	v_mfma_f32_16x16x32_bf16 v[76:79], v[146:149], v[198:201], v[76:79]
	v_mfma_f32_16x16x32_bf16 v[88:91], v[138:141], v[210:213], v[88:91]
	v_mfma_f32_16x16x32_bf16 v[84:87], v[146:149], v[210:213], v[84:87]
	v_mfma_f32_16x16x32_bf16 v[108:111], v[142:145], v[180:183], v[108:111]
	v_mfma_f32_16x16x32_bf16 v[104:107], v[150:153], v[180:183], v[104:107]
	v_mfma_f32_16x16x32_bf16 v[100:103], v[142:145], v[194:197], v[100:103]
	v_mfma_f32_16x16x32_bf16 v[96:99], v[150:153], v[194:197], v[96:99]
	v_mfma_f32_16x16x32_bf16 v[80:83], v[142:145], v[206:209], v[80:83]
	v_mfma_f32_16x16x32_bf16 v[76:79], v[150:153], v[206:209], v[76:79]
	v_mfma_f32_16x16x32_bf16 v[88:91], v[142:145], v[214:217], v[88:91]
	v_mfma_f32_16x16x32_bf16 v[84:87], v[150:153], v[214:217], v[84:87]
	v_mfma_f32_16x16x32_bf16 v[32:35], v[154:157], v[174:177], v[32:35]
	v_mfma_f32_16x16x32_bf16 v[24:27], v[166:169], v[174:177], v[24:27]
	v_mfma_f32_16x16x32_bf16 v[20:23], v[154:157], v[184:187], v[20:23]
	v_mfma_f32_16x16x32_bf16 v[16:19], v[166:169], v[184:187], v[16:19]
	v_mfma_f32_16x16x32_bf16 v[12:15], v[154:157], v[198:201], v[12:15]
	v_mfma_f32_16x16x32_bf16 v[8:11], v[166:169], v[198:201], v[8:11]
	v_mfma_f32_16x16x32_bf16 v[4:7], v[154:157], v[210:213], v[4:7]
	v_mfma_f32_16x16x32_bf16 v[0:3], v[166:169], v[210:213], v[0:3]
	v_mfma_f32_16x16x32_bf16 v[32:35], v[162:165], v[180:183], v[32:35]
	v_mfma_f32_16x16x32_bf16 v[24:27], v[170:173], v[180:183], v[24:27]
	v_mfma_f32_16x16x32_bf16 v[20:23], v[162:165], v[194:197], v[20:23]
	v_mfma_f32_16x16x32_bf16 v[16:19], v[170:173], v[194:197], v[16:19]
	v_mfma_f32_16x16x32_bf16 v[12:15], v[162:165], v[206:209], v[12:15]
	v_mfma_f32_16x16x32_bf16 v[8:11], v[170:173], v[206:209], v[8:11]
	v_mfma_f32_16x16x32_bf16 v[4:7], v[162:165], v[214:217], v[4:7]
	v_mfma_f32_16x16x32_bf16 v[0:3], v[170:173], v[214:217], v[0:3]
	s_barrier
	s_setprio 0
	s_add_i32 s80, 0, 0x18000
	s_add_i32 s94, 0, 0x1c000
	v_add_u32_e32 v150, s80, v203
	v_add_u32_e32 v170, s94, v203
	ds_read_b128 v[138:141], v150
	ds_read_b128 v[142:145], v150 offset:1024
	ds_read_b128 v[146:149], v150 offset:2048
	ds_read_b128 v[150:153], v150 offset:3072
	ds_read_b128 v[154:157], v170
	ds_read_b128 v[162:165], v170 offset:1024
	ds_read_b128 v[166:169], v170 offset:2048
	ds_read_b128 v[170:173], v170 offset:3072
	s_add_u32 s40, s40, 0x40000
	s_addc_u32 s41, s41, 0
	s_mov_b32 m0, s78
	v_lshl_add_u64 v[220:221], s[40:41], 0, v[130:131]
	ds_read_b128 v[174:177], v204 offset:32768
	ds_read_b128 v[180:183], v204 offset:33792
	ds_read_b128 v[184:187], v204 offset:34816
	ds_read_b128 v[194:197], v204 offset:35840
	ds_read_b128 v[198:201], v204 offset:36864
	ds_read_b128 v[206:209], v204 offset:37888
	ds_read_b128 v[210:213], v204 offset:38912
	ds_read_b128 v[214:217], v204 offset:39936
	global_load_lds_dwordx4 v[220:221], off
	v_lshl_add_u64 v[220:221], s[40:41], 0, v[132:133]
	s_mov_b32 m0, s79
	s_nop 0
	global_load_lds_dwordx4 v[220:221], off
	s_waitcnt vmcnt(8) lgkmcnt(0)
	s_setprio 1
	s_barrier
	v_mfma_f32_16x16x32_bf16 v[124:127], v[138:141], v[174:177], v[124:127]
	v_mfma_f32_16x16x32_bf16 v[48:51], v[146:149], v[174:177], v[48:51]
	v_mfma_f32_16x16x32_bf16 v[120:123], v[138:141], v[184:187], v[120:123]
	v_mfma_f32_16x16x32_bf16 v[68:71], v[146:149], v[184:187], v[68:71]
	v_mfma_f32_16x16x32_bf16 v[116:119], v[138:141], v[198:201], v[116:119]
	v_mfma_f32_16x16x32_bf16 v[72:75], v[146:149], v[198:201], v[72:75]
	v_mfma_f32_16x16x32_bf16 v[112:115], v[138:141], v[210:213], v[112:115]
	v_mfma_f32_16x16x32_bf16 v[92:95], v[146:149], v[210:213], v[92:95]
	v_mfma_f32_16x16x32_bf16 v[124:127], v[142:145], v[180:183], v[124:127]
	v_mfma_f32_16x16x32_bf16 v[48:51], v[150:153], v[180:183], v[48:51]
	v_mfma_f32_16x16x32_bf16 v[120:123], v[142:145], v[194:197], v[120:123]
	v_mfma_f32_16x16x32_bf16 v[68:71], v[150:153], v[194:197], v[68:71]
	v_mfma_f32_16x16x32_bf16 v[116:119], v[142:145], v[206:209], v[116:119]
	v_mfma_f32_16x16x32_bf16 v[72:75], v[150:153], v[206:209], v[72:75]
	v_mfma_f32_16x16x32_bf16 v[112:115], v[142:145], v[214:217], v[112:115]
	v_mfma_f32_16x16x32_bf16 v[92:95], v[150:153], v[214:217], v[92:95]
	v_mfma_f32_16x16x32_bf16 v[64:67], v[154:157], v[174:177], v[64:67]
	v_mfma_f32_16x16x32_bf16 v[60:63], v[166:169], v[174:177], v[60:63]
	v_mfma_f32_16x16x32_bf16 v[56:59], v[154:157], v[184:187], v[56:59]
	v_mfma_f32_16x16x32_bf16 v[52:55], v[166:169], v[184:187], v[52:55]
	v_mfma_f32_16x16x32_bf16 v[44:47], v[154:157], v[198:201], v[44:47]
	v_mfma_f32_16x16x32_bf16 v[40:43], v[166:169], v[198:201], v[40:43]
	v_mfma_f32_16x16x32_bf16 v[36:39], v[154:157], v[210:213], v[36:39]
	v_mfma_f32_16x16x32_bf16 v[28:31], v[166:169], v[210:213], v[28:31]
	v_mfma_f32_16x16x32_bf16 v[64:67], v[162:165], v[180:183], v[64:67]
	v_mfma_f32_16x16x32_bf16 v[60:63], v[170:173], v[180:183], v[60:63]
	v_mfma_f32_16x16x32_bf16 v[56:59], v[162:165], v[194:197], v[56:59]
	v_mfma_f32_16x16x32_bf16 v[52:55], v[170:173], v[194:197], v[52:55]
	v_mfma_f32_16x16x32_bf16 v[44:47], v[162:165], v[206:209], v[44:47]
	v_mfma_f32_16x16x32_bf16 v[40:43], v[170:173], v[206:209], v[40:43]
	v_mfma_f32_16x16x32_bf16 v[36:39], v[162:165], v[214:217], v[36:39]
	v_mfma_f32_16x16x32_bf16 v[28:31], v[170:173], v[214:217], v[28:31]
	s_barrier
	s_setprio 0
	s_add_i32 s40, s80, s74
	v_lshl_add_u64 v[158:159], v[158:159], 0, s[14:15]
	s_mov_b32 m0, s40
	ds_read_b128 v[174:177], v204 offset:49152
	ds_read_b128 v[180:183], v204 offset:50176
	ds_read_b128 v[184:187], v204 offset:51200
	ds_read_b128 v[194:197], v204 offset:52224
	ds_read_b128 v[198:201], v204 offset:53248
	ds_read_b128 v[206:209], v204 offset:54272
	ds_read_b128 v[210:213], v204 offset:55296
	ds_read_b128 v[214:217], v204 offset:56320
	global_load_lds_dwordx4 v[158:159], off
	s_add_i32 m0, s40, 0x2000
	s_add_u32 s24, s24, 0x40080
	v_lshl_add_u64 v[158:159], v[188:189], 0, s[14:15]
	s_addc_u32 s25, s25, 0
	s_add_i32 s40, s94, s74
	global_load_lds_dwordx4 v[158:159], off
	v_lshl_add_u64 v[158:159], s[24:25], 0, v[128:129]
	s_mov_b32 m0, s40
	s_nop 0
	global_load_lds_dwordx4 v[158:159], off
	v_lshl_add_u64 v[158:159], s[24:25], 0, v[160:161]
	s_add_i32 m0, s40, 0x2000
	s_nop 0
	global_load_lds_dwordx4 v[158:159], off
	v_lshl_add_u64 v[158:159], v[190:191], 0, s[14:15]
	s_mov_b32 m0, s83
	s_nop 0
	global_load_lds_dwordx4 v[158:159], off
	v_lshl_add_u64 v[158:159], v[218:219], 0, s[14:15]
	s_mov_b32 m0, s84
	s_nop 0
	global_load_lds_dwordx4 v[158:159], off
	s_waitcnt vmcnt(8) lgkmcnt(0)
	s_setprio 1
	s_barrier
	v_mfma_f32_16x16x32_bf16 v[108:111], v[138:141], v[174:177], v[108:111]
	v_mfma_f32_16x16x32_bf16 v[104:107], v[146:149], v[174:177], v[104:107]
	v_mfma_f32_16x16x32_bf16 v[100:103], v[138:141], v[184:187], v[100:103]
	v_mfma_f32_16x16x32_bf16 v[96:99], v[146:149], v[184:187], v[96:99]
	v_mfma_f32_16x16x32_bf16 v[80:83], v[138:141], v[198:201], v[80:83]
	v_mfma_f32_16x16x32_bf16 v[76:79], v[146:149], v[198:201], v[76:79]
	v_mfma_f32_16x16x32_bf16 v[88:91], v[138:141], v[210:213], v[88:91]
	v_mfma_f32_16x16x32_bf16 v[84:87], v[146:149], v[210:213], v[84:87]
	v_mfma_f32_16x16x32_bf16 v[108:111], v[142:145], v[180:183], v[108:111]
	v_mfma_f32_16x16x32_bf16 v[104:107], v[150:153], v[180:183], v[104:107]
	v_mfma_f32_16x16x32_bf16 v[100:103], v[142:145], v[194:197], v[100:103]
	v_mfma_f32_16x16x32_bf16 v[96:99], v[150:153], v[194:197], v[96:99]
	v_mfma_f32_16x16x32_bf16 v[80:83], v[142:145], v[206:209], v[80:83]
	v_mfma_f32_16x16x32_bf16 v[76:79], v[150:153], v[206:209], v[76:79]
	v_mfma_f32_16x16x32_bf16 v[88:91], v[142:145], v[214:217], v[88:91]
	v_mfma_f32_16x16x32_bf16 v[84:87], v[150:153], v[214:217], v[84:87]
	v_mfma_f32_16x16x32_bf16 v[32:35], v[154:157], v[174:177], v[32:35]
	v_mfma_f32_16x16x32_bf16 v[24:27], v[166:169], v[174:177], v[24:27]
	v_mfma_f32_16x16x32_bf16 v[20:23], v[154:157], v[184:187], v[20:23]
	v_mfma_f32_16x16x32_bf16 v[16:19], v[166:169], v[184:187], v[16:19]
	v_mfma_f32_16x16x32_bf16 v[12:15], v[154:157], v[198:201], v[12:15]
	v_mfma_f32_16x16x32_bf16 v[8:11], v[166:169], v[198:201], v[8:11]
	v_mfma_f32_16x16x32_bf16 v[4:7], v[154:157], v[210:213], v[4:7]
	v_mfma_f32_16x16x32_bf16 v[0:3], v[166:169], v[210:213], v[0:3]
	v_mfma_f32_16x16x32_bf16 v[32:35], v[162:165], v[180:183], v[32:35]
	v_mfma_f32_16x16x32_bf16 v[24:27], v[170:173], v[180:183], v[24:27]
	v_mfma_f32_16x16x32_bf16 v[20:23], v[162:165], v[194:197], v[20:23]
	v_mfma_f32_16x16x32_bf16 v[16:19], v[170:173], v[194:197], v[16:19]
	v_mfma_f32_16x16x32_bf16 v[12:15], v[162:165], v[206:209], v[12:15]
	v_mfma_f32_16x16x32_bf16 v[8:11], v[170:173], v[206:209], v[8:11]
	v_mfma_f32_16x16x32_bf16 v[4:7], v[162:165], v[214:217], v[4:7]
	v_mfma_f32_16x16x32_bf16 v[0:3], v[170:173], v[214:217], v[0:3]
	s_barrier
	s_setprio 0
	s_add_i32 s81, s81, 2
	s_add_u32 s90, s90, 0x100
	s_addc_u32 s91, s91, 0
	s_add_u32 vcc_lo, vcc_lo, 0x100
	s_addc_u32 vcc_hi, vcc_hi, 0
	s_add_u32 s4, s4, 0xffffff00
	s_addc_u32 s5, s5, -1
	v_lshl_add_u64 v[134:135], v[134:135], 0, s[16:17]
	s_cmp_gt_u32 s81, 13
	v_lshl_add_u64 v[136:137], v[136:137], 0, s[16:17]
	s_cbranch_scc0 .LBB0_1214
	s_and_b64 vcc, exec, s[58:59]
	s_cbranch_vccz .LBB0_1217
	s_barrier

.LBB0_1375:
	s_ashr_i32 s6, s8, 3
	s_add_i32 s6, s18, s6
	s_mul_hi_i32 s7, s6, 0x2e8ba2e9
	s_lshr_b32 s8, s7, 31
	s_ashr_i32 s7, s7, 5
	s_add_i32 s7, s7, s8
	s_lshl_b32 s8, s7, 3
	s_sub_i32 s9, 0x102, s8
	s_min_i32 s9, s9, 8
	s_mulk_i32 s7, 0xb0
	s_sub_i32 s6, s6, s7
	s_ff1_i32_b32 s18, s9
	s_lshr_b32 s72, s6, s18
	s_lshl_b32 s7, s72, s18
	s_sub_i32 s6, s6, s7
	s_add_i32 s74, s8, s6

.LBB0_1379:
	s_add_i32 s6, 0, 0x10000
	s_add_i32 s7, 0, 0x14000
	v_add_u32_e32 v140, s6, v182
	v_add_u32_e32 v156, s7, v182
	ds_read_b128 v[128:131], v140
	ds_read_b128 v[132:135], v140 offset:1024
	ds_read_b128 v[136:139], v140 offset:2048
	ds_read_b128 v[140:143], v140 offset:3072
	ds_read_b128 v[144:147], v156
	ds_read_b128 v[148:151], v156 offset:1024
	ds_read_b128 v[152:155], v156 offset:2048
	ds_read_b128 v[156:159], v156 offset:3072
	s_add_u32 s4, s78, 0x40080
	s_addc_u32 s5, s79, 0
	v_lshl_add_u64 v[188:189], s[4:5], 0, v[166:167]
	s_add_i32 m0, s55, 0xc000
	ds_read_b128 v[162:165], v183
	ds_read_b128 v[174:177], v183 offset:1024
	ds_read_b128 v[178:181], v183 offset:2048
	ds_read_b128 v[184:187], v183 offset:3072
	ds_read_b128 v[194:197], v183 offset:4096
	ds_read_b128 v[198:201], v183 offset:5120
	ds_read_b128 v[202:205], v183 offset:6144
	ds_read_b128 v[206:209], v183 offset:7168
	global_load_lds_dwordx4 v[188:189], off
	v_lshl_add_u64 v[188:189], s[4:5], 0, v[168:169]
	s_add_i32 m0, s55, 0xe000
	s_nop 0
	global_load_lds_dwordx4 v[188:189], off
	s_waitcnt vmcnt(16) lgkmcnt(0)
	s_setprio 1
	s_barrier
	v_mfma_f32_16x16x32_bf16 v[124:127], v[128:131], v[162:165], 0
	v_mfma_f32_16x16x32_bf16 v[120:123], v[136:139], v[162:165], 0
	v_mfma_f32_16x16x32_bf16 v[116:119], v[128:131], v[178:181], 0
	v_mfma_f32_16x16x32_bf16 v[112:115], v[136:139], v[178:181], 0
	v_mfma_f32_16x16x32_bf16 v[108:111], v[128:131], v[194:197], 0
	v_mfma_f32_16x16x32_bf16 v[104:107], v[136:139], v[194:197], 0
	v_mfma_f32_16x16x32_bf16 v[100:103], v[128:131], v[202:205], 0
	v_mfma_f32_16x16x32_bf16 v[96:99], v[136:139], v[202:205], 0
	v_mfma_f32_16x16x32_bf16 v[124:127], v[132:135], v[174:177], v[124:127]
	v_mfma_f32_16x16x32_bf16 v[120:123], v[140:143], v[174:177], v[120:123]
	v_mfma_f32_16x16x32_bf16 v[116:119], v[132:135], v[184:187], v[116:119]
	v_mfma_f32_16x16x32_bf16 v[112:115], v[140:143], v[184:187], v[112:115]
	v_mfma_f32_16x16x32_bf16 v[108:111], v[132:135], v[198:201], v[108:111]
	v_mfma_f32_16x16x32_bf16 v[104:107], v[140:143], v[198:201], v[104:107]
	v_mfma_f32_16x16x32_bf16 v[100:103], v[132:135], v[206:209], v[100:103]
	v_mfma_f32_16x16x32_bf16 v[96:99], v[140:143], v[206:209], v[96:99]
	v_mfma_f32_16x16x32_bf16 v[92:95], v[144:147], v[162:165], 0
	v_mfma_f32_16x16x32_bf16 v[88:91], v[152:155], v[162:165], 0
	v_mfma_f32_16x16x32_bf16 v[84:87], v[144:147], v[178:181], 0
	v_mfma_f32_16x16x32_bf16 v[80:83], v[152:155], v[178:181], 0
	v_mfma_f32_16x16x32_bf16 v[76:79], v[144:147], v[194:197], 0
	v_mfma_f32_16x16x32_bf16 v[72:75], v[152:155], v[194:197], 0
	v_mfma_f32_16x16x32_bf16 v[68:71], v[144:147], v[202:205], 0
	v_mfma_f32_16x16x32_bf16 v[64:67], v[152:155], v[202:205], 0
	v_mfma_f32_16x16x32_bf16 v[92:95], v[148:151], v[174:177], v[92:95]
	v_mfma_f32_16x16x32_bf16 v[88:91], v[156:159], v[174:177], v[88:91]
	v_mfma_f32_16x16x32_bf16 v[84:87], v[148:151], v[184:187], v[84:87]
	v_mfma_f32_16x16x32_bf16 v[80:83], v[156:159], v[184:187], v[80:83]
	v_mfma_f32_16x16x32_bf16 v[76:79], v[148:151], v[198:201], v[76:79]
	v_mfma_f32_16x16x32_bf16 v[72:75], v[156:159], v[198:201], v[72:75]
	v_mfma_f32_16x16x32_bf16 v[68:71], v[148:151], v[206:209], v[68:71]
	v_mfma_f32_16x16x32_bf16 v[64:67], v[156:159], v[206:209], v[64:67]
	s_barrier
	s_setprio 0
	v_lshl_add_u64 v[188:189], s[76:77], 0, v[172:173]
	s_add_i32 s4, s6, s58
	v_lshl_add_u64 v[190:191], v[188:189], 0, s[16:17]
	s_mov_b32 m0, s4
	ds_read_b128 v[162:165], v183 offset:16384
	ds_read_b128 v[174:177], v183 offset:17408
	ds_read_b128 v[178:181], v183 offset:18432
	ds_read_b128 v[184:187], v183 offset:19456
	ds_read_b128 v[194:197], v183 offset:20480
	ds_read_b128 v[198:201], v183 offset:21504
	ds_read_b128 v[202:205], v183 offset:22528
	ds_read_b128 v[206:209], v183 offset:23552
	global_load_lds_dwordx4 v[190:191], off
	s_add_i32 m0, s4, 0x2000
	v_lshl_add_u64 v[190:191], s[76:77], 0, v[170:171]
	s_add_u32 s4, s76, 0x40100
	v_lshl_add_u64 v[210:211], v[190:191], 0, s[16:17]
	s_addc_u32 s5, s77, 0
	s_add_i32 s6, s7, s58
	global_load_lds_dwordx4 v[210:211], off
	v_lshl_add_u64 v[210:211], s[4:5], 0, v[172:173]
	s_mov_b32 m0, s6
	s_nop 0
	global_load_lds_dwordx4 v[210:211], off
	v_lshl_add_u64 v[210:211], s[4:5], 0, v[170:171]
	s_add_i32 m0, s6, 0x2000
	s_nop 0
	global_load_lds_dwordx4 v[210:211], off
	v_lshl_add_u64 v[210:211], s[78:79], 0, v[166:167]
	v_lshl_add_u64 v[212:213], v[210:211], 0, s[16:17]
	s_mov_b32 m0, s55
	s_nop 0
	global_load_lds_dwordx4 v[212:213], off
	v_lshl_add_u64 v[212:213], s[78:79], 0, v[168:169]
	v_lshl_add_u64 v[214:215], v[212:213], 0, s[16:17]
	s_mov_b32 m0, s59
	s_nop 0
	global_load_lds_dwordx4 v[214:215], off
	s_waitcnt vmcnt(16) lgkmcnt(0)
	s_setprio 1
	s_barrier
	v_mfma_f32_16x16x32_bf16 v[60:63], v[128:131], v[162:165], 0
	v_mfma_f32_16x16x32_bf16 v[56:59], v[136:139], v[162:165], 0
	v_mfma_f32_16x16x32_bf16 v[52:55], v[128:131], v[178:181], 0
	v_mfma_f32_16x16x32_bf16 v[48:51], v[136:139], v[178:181], 0
	v_mfma_f32_16x16x32_bf16 v[44:47], v[128:131], v[194:197], 0
	v_mfma_f32_16x16x32_bf16 v[40:43], v[136:139], v[194:197], 0
	v_mfma_f32_16x16x32_bf16 v[36:39], v[128:131], v[202:205], 0
	v_mfma_f32_16x16x32_bf16 v[32:35], v[136:139], v[202:205], 0
	v_mfma_f32_16x16x32_bf16 v[60:63], v[132:135], v[174:177], v[60:63]
	v_mfma_f32_16x16x32_bf16 v[56:59], v[140:143], v[174:177], v[56:59]
	v_mfma_f32_16x16x32_bf16 v[52:55], v[132:135], v[184:187], v[52:55]
	v_mfma_f32_16x16x32_bf16 v[48:51], v[140:143], v[184:187], v[48:51]
	v_mfma_f32_16x16x32_bf16 v[44:47], v[132:135], v[198:201], v[44:47]
	v_mfma_f32_16x16x32_bf16 v[40:43], v[140:143], v[198:201], v[40:43]
	v_mfma_f32_16x16x32_bf16 v[36:39], v[132:135], v[206:209], v[36:39]
	v_mfma_f32_16x16x32_bf16 v[32:35], v[140:143], v[206:209], v[32:35]
	v_mfma_f32_16x16x32_bf16 v[28:31], v[144:147], v[162:165], 0
	v_mfma_f32_16x16x32_bf16 v[24:27], v[152:155], v[162:165], 0
	v_mfma_f32_16x16x32_bf16 v[20:23], v[144:147], v[178:181], 0
	v_mfma_f32_16x16x32_bf16 v[16:19], v[152:155], v[178:181], 0
	v_mfma_f32_16x16x32_bf16 v[12:15], v[144:147], v[194:197], 0
	v_mfma_f32_16x16x32_bf16 v[8:11], v[152:155], v[194:197], 0
	v_mfma_f32_16x16x32_bf16 v[4:7], v[144:147], v[202:205], 0
	v_mfma_f32_16x16x32_bf16 v[0:3], v[152:155], v[202:205], 0
	v_mfma_f32_16x16x32_bf16 v[28:31], v[148:151], v[174:177], v[28:31]
	v_mfma_f32_16x16x32_bf16 v[24:27], v[156:159], v[174:177], v[24:27]
	v_mfma_f32_16x16x32_bf16 v[20:23], v[148:151], v[184:187], v[20:23]
	v_mfma_f32_16x16x32_bf16 v[16:19], v[156:159], v[184:187], v[16:19]
	v_mfma_f32_16x16x32_bf16 v[12:15], v[148:151], v[198:201], v[12:15]
	v_mfma_f32_16x16x32_bf16 v[8:11], v[156:159], v[198:201], v[8:11]
	v_mfma_f32_16x16x32_bf16 v[4:7], v[148:151], v[206:209], v[4:7]
	v_mfma_f32_16x16x32_bf16 v[0:3], v[156:159], v[206:209], v[0:3]
	s_barrier
	s_setprio 0
	s_add_i32 s6, 0, 0x18000
	s_add_i32 s7, 0, 0x1c000
	v_add_u32_e32 v140, s6, v182
	v_add_u32_e32 v156, s7, v182
	ds_read_b128 v[128:131], v140
	ds_read_b128 v[132:135], v140 offset:1024
	ds_read_b128 v[136:139], v140 offset:2048
	ds_read_b128 v[140:143], v140 offset:3072
	ds_read_b128 v[144:147], v156
	ds_read_b128 v[148:151], v156 offset:1024
	ds_read_b128 v[152:155], v156 offset:2048
	ds_read_b128 v[156:159], v156 offset:3072
	s_add_u32 s4, s78, 0x40100
	s_addc_u32 s5, s79, 0
	s_mov_b32 m0, s1
	v_lshl_add_u64 v[214:215], s[4:5], 0, v[166:167]
	ds_read_b128 v[162:165], v183 offset:32768
	ds_read_b128 v[174:177], v183 offset:33792
	ds_read_b128 v[178:181], v183 offset:34816
	ds_read_b128 v[184:187], v183 offset:35840
	ds_read_b128 v[194:197], v183 offset:36864
	ds_read_b128 v[198:201], v183 offset:37888
	ds_read_b128 v[202:205], v183 offset:38912
	ds_read_b128 v[206:209], v183 offset:39936
	global_load_lds_dwordx4 v[214:215], off
	v_lshl_add_u64 v[214:215], s[4:5], 0, v[168:169]
	s_mov_b32 m0, s50
	s_nop 0
	global_load_lds_dwordx4 v[214:215], off
	s_waitcnt vmcnt(8) lgkmcnt(0)
	s_setprio 1
	s_barrier
	v_mfma_f32_16x16x32_bf16 v[124:127], v[128:131], v[162:165], v[124:127]
	v_mfma_f32_16x16x32_bf16 v[120:123], v[136:139], v[162:165], v[120:123]
	v_mfma_f32_16x16x32_bf16 v[116:119], v[128:131], v[178:181], v[116:119]
	v_mfma_f32_16x16x32_bf16 v[112:115], v[136:139], v[178:181], v[112:115]
	v_mfma_f32_16x16x32_bf16 v[108:111], v[128:131], v[194:197], v[108:111]
	v_mfma_f32_16x16x32_bf16 v[104:107], v[136:139], v[194:197], v[104:107]
	v_mfma_f32_16x16x32_bf16 v[100:103], v[128:131], v[202:205], v[100:103]
	v_mfma_f32_16x16x32_bf16 v[96:99], v[136:139], v[202:205], v[96:99]
	v_mfma_f32_16x16x32_bf16 v[124:127], v[132:135], v[174:177], v[124:127]
	v_mfma_f32_16x16x32_bf16 v[120:123], v[140:143], v[174:177], v[120:123]
	v_mfma_f32_16x16x32_bf16 v[116:119], v[132:135], v[184:187], v[116:119]
	v_mfma_f32_16x16x32_bf16 v[112:115], v[140:143], v[184:187], v[112:115]
	v_mfma_f32_16x16x32_bf16 v[108:111], v[132:135], v[198:201], v[108:111]
	v_mfma_f32_16x16x32_bf16 v[104:107], v[140:143], v[198:201], v[104:107]
	v_mfma_f32_16x16x32_bf16 v[100:103], v[132:135], v[206:209], v[100:103]
	v_mfma_f32_16x16x32_bf16 v[96:99], v[140:143], v[206:209], v[96:99]
	v_mfma_f32_16x16x32_bf16 v[92:95], v[144:147], v[162:165], v[92:95]
	v_mfma_f32_16x16x32_bf16 v[88:91], v[152:155], v[162:165], v[88:91]
	v_mfma_f32_16x16x32_bf16 v[84:87], v[144:147], v[178:181], v[84:87]
	v_mfma_f32_16x16x32_bf16 v[80:83], v[152:155], v[178:181], v[80:83]
	v_mfma_f32_16x16x32_bf16 v[76:79], v[144:147], v[194:197], v[76:79]
	v_mfma_f32_16x16x32_bf16 v[72:75], v[152:155], v[194:197], v[72:75]
	v_mfma_f32_16x16x32_bf16 v[68:71], v[144:147], v[202:205], v[68:71]
	v_mfma_f32_16x16x32_bf16 v[64:67], v[152:155], v[202:205], v[64:67]
	v_mfma_f32_16x16x32_bf16 v[92:95], v[148:151], v[174:177], v[92:95]
	v_mfma_f32_16x16x32_bf16 v[88:91], v[156:159], v[174:177], v[88:91]
	v_mfma_f32_16x16x32_bf16 v[84:87], v[148:151], v[184:187], v[84:87]
	v_mfma_f32_16x16x32_bf16 v[80:83], v[156:159], v[184:187], v[80:83]
	v_mfma_f32_16x16x32_bf16 v[76:79], v[148:151], v[198:201], v[76:79]
	v_mfma_f32_16x16x32_bf16 v[72:75], v[156:159], v[198:201], v[72:75]
	v_mfma_f32_16x16x32_bf16 v[68:71], v[148:151], v[206:209], v[68:71]
	v_mfma_f32_16x16x32_bf16 v[64:67], v[156:159], v[206:209], v[64:67]
	s_barrier
	s_setprio 0
	s_mov_b64 s[8:9], 0x180
	s_add_i32 s4, s6, s58
	v_lshl_add_u64 v[188:189], v[188:189], 0, s[8:9]
	s_mov_b32 m0, s4
	ds_read_b128 v[162:165], v183 offset:49152
	ds_read_b128 v[174:177], v183 offset:50176
	ds_read_b128 v[178:181], v183 offset:51200
	ds_read_b128 v[184:187], v183 offset:52224
	ds_read_b128 v[194:197], v183 offset:53248
	ds_read_b128 v[198:201], v183 offset:54272
	ds_read_b128 v[202:205], v183 offset:55296
	ds_read_b128 v[206:209], v183 offset:56320
	global_load_lds_dwordx4 v[188:189], off
	s_add_i32 m0, s4, 0x2000
	s_add_u32 s4, s76, 0x40180
	v_lshl_add_u64 v[188:189], v[190:191], 0, s[8:9]
	s_addc_u32 s5, s77, 0
	s_add_i32 s6, s7, s58
	global_load_lds_dwordx4 v[188:189], off
	v_lshl_add_u64 v[188:189], s[4:5], 0, v[172:173]
	s_mov_b32 m0, s6
	s_nop 0
	global_load_lds_dwordx4 v[188:189], off
	v_lshl_add_u64 v[188:189], s[4:5], 0, v[170:171]
	s_add_i32 m0, s6, 0x2000
	s_nop 0
	global_load_lds_dwordx4 v[188:189], off
	v_lshl_add_u64 v[188:189], v[210:211], 0, s[8:9]
	s_mov_b32 m0, s62
	s_nop 0
	global_load_lds_dwordx4 v[188:189], off
	v_lshl_add_u64 v[188:189], v[212:213], 0, s[8:9]
	s_mov_b32 m0, s63
	s_nop 0
	global_load_lds_dwordx4 v[188:189], off
	s_waitcnt vmcnt(8) lgkmcnt(0)
	s_setprio 1
	s_barrier
	v_mfma_f32_16x16x32_bf16 v[60:63], v[128:131], v[162:165], v[60:63]
	v_mfma_f32_16x16x32_bf16 v[56:59], v[136:139], v[162:165], v[56:59]
	v_mfma_f32_16x16x32_bf16 v[52:55], v[128:131], v[178:181], v[52:55]
	v_mfma_f32_16x16x32_bf16 v[48:51], v[136:139], v[178:181], v[48:51]
	v_mfma_f32_16x16x32_bf16 v[44:47], v[128:131], v[194:197], v[44:47]
	v_mfma_f32_16x16x32_bf16 v[40:43], v[136:139], v[194:197], v[40:43]
	v_mfma_f32_16x16x32_bf16 v[36:39], v[128:131], v[202:205], v[36:39]
	v_mfma_f32_16x16x32_bf16 v[32:35], v[136:139], v[202:205], v[32:35]
	v_mfma_f32_16x16x32_bf16 v[60:63], v[132:135], v[174:177], v[60:63]
	v_mfma_f32_16x16x32_bf16 v[56:59], v[140:143], v[174:177], v[56:59]
	v_mfma_f32_16x16x32_bf16 v[52:55], v[132:135], v[184:187], v[52:55]
	v_mfma_f32_16x16x32_bf16 v[48:51], v[140:143], v[184:187], v[48:51]
	v_mfma_f32_16x16x32_bf16 v[44:47], v[132:135], v[198:201], v[44:47]
	v_mfma_f32_16x16x32_bf16 v[40:43], v[140:143], v[198:201], v[40:43]
	v_mfma_f32_16x16x32_bf16 v[36:39], v[132:135], v[206:209], v[36:39]
	v_mfma_f32_16x16x32_bf16 v[32:35], v[140:143], v[206:209], v[32:35]
	v_mfma_f32_16x16x32_bf16 v[28:31], v[144:147], v[162:165], v[28:31]
	v_mfma_f32_16x16x32_bf16 v[24:27], v[152:155], v[162:165], v[24:27]
	v_mfma_f32_16x16x32_bf16 v[20:23], v[144:147], v[178:181], v[20:23]
	v_mfma_f32_16x16x32_bf16 v[16:19], v[152:155], v[178:181], v[16:19]
	v_mfma_f32_16x16x32_bf16 v[12:15], v[144:147], v[194:197], v[12:15]
	v_mfma_f32_16x16x32_bf16 v[8:11], v[152:155], v[194:197], v[8:11]
	v_mfma_f32_16x16x32_bf16 v[4:7], v[144:147], v[202:205], v[4:7]
	v_mfma_f32_16x16x32_bf16 v[0:3], v[152:155], v[202:205], v[0:3]
	v_mfma_f32_16x16x32_bf16 v[28:31], v[148:151], v[174:177], v[28:31]
	v_mfma_f32_16x16x32_bf16 v[24:27], v[156:159], v[174:177], v[24:27]
	v_mfma_f32_16x16x32_bf16 v[20:23], v[148:151], v[184:187], v[20:23]
	v_mfma_f32_16x16x32_bf16 v[16:19], v[156:159], v[184:187], v[16:19]
	v_mfma_f32_16x16x32_bf16 v[12:15], v[148:151], v[198:201], v[12:15]
	v_mfma_f32_16x16x32_bf16 v[8:11], v[156:159], v[198:201], v[8:11]
	v_mfma_f32_16x16x32_bf16 v[4:7], v[148:151], v[206:209], v[4:7]
	v_mfma_f32_16x16x32_bf16 v[0:3], v[156:159], v[206:209], v[0:3]
	s_barrier
	s_setprio 0
	s_mov_b32 s4, 2

.LBB0_1381:
	s_add_u32 s8, s43, s92
	s_addc_u32 s9, s44, 0
	s_add_u32 s47, s45, s92
	s_addc_u32 s48, s46, 0
	s_add_i32 s49, 0, 0x10000
	s_cmp_eq_u32 s92, s4
	s_cselect_b32 s23, s18, s9
	s_cselect_b32 s22, s19, s8
	s_cselect_b32 s9, s24, s48
	s_cselect_b32 s8, s25, s47
	s_add_i32 s47, 0, 0x14000
	v_add_u32_e32 v144, s49, v182
	v_add_u32_e32 v160, s47, v182
	ds_read_b128 v[132:135], v144
	ds_read_b128 v[136:139], v144 offset:1024
	ds_read_b128 v[140:143], v144 offset:2048
	ds_read_b128 v[144:147], v144 offset:3072
	ds_read_b128 v[148:151], v160
	ds_read_b128 v[152:155], v160 offset:1024
	ds_read_b128 v[156:159], v160 offset:2048
	ds_read_b128 v[162:165], v160 offset:3072
	v_lshl_add_u64 v[188:189], v[128:129], 0, s[92:93]
	s_add_i32 m0, s55, 0xc000
	ds_read_b128 v[174:177], v183
	ds_read_b128 v[178:181], v183 offset:1024
	ds_read_b128 v[184:187], v183 offset:2048
	ds_read_b128 v[194:197], v183 offset:3072
	ds_read_b128 v[198:201], v183 offset:4096
	ds_read_b128 v[202:205], v183 offset:5120
	ds_read_b128 v[206:209], v183 offset:6144
	ds_read_b128 v[210:213], v183 offset:7168
	global_load_lds_dwordx4 v[188:189], off
	v_lshl_add_u64 v[188:189], v[130:131], 0, s[92:93]
	s_add_i32 m0, s55, 0xe000
	s_nop 0
	global_load_lds_dwordx4 v[188:189], off
	s_waitcnt vmcnt(8) lgkmcnt(0)
	s_setprio 1
	s_barrier
	v_mfma_f32_16x16x32_bf16 v[124:127], v[132:135], v[174:177], v[124:127]
	v_mfma_f32_16x16x32_bf16 v[120:123], v[140:143], v[174:177], v[120:123]
	v_mfma_f32_16x16x32_bf16 v[116:119], v[132:135], v[184:187], v[116:119]
	v_mfma_f32_16x16x32_bf16 v[112:115], v[140:143], v[184:187], v[112:115]
	v_mfma_f32_16x16x32_bf16 v[108:111], v[132:135], v[198:201], v[108:111]
	v_mfma_f32_16x16x32_bf16 v[104:107], v[140:143], v[198:201], v[104:107]
	v_mfma_f32_16x16x32_bf16 v[100:103], v[132:135], v[206:209], v[100:103]
	v_mfma_f32_16x16x32_bf16 v[96:99], v[140:143], v[206:209], v[96:99]
	v_mfma_f32_16x16x32_bf16 v[124:127], v[136:139], v[178:181], v[124:127]
	v_mfma_f32_16x16x32_bf16 v[120:123], v[144:147], v[178:181], v[120:123]
	v_mfma_f32_16x16x32_bf16 v[116:119], v[136:139], v[194:197], v[116:119]
	v_mfma_f32_16x16x32_bf16 v[112:115], v[144:147], v[194:197], v[112:115]
	v_mfma_f32_16x16x32_bf16 v[108:111], v[136:139], v[202:205], v[108:111]
	v_mfma_f32_16x16x32_bf16 v[104:107], v[144:147], v[202:205], v[104:107]
	v_mfma_f32_16x16x32_bf16 v[100:103], v[136:139], v[210:213], v[100:103]
	v_mfma_f32_16x16x32_bf16 v[96:99], v[144:147], v[210:213], v[96:99]
	v_mfma_f32_16x16x32_bf16 v[92:95], v[148:151], v[174:177], v[92:95]
	v_mfma_f32_16x16x32_bf16 v[88:91], v[156:159], v[174:177], v[88:91]
	v_mfma_f32_16x16x32_bf16 v[84:87], v[148:151], v[184:187], v[84:87]
	v_mfma_f32_16x16x32_bf16 v[80:83], v[156:159], v[184:187], v[80:83]
	v_mfma_f32_16x16x32_bf16 v[76:79], v[148:151], v[198:201], v[76:79]
	v_mfma_f32_16x16x32_bf16 v[72:75], v[156:159], v[198:201], v[72:75]
	v_mfma_f32_16x16x32_bf16 v[68:71], v[148:151], v[206:209], v[68:71]
	v_mfma_f32_16x16x32_bf16 v[64:67], v[156:159], v[206:209], v[64:67]
	v_mfma_f32_16x16x32_bf16 v[92:95], v[152:155], v[178:181], v[92:95]
	v_mfma_f32_16x16x32_bf16 v[88:91], v[162:165], v[178:181], v[88:91]
	v_mfma_f32_16x16x32_bf16 v[84:87], v[152:155], v[194:197], v[84:87]
	v_mfma_f32_16x16x32_bf16 v[80:83], v[162:165], v[194:197], v[80:83]
	v_mfma_f32_16x16x32_bf16 v[76:79], v[152:155], v[202:205], v[76:79]
	v_mfma_f32_16x16x32_bf16 v[72:75], v[162:165], v[202:205], v[72:75]
	v_mfma_f32_16x16x32_bf16 v[68:71], v[152:155], v[210:213], v[68:71]
	v_mfma_f32_16x16x32_bf16 v[64:67], v[162:165], v[210:213], v[64:67]
	s_barrier
	s_setprio 0
	s_add_i32 s48, s49, s58
	v_lshl_add_u64 v[188:189], s[8:9], 0, v[172:173]
	s_mov_b32 m0, s48
	ds_read_b128 v[174:177], v183 offset:16384
	ds_read_b128 v[178:181], v183 offset:17408
	ds_read_b128 v[184:187], v183 offset:18432
	ds_read_b128 v[194:197], v183 offset:19456
	ds_read_b128 v[198:201], v183 offset:20480
	ds_read_b128 v[202:205], v183 offset:21504
	ds_read_b128 v[206:209], v183 offset:22528
	ds_read_b128 v[210:213], v183 offset:23552
	global_load_lds_dwordx4 v[188:189], off
	s_add_i32 m0, s48, 0x2000
	s_add_u32 s48, s8, 0x40000
	v_lshl_add_u64 v[190:191], s[8:9], 0, v[170:171]
	s_addc_u32 s49, s9, 0
	s_add_i32 s47, s47, s58
	global_load_lds_dwordx4 v[190:191], off
	v_lshl_add_u64 v[214:215], s[48:49], 0, v[172:173]
	s_mov_b32 m0, s47
	v_lshl_add_u64 v[216:217], s[22:23], 0, v[168:169]
	global_load_lds_dwordx4 v[214:215], off
	v_lshl_add_u64 v[214:215], s[48:49], 0, v[170:171]
	s_add_i32 m0, s47, 0x2000
	s_nop 0
	global_load_lds_dwordx4 v[214:215], off
	v_lshl_add_u64 v[214:215], s[22:23], 0, v[166:167]
	s_mov_b32 m0, s55
	s_nop 0
	global_load_lds_dwordx4 v[214:215], off
	s_mov_b32 m0, s59
	s_nop 0
	global_load_lds_dwordx4 v[216:217], off
	s_waitcnt vmcnt(8) lgkmcnt(0)
	s_setprio 1
	s_barrier
	v_mfma_f32_16x16x32_bf16 v[60:63], v[132:135], v[174:177], v[60:63]
	v_mfma_f32_16x16x32_bf16 v[56:59], v[140:143], v[174:177], v[56:59]
	v_mfma_f32_16x16x32_bf16 v[52:55], v[132:135], v[184:187], v[52:55]
	v_mfma_f32_16x16x32_bf16 v[48:51], v[140:143], v[184:187], v[48:51]
	v_mfma_f32_16x16x32_bf16 v[44:47], v[132:135], v[198:201], v[44:47]
	v_mfma_f32_16x16x32_bf16 v[40:43], v[140:143], v[198:201], v[40:43]
	v_mfma_f32_16x16x32_bf16 v[36:39], v[132:135], v[206:209], v[36:39]
	v_mfma_f32_16x16x32_bf16 v[32:35], v[140:143], v[206:209], v[32:35]
	v_mfma_f32_16x16x32_bf16 v[60:63], v[136:139], v[178:181], v[60:63]
	v_mfma_f32_16x16x32_bf16 v[56:59], v[144:147], v[178:181], v[56:59]
	v_mfma_f32_16x16x32_bf16 v[52:55], v[136:139], v[194:197], v[52:55]
	v_mfma_f32_16x16x32_bf16 v[48:51], v[144:147], v[194:197], v[48:51]
	v_mfma_f32_16x16x32_bf16 v[44:47], v[136:139], v[202:205], v[44:47]
	v_mfma_f32_16x16x32_bf16 v[40:43], v[144:147], v[202:205], v[40:43]
	v_mfma_f32_16x16x32_bf16 v[36:39], v[136:139], v[210:213], v[36:39]
	v_mfma_f32_16x16x32_bf16 v[32:35], v[144:147], v[210:213], v[32:35]
	v_mfma_f32_16x16x32_bf16 v[28:31], v[148:151], v[174:177], v[28:31]
	v_mfma_f32_16x16x32_bf16 v[24:27], v[156:159], v[174:177], v[24:27]
	v_mfma_f32_16x16x32_bf16 v[20:23], v[148:151], v[184:187], v[20:23]
	v_mfma_f32_16x16x32_bf16 v[16:19], v[156:159], v[184:187], v[16:19]
	v_mfma_f32_16x16x32_bf16 v[12:15], v[148:151], v[198:201], v[12:15]
	v_mfma_f32_16x16x32_bf16 v[8:11], v[156:159], v[198:201], v[8:11]
	v_mfma_f32_16x16x32_bf16 v[4:7], v[148:151], v[206:209], v[4:7]
	v_mfma_f32_16x16x32_bf16 v[0:3], v[156:159], v[206:209], v[0:3]
	v_mfma_f32_16x16x32_bf16 v[28:31], v[152:155], v[178:181], v[28:31]
	v_mfma_f32_16x16x32_bf16 v[24:27], v[162:165], v[178:181], v[24:27]
	v_mfma_f32_16x16x32_bf16 v[20:23], v[152:155], v[194:197], v[20:23]
	v_mfma_f32_16x16x32_bf16 v[16:19], v[162:165], v[194:197], v[16:19]
	v_mfma_f32_16x16x32_bf16 v[12:15], v[152:155], v[202:205], v[12:15]
	v_mfma_f32_16x16x32_bf16 v[8:11], v[162:165], v[202:205], v[8:11]
	v_mfma_f32_16x16x32_bf16 v[4:7], v[152:155], v[210:213], v[4:7]
	v_mfma_f32_16x16x32_bf16 v[0:3], v[162:165], v[210:213], v[0:3]
	s_barrier
	s_setprio 0
	s_add_i32 s47, 0, 0x18000
	s_add_i32 s48, 0, 0x1c000
	v_add_u32_e32 v144, s47, v182
	v_add_u32_e32 v160, s48, v182
	ds_read_b128 v[132:135], v144
	ds_read_b128 v[136:139], v144 offset:1024
	ds_read_b128 v[140:143], v144 offset:2048
	ds_read_b128 v[144:147], v144 offset:3072
	ds_read_b128 v[148:151], v160
	ds_read_b128 v[152:155], v160 offset:1024
	ds_read_b128 v[156:159], v160 offset:2048
	ds_read_b128 v[162:165], v160 offset:3072
	s_add_u32 s22, s22, 0x40000
	s_addc_u32 s23, s23, 0
	s_mov_b32 m0, s1
	v_lshl_add_u64 v[218:219], s[22:23], 0, v[166:167]
	ds_read_b128 v[174:177], v183 offset:32768
	ds_read_b128 v[178:181], v183 offset:33792
	ds_read_b128 v[184:187], v183 offset:34816
	ds_read_b128 v[194:197], v183 offset:35840
	ds_read_b128 v[198:201], v183 offset:36864
	ds_read_b128 v[202:205], v183 offset:37888
	ds_read_b128 v[206:209], v183 offset:38912
	ds_read_b128 v[210:213], v183 offset:39936
	global_load_lds_dwordx4 v[218:219], off
	v_lshl_add_u64 v[218:219], s[22:23], 0, v[168:169]
	s_mov_b32 m0, s50
	s_nop 0
	global_load_lds_dwordx4 v[218:219], off
	s_waitcnt vmcnt(8) lgkmcnt(0)
	s_setprio 1
	s_barrier
	v_mfma_f32_16x16x32_bf16 v[124:127], v[132:135], v[174:177], v[124:127]
	v_mfma_f32_16x16x32_bf16 v[120:123], v[140:143], v[174:177], v[120:123]
	v_mfma_f32_16x16x32_bf16 v[116:119], v[132:135], v[184:187], v[116:119]
	v_mfma_f32_16x16x32_bf16 v[112:115], v[140:143], v[184:187], v[112:115]
	v_mfma_f32_16x16x32_bf16 v[108:111], v[132:135], v[198:201], v[108:111]
	v_mfma_f32_16x16x32_bf16 v[104:107], v[140:143], v[198:201], v[104:107]
	v_mfma_f32_16x16x32_bf16 v[100:103], v[132:135], v[206:209], v[100:103]
	v_mfma_f32_16x16x32_bf16 v[96:99], v[140:143], v[206:209], v[96:99]
	v_mfma_f32_16x16x32_bf16 v[124:127], v[136:139], v[178:181], v[124:127]
	v_mfma_f32_16x16x32_bf16 v[120:123], v[144:147], v[178:181], v[120:123]
	v_mfma_f32_16x16x32_bf16 v[116:119], v[136:139], v[194:197], v[116:119]
	v_mfma_f32_16x16x32_bf16 v[112:115], v[144:147], v[194:197], v[112:115]
	v_mfma_f32_16x16x32_bf16 v[108:111], v[136:139], v[202:205], v[108:111]
	v_mfma_f32_16x16x32_bf16 v[104:107], v[144:147], v[202:205], v[104:107]
	v_mfma_f32_16x16x32_bf16 v[100:103], v[136:139], v[210:213], v[100:103]
	v_mfma_f32_16x16x32_bf16 v[96:99], v[144:147], v[210:213], v[96:99]
	v_mfma_f32_16x16x32_bf16 v[92:95], v[148:151], v[174:177], v[92:95]
	v_mfma_f32_16x16x32_bf16 v[88:91], v[156:159], v[174:177], v[88:91]
	v_mfma_f32_16x16x32_bf16 v[84:87], v[148:151], v[184:187], v[84:87]
	v_mfma_f32_16x16x32_bf16 v[80:83], v[156:159], v[184:187], v[80:83]
	v_mfma_f32_16x16x32_bf16 v[76:79], v[148:151], v[198:201], v[76:79]
	v_mfma_f32_16x16x32_bf16 v[72:75], v[156:159], v[198:201], v[72:75]
	v_mfma_f32_16x16x32_bf16 v[68:71], v[148:151], v[206:209], v[68:71]
	v_mfma_f32_16x16x32_bf16 v[64:67], v[156:159], v[206:209], v[64:67]
	v_mfma_f32_16x16x32_bf16 v[92:95], v[152:155], v[178:181], v[92:95]
	v_mfma_f32_16x16x32_bf16 v[88:91], v[162:165], v[178:181], v[88:91]
	v_mfma_f32_16x16x32_bf16 v[84:87], v[152:155], v[194:197], v[84:87]
	v_mfma_f32_16x16x32_bf16 v[80:83], v[162:165], v[194:197], v[80:83]
	v_mfma_f32_16x16x32_bf16 v[76:79], v[152:155], v[202:205], v[76:79]
	v_mfma_f32_16x16x32_bf16 v[72:75], v[162:165], v[202:205], v[72:75]
	v_mfma_f32_16x16x32_bf16 v[68:71], v[152:155], v[210:213], v[68:71]
	v_mfma_f32_16x16x32_bf16 v[64:67], v[162:165], v[210:213], v[64:67]
	s_barrier
	s_setprio 0
	s_add_i32 s22, s47, s58
	v_lshl_add_u64 v[188:189], v[188:189], 0, s[14:15]
	s_mov_b32 m0, s22
	ds_read_b128 v[174:177], v183 offset:49152
	ds_read_b128 v[178:181], v183 offset:50176
	ds_read_b128 v[184:187], v183 offset:51200
	ds_read_b128 v[194:197], v183 offset:52224
	ds_read_b128 v[198:201], v183 offset:53248
	ds_read_b128 v[202:205], v183 offset:54272
	ds_read_b128 v[206:209], v183 offset:55296
	ds_read_b128 v[210:213], v183 offset:56320
	global_load_lds_dwordx4 v[188:189], off
	s_add_i32 m0, s22, 0x2000
	s_add_u32 s8, s8, 0x40080
	v_lshl_add_u64 v[188:189], v[190:191], 0, s[14:15]
	s_addc_u32 s9, s9, 0
	s_add_i32 s22, s48, s58
	global_load_lds_dwordx4 v[188:189], off
	v_lshl_add_u64 v[188:189], s[8:9], 0, v[172:173]
	s_mov_b32 m0, s22
	s_nop 0
	global_load_lds_dwordx4 v[188:189], off
	v_lshl_add_u64 v[188:189], s[8:9], 0, v[170:171]
	s_add_i32 m0, s22, 0x2000
	s_nop 0
	global_load_lds_dwordx4 v[188:189], off
	v_lshl_add_u64 v[188:189], v[214:215], 0, s[14:15]
	s_mov_b32 m0, s62
	s_nop 0
	global_load_lds_dwordx4 v[188:189], off
	v_lshl_add_u64 v[188:189], v[216:217], 0, s[14:15]
	s_mov_b32 m0, s63
	s_nop 0
	global_load_lds_dwordx4 v[188:189], off
	s_waitcnt vmcnt(8) lgkmcnt(0)
	s_setprio 1
	s_barrier
	v_mfma_f32_16x16x32_bf16 v[60:63], v[132:135], v[174:177], v[60:63]
	v_mfma_f32_16x16x32_bf16 v[56:59], v[140:143], v[174:177], v[56:59]
	v_mfma_f32_16x16x32_bf16 v[52:55], v[132:135], v[184:187], v[52:55]
	v_mfma_f32_16x16x32_bf16 v[48:51], v[140:143], v[184:187], v[48:51]
	v_mfma_f32_16x16x32_bf16 v[44:47], v[132:135], v[198:201], v[44:47]
	v_mfma_f32_16x16x32_bf16 v[40:43], v[140:143], v[198:201], v[40:43]
	v_mfma_f32_16x16x32_bf16 v[36:39], v[132:135], v[206:209], v[36:39]
	v_mfma_f32_16x16x32_bf16 v[32:35], v[140:143], v[206:209], v[32:35]
	v_mfma_f32_16x16x32_bf16 v[60:63], v[136:139], v[178:181], v[60:63]
	v_mfma_f32_16x16x32_bf16 v[56:59], v[144:147], v[178:181], v[56:59]
	v_mfma_f32_16x16x32_bf16 v[52:55], v[136:139], v[194:197], v[52:55]
	v_mfma_f32_16x16x32_bf16 v[48:51], v[144:147], v[194:197], v[48:51]
	v_mfma_f32_16x16x32_bf16 v[44:47], v[136:139], v[202:205], v[44:47]
	v_mfma_f32_16x16x32_bf16 v[40:43], v[144:147], v[202:205], v[40:43]
	v_mfma_f32_16x16x32_bf16 v[36:39], v[136:139], v[210:213], v[36:39]
	v_mfma_f32_16x16x32_bf16 v[32:35], v[144:147], v[210:213], v[32:35]
	v_mfma_f32_16x16x32_bf16 v[28:31], v[148:151], v[174:177], v[28:31]
	v_mfma_f32_16x16x32_bf16 v[24:27], v[156:159], v[174:177], v[24:27]
	v_mfma_f32_16x16x32_bf16 v[20:23], v[148:151], v[184:187], v[20:23]
	v_mfma_f32_16x16x32_bf16 v[16:19], v[156:159], v[184:187], v[16:19]
	v_mfma_f32_16x16x32_bf16 v[12:15], v[148:151], v[198:201], v[12:15]
	v_mfma_f32_16x16x32_bf16 v[8:11], v[156:159], v[198:201], v[8:11]
	v_mfma_f32_16x16x32_bf16 v[4:7], v[148:151], v[206:209], v[4:7]
	v_mfma_f32_16x16x32_bf16 v[0:3], v[156:159], v[206:209], v[0:3]
	v_mfma_f32_16x16x32_bf16 v[28:31], v[152:155], v[178:181], v[28:31]
	v_mfma_f32_16x16x32_bf16 v[24:27], v[162:165], v[178:181], v[24:27]
	v_mfma_f32_16x16x32_bf16 v[20:23], v[152:155], v[194:197], v[20:23]
	v_mfma_f32_16x16x32_bf16 v[16:19], v[162:165], v[194:197], v[16:19]
	v_mfma_f32_16x16x32_bf16 v[12:15], v[152:155], v[202:205], v[12:15]
	v_mfma_f32_16x16x32_bf16 v[8:11], v[162:165], v[202:205], v[8:11]
	v_mfma_f32_16x16x32_bf16 v[4:7], v[152:155], v[210:213], v[4:7]
	v_mfma_f32_16x16x32_bf16 v[0:3], v[162:165], v[210:213], v[0:3]
	s_barrier
	s_setprio 0
	s_add_i32 s42, s42, 2
	s_add_u32 s43, s43, 0x100
	s_addc_u32 s44, s44, 0
	s_add_u32 s45, s45, 0x100
	s_addc_u32 s46, s46, 0
	s_add_u32 s4, s4, 0xffffff00
	s_addc_u32 s5, s5, -1
	v_lshl_add_u64 v[128:129], v[128:129], 0, s[16:17]
	s_cmp_gt_u32 s42, 13
	v_lshl_add_u64 v[130:131], v[130:131], 0, s[16:17]
	s_cbranch_scc0 .LBB0_1381
	s_and_b64 vcc, exec, s[70:71]
	s_cbranch_vccz .LBB0_1384
	s_barrier

.LBB0_1541:
	s_and_b32 s8, s24, 0xffffffc0
	v_or_b32_e32 v0, s8, v56
	s_movk_i32 s36, 0x1600
	v_mad_i64_i32 v[32:33], s[36:37], v0, s36, v[48:49]
	v_add_co_u32_e32 v36, vcc, 0x16000, v32
	s_and_b32 s9, s22, 0x3e0
	s_nop 0
	v_addc_co_u32_e32 v37, vcc, 0, v33, vcc
	v_or_b32_e32 v0, s9, v56
	v_add_co_u32_e32 v38, vcc, 0x2c000, v32
	v_mul_u32_u24_e32 v0, 0xb00, v0
	s_nop 0
	v_addc_co_u32_e32 v39, vcc, 0, v33, vcc
	v_lshlrev_b32_e32 v160, 1, v0
	v_add_co_u32_e32 v44, vcc, 0x42000, v32
	v_lshl_add_u64 v[52:53], v[50:51], 0, v[160:161]
	s_nop 0
	v_addc_co_u32_e32 v45, vcc, 0, v33, vcc
	s_mov_b32 s36, 0x16000
	v_add_co_u32_e32 v54, vcc, s36, v52
	s_waitcnt lgkmcnt(0)
	global_load_dwordx4 v[0:3], v[32:33], off
	global_load_dwordx4 v[4:7], v[36:37], off
	v_addc_co_u32_e32 v55, vcc, 0, v53, vcc
	global_load_dwordx4 v[8:11], v[38:39], off
	global_load_dwordx4 v[12:15], v[44:45], off
	global_load_dwordx4 v[16:19], v[52:53], off
	global_load_dwordx4 v[20:23], v[54:55], off
	s_waitcnt vmcnt(1)
	v_mfma_f32_16x16x32_bf16 v[24:27], v[16:19], v[0:3], 0
	s_waitcnt vmcnt(0)
	v_mfma_f32_16x16x32_bf16 v[0:3], v[20:23], v[0:3], 0
	v_mfma_f32_16x16x32_bf16 v[28:31], v[16:19], v[4:7], 0
	v_mfma_f32_16x16x32_bf16 v[4:7], v[20:23], v[4:7], 0
	v_mfma_f32_16x16x32_bf16 v[40:43], v[16:19], v[8:11], 0
	v_mfma_f32_16x16x32_bf16 v[8:11], v[20:23], v[8:11], 0
	v_mfma_f32_16x16x32_bf16 v[16:19], v[16:19], v[12:15], 0
	v_mfma_f32_16x16x32_bf16 v[12:15], v[20:23], v[12:15], 0
	global_load_dwordx4 v[20:23], v[32:33], off offset:64
	global_load_dwordx4 v[62:65], v[36:37], off offset:64
	global_load_dwordx4 v[66:69], v[38:39], off offset:64
	global_load_dwordx4 v[70:73], v[44:45], off offset:64
	global_load_dwordx4 v[74:77], v[52:53], off offset:64
	global_load_dwordx4 v[78:81], v[54:55], off offset:64
	s_waitcnt vmcnt(1)
	v_mfma_f32_16x16x32_bf16 v[24:27], v[74:77], v[20:23], v[24:27]
	s_waitcnt vmcnt(0)
	v_mfma_f32_16x16x32_bf16 v[0:3], v[78:81], v[20:23], v[0:3]
	v_mfma_f32_16x16x32_bf16 v[20:23], v[74:77], v[62:65], v[28:31]
	v_mfma_f32_16x16x32_bf16 v[4:7], v[78:81], v[62:65], v[4:7]
	v_mfma_f32_16x16x32_bf16 v[28:31], v[74:77], v[66:69], v[40:43]
	v_mfma_f32_16x16x32_bf16 v[8:11], v[78:81], v[66:69], v[8:11]
	v_mfma_f32_16x16x32_bf16 v[16:19], v[74:77], v[70:73], v[16:19]
	v_mfma_f32_16x16x32_bf16 v[12:15], v[78:81], v[70:73], v[12:15]
	global_load_dwordx4 v[40:43], v[32:33], off offset:128
	global_load_dwordx4 v[62:65], v[36:37], off offset:128
	global_load_dwordx4 v[66:69], v[38:39], off offset:128
	global_load_dwordx4 v[70:73], v[44:45], off offset:128
	global_load_dwordx4 v[74:77], v[52:53], off offset:128
	global_load_dwordx4 v[78:81], v[54:55], off offset:128
	global_load_dwordx4 v[148:151], v[32:33], off offset:192
	global_load_dwordx4 v[152:155], v[36:37], off offset:192
	global_load_dwordx4 v[156:159], v[38:39], off offset:192
	global_load_dwordx4 v[162:165], v[44:45], off offset:192
	global_load_dwordx4 v[166:169], v[52:53], off offset:192
	global_load_dwordx4 v[170:173], v[54:55], off offset:192
	global_load_dwordx4 v[174:177], v[32:33], off offset:256
	global_load_dwordx4 v[178:181], v[36:37], off offset:256
	global_load_dwordx4 v[182:185], v[38:39], off offset:256
	global_load_dwordx4 v[88:91], v[44:45], off offset:256
	global_load_dwordx4 v[92:95], v[52:53], off offset:256
	global_load_dwordx4 v[96:99], v[54:55], off offset:256
	s_waitcnt vmcnt(12)
	v_mfma_f32_16x16x32_bf16 v[24:27], v[74:77], v[40:43], v[24:27]
	v_mfma_f32_16x16x32_bf16 v[0:3], v[78:81], v[40:43], v[0:3]
	v_mfma_f32_16x16x32_bf16 v[20:23], v[74:77], v[62:65], v[20:23]
	v_mfma_f32_16x16x32_bf16 v[4:7], v[78:81], v[62:65], v[4:7]
	v_mfma_f32_16x16x32_bf16 v[28:31], v[74:77], v[66:69], v[28:31]
	v_mfma_f32_16x16x32_bf16 v[8:11], v[78:81], v[66:69], v[8:11]
	v_mfma_f32_16x16x32_bf16 v[16:19], v[74:77], v[70:73], v[16:19]
	v_mfma_f32_16x16x32_bf16 v[12:15], v[78:81], v[70:73], v[12:15]
	global_load_dwordx4 v[40:43], v[32:33], off offset:320
	global_load_dwordx4 v[62:65], v[36:37], off offset:320
	global_load_dwordx4 v[66:69], v[38:39], off offset:320
	global_load_dwordx4 v[70:73], v[44:45], off offset:320
	global_load_dwordx4 v[74:77], v[52:53], off offset:320
	global_load_dwordx4 v[78:81], v[54:55], off offset:320
	s_waitcnt vmcnt(12)
	v_mfma_f32_16x16x32_bf16 v[24:27], v[166:169], v[148:151], v[24:27]
	v_mfma_f32_16x16x32_bf16 v[0:3], v[170:173], v[148:151], v[0:3]
	v_mfma_f32_16x16x32_bf16 v[20:23], v[166:169], v[152:155], v[20:23]
	v_mfma_f32_16x16x32_bf16 v[4:7], v[170:173], v[152:155], v[4:7]
	v_mfma_f32_16x16x32_bf16 v[28:31], v[166:169], v[156:159], v[28:31]
	v_mfma_f32_16x16x32_bf16 v[8:11], v[170:173], v[156:159], v[8:11]
	v_mfma_f32_16x16x32_bf16 v[16:19], v[166:169], v[162:165], v[16:19]
	v_mfma_f32_16x16x32_bf16 v[12:15], v[170:173], v[162:165], v[12:15]
	global_load_dwordx4 v[148:151], v[32:33], off offset:384
	global_load_dwordx4 v[152:155], v[36:37], off offset:384
	global_load_dwordx4 v[156:159], v[38:39], off offset:384
	global_load_dwordx4 v[162:165], v[44:45], off offset:384
	global_load_dwordx4 v[166:169], v[52:53], off offset:384
	global_load_dwordx4 v[170:173], v[54:55], off offset:384
	s_waitcnt vmcnt(12)
	v_mfma_f32_16x16x32_bf16 v[24:27], v[92:95], v[174:177], v[24:27]
	v_mfma_f32_16x16x32_bf16 v[0:3], v[96:99], v[174:177], v[0:3]
	v_mfma_f32_16x16x32_bf16 v[20:23], v[92:95], v[178:181], v[20:23]
	v_mfma_f32_16x16x32_bf16 v[4:7], v[96:99], v[178:181], v[4:7]
	v_mfma_f32_16x16x32_bf16 v[28:31], v[92:95], v[182:185], v[28:31]
	v_mfma_f32_16x16x32_bf16 v[8:11], v[96:99], v[182:185], v[8:11]
	v_mfma_f32_16x16x32_bf16 v[16:19], v[92:95], v[88:91], v[16:19]
	v_mfma_f32_16x16x32_bf16 v[12:15], v[96:99], v[88:91], v[12:15]
	global_load_dwordx4 v[174:177], v[32:33], off offset:448
	global_load_dwordx4 v[178:181], v[36:37], off offset:448
	global_load_dwordx4 v[182:185], v[38:39], off offset:448
	global_load_dwordx4 v[88:91], v[44:45], off offset:448
	global_load_dwordx4 v[92:95], v[52:53], off offset:448
	global_load_dwordx4 v[96:99], v[54:55], off offset:448
	s_waitcnt vmcnt(12)
	v_mfma_f32_16x16x32_bf16 v[24:27], v[74:77], v[40:43], v[24:27]
	v_mfma_f32_16x16x32_bf16 v[0:3], v[78:81], v[40:43], v[0:3]
	v_mfma_f32_16x16x32_bf16 v[20:23], v[74:77], v[62:65], v[20:23]
	v_mfma_f32_16x16x32_bf16 v[4:7], v[78:81], v[62:65], v[4:7]
	v_mfma_f32_16x16x32_bf16 v[28:31], v[74:77], v[66:69], v[28:31]
	v_mfma_f32_16x16x32_bf16 v[8:11], v[78:81], v[66:69], v[8:11]
	v_mfma_f32_16x16x32_bf16 v[16:19], v[74:77], v[70:73], v[16:19]
	v_mfma_f32_16x16x32_bf16 v[12:15], v[78:81], v[70:73], v[12:15]
	global_load_dwordx4 v[40:43], v[32:33], off offset:512
	global_load_dwordx4 v[62:65], v[36:37], off offset:512
	global_load_dwordx4 v[66:69], v[38:39], off offset:512
	global_load_dwordx4 v[70:73], v[44:45], off offset:512
	global_load_dwordx4 v[74:77], v[52:53], off offset:512
	global_load_dwordx4 v[78:81], v[54:55], off offset:512
	s_waitcnt vmcnt(12)
	v_mfma_f32_16x16x32_bf16 v[24:27], v[166:169], v[148:151], v[24:27]
	v_mfma_f32_16x16x32_bf16 v[0:3], v[170:173], v[148:151], v[0:3]
	v_mfma_f32_16x16x32_bf16 v[20:23], v[166:169], v[152:155], v[20:23]
	v_mfma_f32_16x16x32_bf16 v[4:7], v[170:173], v[152:155], v[4:7]
	v_mfma_f32_16x16x32_bf16 v[28:31], v[166:169], v[156:159], v[28:31]
	v_mfma_f32_16x16x32_bf16 v[8:11], v[170:173], v[156:159], v[8:11]
	v_mfma_f32_16x16x32_bf16 v[16:19], v[166:169], v[162:165], v[16:19]
	v_mfma_f32_16x16x32_bf16 v[12:15], v[170:173], v[162:165], v[12:15]
	s_waitcnt vmcnt(6)
	v_mfma_f32_16x16x32_bf16 v[24:27], v[92:95], v[174:177], v[24:27]
	v_mfma_f32_16x16x32_bf16 v[0:3], v[96:99], v[174:177], v[0:3]
	v_mfma_f32_16x16x32_bf16 v[20:23], v[92:95], v[178:181], v[20:23]
	v_mfma_f32_16x16x32_bf16 v[4:7], v[96:99], v[178:181], v[4:7]
	v_mfma_f32_16x16x32_bf16 v[28:31], v[92:95], v[182:185], v[28:31]
	v_mfma_f32_16x16x32_bf16 v[8:11], v[96:99], v[182:185], v[8:11]
	v_mfma_f32_16x16x32_bf16 v[16:19], v[92:95], v[88:91], v[16:19]
	v_mfma_f32_16x16x32_bf16 v[12:15], v[96:99], v[88:91], v[12:15]
	s_waitcnt vmcnt(0)
	v_mfma_f32_16x16x32_bf16 v[24:27], v[74:77], v[40:43], v[24:27]
	v_mfma_f32_16x16x32_bf16 v[0:3], v[78:81], v[40:43], v[0:3]
	v_mfma_f32_16x16x32_bf16 v[20:23], v[74:77], v[62:65], v[20:23]
	v_mfma_f32_16x16x32_bf16 v[4:7], v[78:81], v[62:65], v[4:7]
	v_mfma_f32_16x16x32_bf16 v[40:43], v[74:77], v[66:69], v[28:31]
	v_mfma_f32_16x16x32_bf16 v[8:11], v[78:81], v[66:69], v[8:11]
	v_mfma_f32_16x16x32_bf16 v[62:65], v[74:77], v[70:73], v[16:19]
	v_mfma_f32_16x16x32_bf16 v[12:15], v[78:81], v[70:73], v[12:15]
	s_nop 1
	global_load_dwordx4 v[16:19], v[32:33], off offset:576
	global_load_dwordx4 v[66:69], v[36:37], off offset:576
	global_load_dwordx4 v[70:73], v[38:39], off offset:576
	global_load_dwordx4 v[74:77], v[44:45], off offset:576
	global_load_dwordx4 v[78:81], v[52:53], off offset:576
	global_load_dwordx4 v[82:85], v[54:55], off offset:576
	s_waitcnt vmcnt(1)
	v_mfma_f32_16x16x32_bf16 v[28:31], v[78:81], v[16:19], v[24:27]
	s_waitcnt vmcnt(0)
	v_mfma_f32_16x16x32_bf16 v[24:27], v[82:85], v[16:19], v[0:3]
	v_mfma_f32_16x16x32_bf16 v[16:19], v[78:81], v[66:69], v[20:23]
	v_mfma_f32_16x16x32_bf16 v[20:23], v[82:85], v[66:69], v[4:7]
	v_mfma_f32_16x16x32_bf16 v[0:3], v[78:81], v[70:73], v[40:43]
	v_mfma_f32_16x16x32_bf16 v[4:7], v[82:85], v[70:73], v[8:11]
	v_mfma_f32_16x16x32_bf16 v[8:11], v[78:81], v[74:77], v[62:65]
	global_load_dwordx4 v[32:35], v[32:33], off offset:640
	s_nop 0
	global_load_dwordx4 v[40:43], v[36:37], off offset:640
	s_nop 0
	global_load_dwordx4 v[36:39], v[38:39], off offset:640
	s_nop 0
	global_load_dwordx4 v[44:47], v[44:45], off offset:640
	s_nop 0
	global_load_dwordx4 v[62:65], v[52:53], off offset:640
	s_nop 0
	global_load_dwordx4 v[52:55], v[54:55], off offset:640
	v_mfma_f32_16x16x32_bf16 v[12:15], v[82:85], v[74:77], v[12:15]
	s_waitcnt vmcnt(1)
	v_mfma_f32_16x16x32_bf16 v[28:31], v[62:65], v[32:35], v[28:31]
	s_waitcnt vmcnt(0)
	v_mfma_f32_16x16x32_bf16 v[24:27], v[52:55], v[32:35], v[24:27]
	v_add_u32_e32 v32, s19, v57
	v_mfma_f32_16x16x32_bf16 v[16:19], v[62:65], v[40:43], v[16:19]
	v_mfma_f32_16x16x32_bf16 v[20:23], v[52:55], v[40:43], v[20:23]
	v_mfma_f32_16x16x32_bf16 v[0:3], v[62:65], v[36:39], v[0:3]
	v_mfma_f32_16x16x32_bf16 v[4:7], v[52:55], v[36:39], v[4:7]
	v_mfma_f32_16x16x32_bf16 v[8:11], v[62:65], v[44:47], v[8:11]
	v_mfma_f32_16x16x32_bf16 v[12:15], v[52:55], v[44:47], v[12:15]
	ds_write_b128 v32, v[28:31]
	ds_write_b128 v32, v[24:27] offset:1024
	s_nop 0
	ds_write_b128 v32, v[16:19] offset:2048
	ds_write_b128 v32, v[20:23] offset:3072
	ds_write_b128 v32, v[0:3] offset:4096
	ds_write_b128 v32, v[4:7] offset:5120
	ds_write_b128 v32, v[8:11] offset:6144
	ds_write_b128 v32, v[12:15] offset:7168
	s_waitcnt lgkmcnt(0)
	s_barrier
	ds_read_b128 v[0:3], v58
	ds_read_b128 v[4:7], v58 offset:8192
	v_or_b32_e32 v17, s9, v60
	s_waitcnt lgkmcnt(0)
	v_pk_add_f32 v[6:7], v[2:3], v[6:7]
	v_pk_add_f32 v[4:5], v[0:1], v[4:5]
	ds_read_b128 v[0:3], v58 offset:16384
	s_waitcnt lgkmcnt(0)
	v_pk_add_f32 v[6:7], v[6:7], v[2:3]
	v_pk_add_f32 v[4:5], v[4:5], v[0:1]
	ds_read_b128 v[0:3], v58 offset:24576
	s_waitcnt lgkmcnt(0)
	v_pk_add_f32 v[6:7], v[6:7], v[2:3]
	v_pk_add_f32 v[4:5], v[4:5], v[0:1]
	ds_read_b128 v[0:3], v58 offset:32768
	s_waitcnt lgkmcnt(0)
	v_pk_add_f32 v[6:7], v[6:7], v[2:3]
	v_pk_add_f32 v[4:5], v[4:5], v[0:1]
	ds_read_b128 v[0:3], v58 offset:40960
	s_waitcnt lgkmcnt(0)
	v_pk_add_f32 v[6:7], v[6:7], v[2:3]
	v_pk_add_f32 v[4:5], v[4:5], v[0:1]
	ds_read_b128 v[0:3], v58 offset:49152
	s_waitcnt lgkmcnt(0)
	v_pk_add_f32 v[6:7], v[6:7], v[2:3]
	v_pk_add_f32 v[4:5], v[4:5], v[0:1]
	ds_read_b128 v[0:3], v58 offset:57344
	s_waitcnt lgkmcnt(0)
	s_barrier
	v_pk_add_f32 v[12:13], v[4:5], v[0:1]
	v_add_u32_e32 v0, s8, v59
	v_ashrrev_i32_e32 v1, 31, v0
	s_mov_b64 s[8:9], 0x10000
	v_lshl_add_u64 v[18:19], v[0:1], 0, s[8:9]
	v_lshlrev_b64 v[8:9], 3, v[18:19]
	v_lshl_add_u64 v[0:1], s[4:5], 0, v[8:9]
	global_load_dwordx2 v[0:1], v[0:1], off
	v_pk_add_f32 v[10:11], v[6:7], v[2:3]
	v_lshlrev_b64 v[18:19], 11, v[18:19]
	v_lshl_or_b32 v18, v17, 1, v18
	v_lshl_add_u64 v[20:21], s[50:51], 0, v[18:19]
	s_waitcnt vmcnt(0)
	v_pk_mul_f32 v[14:15], v[0:1], s[96:97] op_sel_hi:[1,0]
	s_nop 0
	v_fma_f32 v0, -v14, v14, v15
	v_max_f32_e32 v0, 0, v0
	v_add_f32_e32 v0, 0x3727c5ac, v0
	v_cmp_gt_f32_e32 vcc, s97, v0
	v_mul_f32_e32 v1, 0x4f800000, v0
	s_nop 0
	v_cndmask_b32_e32 v0, v0, v1, vcc
	v_sqrt_f32_e32 v1, v0
	s_nop 0
	v_add_u32_e32 v2, -1, v1
	v_fma_f32 v3, -v2, v1, v0
	v_cmp_ge_f32_e64 s[40:41], 0, v3
	v_add_u32_e32 v3, 1, v1
	s_nop 0
	v_cndmask_b32_e64 v2, v1, v2, s[40:41]
	v_fma_f32 v1, -v3, v1, v0
	v_cmp_lt_f32_e64 s[40:41], 0, v1
	s_nop 1
	v_cndmask_b32_e64 v1, v2, v3, s[40:41]
	v_mul_f32_e32 v2, 0x37800000, v1
	v_cndmask_b32_e32 v1, v1, v2, vcc
	v_cmp_class_f32_e32 vcc, v0, v248
	s_nop 1
	v_cndmask_b32_e32 v0, v1, v0, vcc
	v_div_scale_f32 v1, s[8:9], v0, v0, 1.0
	v_rcp_f32_e32 v2, v1
	s_nop 0
	v_fma_f32 v3, -v1, v2, 1.0
	v_fmac_f32_e32 v2, v3, v2
	v_div_scale_f32 v3, vcc, 1.0, v0, 1.0
	v_mul_f32_e32 v4, v3, v2
	v_fma_f32 v5, -v1, v4, v3
	v_fmac_f32_e32 v4, v5, v2
	v_fma_f32 v1, -v1, v4, v3
	v_div_fmas_f32 v1, v1, v2, v4
	v_div_fixup_f32 v16, v1, v0, 1.0
	v_lshlrev_b32_e32 v0, 2, v17
	global_load_dwordx4 v[4:7], v0, s[52:53]
	s_nop 0
	global_load_dwordx4 v[0:3], v0, s[54:55]
	s_waitcnt vmcnt(1)
	v_pk_mul_f32 v[4:5], v[4:5], v[16:17] op_sel_hi:[1,0]
	global_load_dwordx2 v[20:21], v[20:21], off
	s_waitcnt vmcnt(1)
	v_pk_fma_f32 v[0:1], v[14:15], v[4:5], v[0:1] op_sel_hi:[0,1,1] neg_lo:[1,0,0] neg_hi:[1,0,0]
	v_pk_mul_f32 v[6:7], v[6:7], v[16:17] op_sel_hi:[1,0]
	s_waitcnt vmcnt(0)
	v_lshlrev_b32_e32 v22, 16, v20
	v_and_b32_e32 v23, 0xffff0000, v20
	v_pk_fma_f32 v[0:1], v[22:23], v[4:5], v[0:1]
	v_lshlrev_b32_e32 v4, 16, v21
	v_and_b32_e32 v5, 0xffff0000, v21
	v_pk_fma_f32 v[2:3], v[14:15], v[6:7], v[2:3] op_sel_hi:[0,1,1] neg_lo:[1,0,0] neg_hi:[1,0,0]
	v_pk_fma_f32 v[2:3], v[4:5], v[6:7], v[2:3]
	v_pk_fma_f32 v[0:1], v[0:1], s[12:13], v[12:13] op_sel_hi:[1,0,1]
	v_pk_fma_f32 v[2:3], v[2:3], s[12:13], v[10:11] op_sel_hi:[1,0,1]
	v_cvt_pk_bf16_f32 v0, v0, v1
	v_cvt_pk_bf16_f32 v1, v2, v3
	v_lshl_add_u64 v[2:3], s[56:57], 0, v[18:19]
	global_store_dwordx2 v[2:3], v[0:1], off
	v_lshlrev_b32_e32 v2, 16, v0
	v_and_b32_e32 v0, 0xffff0000, v0
	v_lshlrev_b32_e32 v4, 16, v1
	v_and_b32_e32 v1, 0xffff0000, v1
	v_add_f32_e32 v3, v2, v0
	v_add_f32_e32 v5, v4, v1
	v_mul_f32_e32 v0, v0, v0
	v_mul_f32_e32 v1, v1, v1
	v_fmac_f32_e32 v0, v2, v2
	v_fmac_f32_e32 v1, v4, v4
	v_add_f32_e32 v2, v0, v1
	v_mbcnt_lo_u32_b32 v0, -1, 0
	v_mbcnt_hi_u32_b32 v0, -1, v0
	v_add_f32_e32 v3, v3, v5
	v_lshlrev_b32_e32 v0, 2, v0
	v_xor_b32_e32 v0, 64, v0
	ds_bpermute_b32 v0, v0, v3
	v_mbcnt_lo_u32_b32 v1, -1, 0
	v_mbcnt_hi_u32_b32 v1, -1, v1
	s_waitcnt lgkmcnt(0)
	v_add_f32_e32 v0, v3, v0
	v_mbcnt_lo_u32_b32 v3, -1, 0
	v_mbcnt_hi_u32_b32 v3, -1, v3
	v_lshlrev_b32_e32 v1, 2, v1
	v_lshlrev_b32_e32 v3, 2, v3
	v_xor_b32_e32 v3, 64, v3
	ds_bpermute_b32 v3, v3, v2
	v_xor_b32_e32 v1, 0x80, v1
	ds_bpermute_b32 v1, v1, v0
	s_waitcnt lgkmcnt(1)
	v_add_f32_e32 v2, v2, v3
	v_mbcnt_lo_u32_b32 v3, -1, 0
	v_mbcnt_hi_u32_b32 v3, -1, v3
	s_nop 0
	v_lshlrev_b32_e32 v3, 2, v3
	v_xor_b32_e32 v3, 0x80, v3
	ds_bpermute_b32 v3, v3, v2
	s_and_saveexec_b64 s[8:9], s[38:39]
	s_cbranch_execz .LBB0_1540
	s_waitcnt lgkmcnt(0)
	v_add_f32_e32 v2, v2, v3
	v_add_f32_e32 v3, v0, v1
	v_lshl_add_u64 v[0:1], s[58:59], 0, v[8:9]
	global_atomic_add_f32 v[0:1], v3, off
	global_atomic_add_f32 v[0:1], v2, off offset:4
	s_branch .LBB0_1540

.LBB0_1567:
.LBB0_1568:
	s_add_i32 s19, 0, 0x10000
	s_add_i32 s36, 0, 0x14000
	v_add_u32_e32 v12, s19, v174
	v_add_u32_e32 v28, s36, v174
	ds_read_b128 v[0:3], v12
	ds_read_b128 v[4:7], v12 offset:1024
	ds_read_b128 v[8:11], v12 offset:2048
	ds_read_b128 v[12:15], v12 offset:3072
	ds_read_b128 v[16:19], v28
	ds_read_b128 v[20:23], v28 offset:1024
	ds_read_b128 v[24:27], v28 offset:2048
	ds_read_b128 v[28:31], v28 offset:3072
	s_add_u32 s24, s22, 0xb0080
	s_addc_u32 s25, s23, 0
	s_waitcnt vmcnt(0)
	v_lshl_add_u64 v[64:65], s[24:25], 0, v[128:129]
	s_add_i32 m0, s73, 0xc000
	ds_read_b128 v[32:35], v175
	ds_read_b128 v[36:39], v175 offset:1024
	ds_read_b128 v[40:43], v175 offset:2048
	ds_read_b128 v[44:47], v175 offset:3072
	ds_read_b128 v[48:51], v175 offset:4096
	ds_read_b128 v[52:55], v175 offset:5120
	ds_read_b128 v[56:59], v175 offset:6144
	ds_read_b128 v[60:63], v175 offset:7168
	global_load_lds_dwordx4 v[64:65], off
	v_lshl_add_u64 v[64:65], s[24:25], 0, v[132:133]
	s_add_i32 m0, s73, 0xe000
	s_nop 0
	global_load_lds_dwordx4 v[64:65], off
	s_waitcnt vmcnt(40) lgkmcnt(0)
	s_setprio 1
	s_barrier
	v_mfma_f32_16x16x32_bf16 v[64:67], v[0:3], v[32:35], 0
	v_mfma_f32_16x16x32_bf16 v[68:71], v[8:11], v[32:35], 0
	v_mfma_f32_16x16x32_bf16 v[72:75], v[0:3], v[40:43], 0
	v_mfma_f32_16x16x32_bf16 v[76:79], v[8:11], v[40:43], 0
	v_mfma_f32_16x16x32_bf16 v[80:83], v[0:3], v[48:51], 0
	v_mfma_f32_16x16x32_bf16 v[84:87], v[8:11], v[48:51], 0
	v_mfma_f32_16x16x32_bf16 v[88:91], v[0:3], v[56:59], 0
	v_mfma_f32_16x16x32_bf16 v[92:95], v[8:11], v[56:59], 0
	v_mfma_f32_16x16x32_bf16 v[64:67], v[4:7], v[36:39], v[64:67]
	v_mfma_f32_16x16x32_bf16 v[68:71], v[12:15], v[36:39], v[68:71]
	v_mfma_f32_16x16x32_bf16 v[72:75], v[4:7], v[44:47], v[72:75]
	v_mfma_f32_16x16x32_bf16 v[76:79], v[12:15], v[44:47], v[76:79]
	v_mfma_f32_16x16x32_bf16 v[80:83], v[4:7], v[52:55], v[80:83]
	v_mfma_f32_16x16x32_bf16 v[84:87], v[12:15], v[52:55], v[84:87]
	v_mfma_f32_16x16x32_bf16 v[88:91], v[4:7], v[60:63], v[88:91]
	v_mfma_f32_16x16x32_bf16 v[92:95], v[12:15], v[60:63], v[92:95]
	v_mfma_f32_16x16x32_bf16 v[96:99], v[16:19], v[32:35], 0
	v_mfma_f32_16x16x32_bf16 v[32:35], v[24:27], v[32:35], 0
	v_mfma_f32_16x16x32_bf16 v[96:99], v[20:23], v[36:39], v[96:99]
	v_mfma_f32_16x16x32_bf16 v[32:35], v[28:31], v[36:39], v[32:35]
	v_mfma_f32_16x16x32_bf16 v[36:39], v[16:19], v[40:43], 0
	v_mfma_f32_16x16x32_bf16 v[40:43], v[24:27], v[40:43], 0
	v_mfma_f32_16x16x32_bf16 v[36:39], v[20:23], v[44:47], v[36:39]
	v_mfma_f32_16x16x32_bf16 v[40:43], v[28:31], v[44:47], v[40:43]
	v_mfma_f32_16x16x32_bf16 v[44:47], v[16:19], v[48:51], 0
	v_mfma_f32_16x16x32_bf16 v[48:51], v[24:27], v[48:51], 0
	v_mfma_f32_16x16x32_bf16 v[44:47], v[20:23], v[52:55], v[44:47]
	v_mfma_f32_16x16x32_bf16 v[48:51], v[28:31], v[52:55], v[48:51]
	v_mfma_f32_16x16x32_bf16 v[52:55], v[16:19], v[56:59], 0
	v_mfma_f32_16x16x32_bf16 v[52:55], v[20:23], v[60:63], v[52:55]
	v_mfma_f32_16x16x32_bf16 v[56:59], v[24:27], v[56:59], 0
	v_mfma_f32_16x16x32_bf16 v[134:137], v[28:31], v[60:63], v[56:59]
	s_barrier
	s_setprio 0
	v_lshl_add_u64 v[158:159], s[8:9], 0, v[130:131]
	s_add_i32 s19, s19, s72
	v_lshl_add_u64 v[124:125], v[158:159], 0, s[16:17]
	s_mov_b32 m0, s19
	s_nop 0
	ds_read_b128 v[56:59], v175 offset:16384
	ds_read_b128 v[60:63], v175 offset:17408
	ds_read_b128 v[100:103], v175 offset:18432
	ds_read_b128 v[104:107], v175 offset:19456
	ds_read_b128 v[108:111], v175 offset:20480
	ds_read_b128 v[112:115], v175 offset:21504
	ds_read_b128 v[116:119], v175 offset:22528
	ds_read_b128 v[120:123], v175 offset:23552
	global_load_lds_dwordx4 v[124:125], off
	s_add_i32 m0, s19, 0x2000
	v_lshl_add_u64 v[188:189], s[8:9], 0, v[160:161]
	s_add_u32 s24, s8, 0xb0100
	v_lshl_add_u64 v[124:125], v[188:189], 0, s[16:17]
	s_addc_u32 s25, s9, 0
	s_add_i32 s19, s36, s72
	global_load_lds_dwordx4 v[124:125], off
	v_lshl_add_u64 v[124:125], s[24:25], 0, v[130:131]
	s_mov_b32 m0, s19
	v_lshl_add_u64 v[190:191], s[22:23], 0, v[128:129]
	global_load_lds_dwordx4 v[124:125], off
	v_lshl_add_u64 v[124:125], s[24:25], 0, v[160:161]
	s_add_i32 m0, s19, 0x2000
	v_lshl_add_u64 v[246:247], s[22:23], 0, v[132:133]
	global_load_lds_dwordx4 v[124:125], off
	v_lshl_add_u64 v[124:125], v[190:191], 0, s[16:17]
	s_mov_b32 m0, s73
	s_nop 0
	global_load_lds_dwordx4 v[124:125], off
	v_lshl_add_u64 v[124:125], v[246:247], 0, s[16:17]
	s_mov_b32 m0, s74
	s_nop 0
	global_load_lds_dwordx4 v[124:125], off
	s_waitcnt vmcnt(40) lgkmcnt(0)
	s_setprio 1
	s_barrier
	v_mfma_f32_16x16x32_bf16 v[124:127], v[0:3], v[56:59], 0
	v_mfma_f32_16x16x32_bf16 v[138:141], v[4:7], v[60:63], v[124:127]
	v_mfma_f32_16x16x32_bf16 v[124:127], v[8:11], v[56:59], 0
	v_mfma_f32_16x16x32_bf16 v[142:145], v[12:15], v[60:63], v[124:127]
	v_mfma_f32_16x16x32_bf16 v[124:127], v[0:3], v[100:103], 0
	v_mfma_f32_16x16x32_bf16 v[146:149], v[4:7], v[104:107], v[124:127]
	v_mfma_f32_16x16x32_bf16 v[124:127], v[8:11], v[100:103], 0
	v_mfma_f32_16x16x32_bf16 v[150:153], v[12:15], v[104:107], v[124:127]
	v_mfma_f32_16x16x32_bf16 v[124:127], v[0:3], v[108:111], 0
	v_mfma_f32_16x16x32_bf16 v[0:3], v[0:3], v[116:119], 0
	v_mfma_f32_16x16x32_bf16 v[154:157], v[4:7], v[112:115], v[124:127]
	v_mfma_f32_16x16x32_bf16 v[0:3], v[4:7], v[120:123], v[0:3]
	v_mfma_f32_16x16x32_bf16 v[4:7], v[8:11], v[116:119], 0
	v_mfma_f32_16x16x32_bf16 v[124:127], v[8:11], v[108:111], 0
	v_mfma_f32_16x16x32_bf16 v[4:7], v[12:15], v[120:123], v[4:7]
	v_mfma_f32_16x16x32_bf16 v[162:165], v[12:15], v[112:115], v[124:127]
	v_mfma_f32_16x16x32_bf16 v[8:11], v[16:19], v[56:59], 0
	v_mfma_f32_16x16x32_bf16 v[166:169], v[20:23], v[60:63], v[8:11]
	v_mfma_f32_16x16x32_bf16 v[8:11], v[24:27], v[56:59], 0
	v_mfma_f32_16x16x32_bf16 v[170:173], v[28:31], v[60:63], v[8:11]
	v_mfma_f32_16x16x32_bf16 v[8:11], v[16:19], v[100:103], 0
	v_mfma_f32_16x16x32_bf16 v[176:179], v[20:23], v[104:107], v[8:11]
	v_mfma_f32_16x16x32_bf16 v[8:11], v[24:27], v[100:103], 0
	v_mfma_f32_16x16x32_bf16 v[180:183], v[28:31], v[104:107], v[8:11]
	v_mfma_f32_16x16x32_bf16 v[8:11], v[16:19], v[108:111], 0
	v_mfma_f32_16x16x32_bf16 v[184:187], v[20:23], v[112:115], v[8:11]
	v_mfma_f32_16x16x32_bf16 v[8:11], v[24:27], v[108:111], 0
	v_mfma_f32_16x16x32_bf16 v[194:197], v[28:31], v[112:115], v[8:11]
	v_mfma_f32_16x16x32_bf16 v[8:11], v[16:19], v[116:119], 0
	v_mfma_f32_16x16x32_bf16 v[198:201], v[20:23], v[120:123], v[8:11]
	v_mfma_f32_16x16x32_bf16 v[8:11], v[24:27], v[116:119], 0
	v_mfma_f32_16x16x32_bf16 v[202:205], v[28:31], v[120:123], v[8:11]
	s_barrier
	s_setprio 0
	s_add_i32 s19, 0, 0x18000
	v_add_u32_e32 v16, s19, v174
	s_add_i32 s36, 0, 0x1c000
	s_nop 1
	ds_read_b128 v[8:11], v16
	ds_read_b128 v[12:15], v16 offset:1024
	ds_read_b128 v[28:31], v16 offset:2048
	ds_read_b128 v[206:209], v16 offset:3072
	v_add_u32_e32 v16, s36, v174
	ds_read_b128 v[210:213], v16
	ds_read_b128 v[214:217], v16 offset:1024
	ds_read_b128 v[218:221], v16 offset:2048
	ds_read_b128 v[222:225], v16 offset:3072
	s_add_u32 s24, s22, 0xb0100
	s_addc_u32 s25, s23, 0
	s_mov_b32 m0, s75
	v_lshl_add_u64 v[100:101], s[24:25], 0, v[128:129]
	ds_read_b128 v[16:19], v175 offset:32768
	ds_read_b128 v[20:23], v175 offset:33792
	ds_read_b128 v[24:27], v175 offset:34816
	ds_read_b128 v[56:59], v175 offset:35840
	ds_read_b128 v[60:63], v175 offset:36864
	ds_read_b128 v[226:229], v175 offset:37888
	ds_read_b128 v[230:233], v175 offset:38912
	ds_read_b128 v[234:237], v175 offset:39936
	global_load_lds_dwordx4 v[100:101], off
	v_lshl_add_u64 v[100:101], s[24:25], 0, v[132:133]
	s_mov_b32 m0, s76
	s_nop 0
	global_load_lds_dwordx4 v[100:101], off
	s_waitcnt vmcnt(8) lgkmcnt(0)
	s_setprio 1
	s_barrier
	v_mfma_f32_16x16x32_bf16 v[64:67], v[8:11], v[16:19], v[64:67]
	v_mfma_f32_16x16x32_bf16 v[124:127], v[12:15], v[20:23], v[64:67]
	v_mfma_f32_16x16x32_bf16 v[64:67], v[28:31], v[16:19], v[68:71]
	v_mfma_f32_16x16x32_bf16 v[120:123], v[206:209], v[20:23], v[64:67]
	v_mfma_f32_16x16x32_bf16 v[64:67], v[8:11], v[24:27], v[72:75]
	v_mfma_f32_16x16x32_bf16 v[116:119], v[12:15], v[56:59], v[64:67]
	v_mfma_f32_16x16x32_bf16 v[64:67], v[28:31], v[24:27], v[76:79]
	v_mfma_f32_16x16x32_bf16 v[112:115], v[206:209], v[56:59], v[64:67]
	v_mfma_f32_16x16x32_bf16 v[64:67], v[8:11], v[60:63], v[80:83]
	v_mfma_f32_16x16x32_bf16 v[108:111], v[12:15], v[226:229], v[64:67]
	v_mfma_f32_16x16x32_bf16 v[64:67], v[28:31], v[60:63], v[84:87]
	v_mfma_f32_16x16x32_bf16 v[104:107], v[206:209], v[226:229], v[64:67]
	v_mfma_f32_16x16x32_bf16 v[64:67], v[8:11], v[230:233], v[88:91]
	v_mfma_f32_16x16x32_bf16 v[100:103], v[12:15], v[234:237], v[64:67]
	v_mfma_f32_16x16x32_bf16 v[64:67], v[28:31], v[230:233], v[92:95]
	v_mfma_f32_16x16x32_bf16 v[92:95], v[206:209], v[234:237], v[64:67]
	v_mfma_f32_16x16x32_bf16 v[64:67], v[210:213], v[16:19], v[96:99]
	v_mfma_f32_16x16x32_bf16 v[16:19], v[218:221], v[16:19], v[32:35]
	v_mfma_f32_16x16x32_bf16 v[76:79], v[222:225], v[20:23], v[16:19]
	v_mfma_f32_16x16x32_bf16 v[16:19], v[210:213], v[24:27], v[36:39]
	v_mfma_f32_16x16x32_bf16 v[72:75], v[214:217], v[56:59], v[16:19]
	v_mfma_f32_16x16x32_bf16 v[16:19], v[218:221], v[24:27], v[40:43]
	v_mfma_f32_16x16x32_bf16 v[68:71], v[222:225], v[56:59], v[16:19]
	v_mfma_f32_16x16x32_bf16 v[16:19], v[210:213], v[60:63], v[44:47]
	v_mfma_f32_16x16x32_bf16 v[80:83], v[214:217], v[20:23], v[64:67]
	v_mfma_f32_16x16x32_bf16 v[64:67], v[214:217], v[226:229], v[16:19]
	v_mfma_f32_16x16x32_bf16 v[16:19], v[218:221], v[60:63], v[48:51]
	v_mfma_f32_16x16x32_bf16 v[60:63], v[222:225], v[226:229], v[16:19]
	v_mfma_f32_16x16x32_bf16 v[16:19], v[210:213], v[230:233], v[52:55]
	v_mfma_f32_16x16x32_bf16 v[56:59], v[214:217], v[234:237], v[16:19]
	v_mfma_f32_16x16x32_bf16 v[16:19], v[218:221], v[230:233], v[134:137]
	v_mfma_f32_16x16x32_bf16 v[48:51], v[222:225], v[234:237], v[16:19]
	s_barrier
	s_setprio 0
	s_mov_b64 s[80:81], 0x180
	s_add_i32 s19, s19, s72
	s_nop 2
	v_lshl_add_u64 v[16:17], v[158:159], 0, s[80:81]
	s_mov_b32 m0, s19
	ds_read_b128 v[32:35], v175 offset:49152
	ds_read_b128 v[36:39], v175 offset:50176
	ds_read_b128 v[134:137], v175 offset:51200
	ds_read_b128 v[226:229], v175 offset:52224
	ds_read_b128 v[230:233], v175 offset:53248
	ds_read_b128 v[234:237], v175 offset:54272
	ds_read_b128 v[238:241], v175 offset:55296
	ds_read_b128 v[242:245], v175 offset:56320
	global_load_lds_dwordx4 v[16:17], off
	s_add_i32 m0, s19, 0x2000
	s_add_u32 s24, s8, 0xb0180
	v_lshl_add_u64 v[16:17], v[188:189], 0, s[80:81]
	s_addc_u32 s25, s9, 0
	s_add_i32 s19, s36, s72
	global_load_lds_dwordx4 v[16:17], off
	v_lshl_add_u64 v[16:17], s[24:25], 0, v[130:131]
	s_mov_b32 m0, s19
	s_nop 0
	global_load_lds_dwordx4 v[16:17], off
	v_lshl_add_u64 v[16:17], s[24:25], 0, v[160:161]
	s_add_i32 m0, s19, 0x2000
	s_nop 0
	global_load_lds_dwordx4 v[16:17], off
	v_lshl_add_u64 v[16:17], v[190:191], 0, s[80:81]
	s_mov_b32 m0, s78
	s_nop 0
	global_load_lds_dwordx4 v[16:17], off
	v_lshl_add_u64 v[16:17], v[246:247], 0, s[80:81]
	s_mov_b32 m0, s79
	v_mov_b32_e32 v247, 0x77
	global_load_lds_dwordx4 v[16:17], off
	s_waitcnt vmcnt(8)
	s_waitcnt lgkmcnt(0)
	v_mov_b32_e32 v246, 0x7c
	s_barrier
	s_setprio 1
	s_waitcnt lgkmcnt(0)
	v_mfma_f32_16x16x32_bf16 v[16:19], v[8:11], v[32:35], v[138:141]
	v_mfma_f32_16x16x32_bf16 v[96:99], v[12:15], v[36:39], v[16:19]
	v_mfma_f32_16x16x32_bf16 v[16:19], v[28:31], v[32:35], v[142:145]
	v_mfma_f32_16x16x32_bf16 v[88:91], v[206:209], v[36:39], v[16:19]
	v_mfma_f32_16x16x32_bf16 v[16:19], v[8:11], v[134:137], v[146:149]
	v_mfma_f32_16x16x32_bf16 v[84:87], v[12:15], v[226:229], v[16:19]
	v_mfma_f32_16x16x32_bf16 v[16:19], v[28:31], v[134:137], v[150:153]
	v_mfma_f32_16x16x32_bf16 v[24:27], v[206:209], v[226:229], v[16:19]
	v_mfma_f32_16x16x32_bf16 v[16:19], v[8:11], v[230:233], v[154:157]
	v_mfma_f32_16x16x32_bf16 v[0:3], v[8:11], v[238:241], v[0:3]
	v_mfma_f32_16x16x32_bf16 v[20:23], v[12:15], v[234:237], v[16:19]
	v_mfma_f32_16x16x32_bf16 v[16:19], v[28:31], v[230:233], v[162:165]
	v_mfma_f32_16x16x32_bf16 v[12:15], v[12:15], v[242:245], v[0:3]
	v_mfma_f32_16x16x32_bf16 v[0:3], v[28:31], v[238:241], v[4:7]
	v_mfma_f32_16x16x32_bf16 v[16:19], v[206:209], v[234:237], v[16:19]
	v_mfma_f32_16x16x32_bf16 v[8:11], v[206:209], v[242:245], v[0:3]
	v_mfma_f32_16x16x32_bf16 v[0:3], v[210:213], v[32:35], v[166:169]
	v_mfma_f32_16x16x32_bf16 v[52:55], v[214:217], v[36:39], v[0:3]
	v_mfma_f32_16x16x32_bf16 v[0:3], v[218:221], v[32:35], v[170:173]
	v_mfma_f32_16x16x32_bf16 v[44:47], v[222:225], v[36:39], v[0:3]
	v_mfma_f32_16x16x32_bf16 v[0:3], v[210:213], v[134:137], v[176:179]
	v_mfma_f32_16x16x32_bf16 v[40:43], v[214:217], v[226:229], v[0:3]
	v_mfma_f32_16x16x32_bf16 v[0:3], v[218:221], v[134:137], v[180:183]
	v_mfma_f32_16x16x32_bf16 v[36:39], v[222:225], v[226:229], v[0:3]
	v_mfma_f32_16x16x32_bf16 v[0:3], v[210:213], v[230:233], v[184:187]
	v_mfma_f32_16x16x32_bf16 v[32:35], v[214:217], v[234:237], v[0:3]
	v_mfma_f32_16x16x32_bf16 v[0:3], v[218:221], v[230:233], v[194:197]
	v_mfma_f32_16x16x32_bf16 v[28:31], v[222:225], v[234:237], v[0:3]
	v_mfma_f32_16x16x32_bf16 v[0:3], v[210:213], v[238:241], v[198:201]
	v_mfma_f32_16x16x32_bf16 v[4:7], v[214:217], v[242:245], v[0:3]
	v_mfma_f32_16x16x32_bf16 v[0:3], v[218:221], v[238:241], v[202:205]
	v_mov_b32_e32 v241, 0x7f
	v_mfma_f32_16x16x32_bf16 v[0:3], v[222:225], v[242:245], v[0:3]
	v_mov_b32_e32 v245, 0x7d
	v_mov_b32_e32 v244, 0x7e
	v_mov_b64_e32 v[242:243], 0x400
	s_setprio 0
	s_barrier
	s_mov_b32 s24, 2

.LBB0_1570:
	s_add_u32 s22, s36, s92
	s_addc_u32 s23, s37, 0
	s_add_u32 s80, s67, s92
	s_addc_u32 s87, s81, 0
	s_add_i32 s88, 0, 0x10000
	s_cmp_eq_u32 s92, s8
	s_cselect_b32 s25, s41, s23
	s_cselect_b32 s24, s40, s22
	s_cselect_b32 s23, s69, s87
	s_cselect_b32 s22, s68, s80
	s_add_i32 s80, 0, 0x14000
	v_add_u32_e32 v150, s88, v174
	v_add_u32_e32 v158, s80, v174
	ds_read_b128 v[138:141], v150
	ds_read_b128 v[142:145], v150 offset:1024
	ds_read_b128 v[146:149], v150 offset:2048
	ds_read_b128 v[150:153], v150 offset:3072
	ds_read_b128 v[154:157], v158
	ds_read_b128 v[162:165], v158 offset:1024
	ds_read_b128 v[166:169], v158 offset:2048
	ds_read_b128 v[170:173], v158 offset:3072
	v_lshl_add_u64 v[158:159], v[134:135], 0, s[92:93]
	s_add_i32 m0, s73, 0xc000
	ds_read_b128 v[176:179], v175
	ds_read_b128 v[180:183], v175 offset:1024
	ds_read_b128 v[184:187], v175 offset:2048
	ds_read_b128 v[194:197], v175 offset:3072
	ds_read_b128 v[198:201], v175 offset:4096
	ds_read_b128 v[202:205], v175 offset:5120
	ds_read_b128 v[206:209], v175 offset:6144
	ds_read_b128 v[210:213], v175 offset:7168
	global_load_lds_dwordx4 v[158:159], off
	v_lshl_add_u64 v[158:159], v[136:137], 0, s[92:93]
	s_add_i32 m0, s73, 0xe000
	s_nop 0
	global_load_lds_dwordx4 v[158:159], off
	s_waitcnt vmcnt(8) lgkmcnt(0)
	s_setprio 1
	s_barrier
	v_mfma_f32_16x16x32_bf16 v[124:127], v[138:141], v[176:179], v[124:127]
	v_mfma_f32_16x16x32_bf16 v[120:123], v[146:149], v[176:179], v[120:123]
	v_mfma_f32_16x16x32_bf16 v[116:119], v[138:141], v[184:187], v[116:119]
	v_mfma_f32_16x16x32_bf16 v[112:115], v[146:149], v[184:187], v[112:115]
	v_mfma_f32_16x16x32_bf16 v[108:111], v[138:141], v[198:201], v[108:111]
	v_mfma_f32_16x16x32_bf16 v[104:107], v[146:149], v[198:201], v[104:107]
	v_mfma_f32_16x16x32_bf16 v[100:103], v[138:141], v[206:209], v[100:103]
	v_mfma_f32_16x16x32_bf16 v[92:95], v[146:149], v[206:209], v[92:95]
	v_mfma_f32_16x16x32_bf16 v[124:127], v[142:145], v[180:183], v[124:127]
	v_mfma_f32_16x16x32_bf16 v[120:123], v[150:153], v[180:183], v[120:123]
	v_mfma_f32_16x16x32_bf16 v[116:119], v[142:145], v[194:197], v[116:119]
	v_mfma_f32_16x16x32_bf16 v[112:115], v[150:153], v[194:197], v[112:115]
	v_mfma_f32_16x16x32_bf16 v[108:111], v[142:145], v[202:205], v[108:111]
	v_mfma_f32_16x16x32_bf16 v[104:107], v[150:153], v[202:205], v[104:107]
	v_mfma_f32_16x16x32_bf16 v[100:103], v[142:145], v[210:213], v[100:103]
	v_mfma_f32_16x16x32_bf16 v[92:95], v[150:153], v[210:213], v[92:95]
	v_mfma_f32_16x16x32_bf16 v[80:83], v[154:157], v[176:179], v[80:83]
	v_mfma_f32_16x16x32_bf16 v[76:79], v[166:169], v[176:179], v[76:79]
	v_mfma_f32_16x16x32_bf16 v[72:75], v[154:157], v[184:187], v[72:75]
	v_mfma_f32_16x16x32_bf16 v[68:71], v[166:169], v[184:187], v[68:71]
	v_mfma_f32_16x16x32_bf16 v[64:67], v[154:157], v[198:201], v[64:67]
	v_mfma_f32_16x16x32_bf16 v[60:63], v[166:169], v[198:201], v[60:63]
	v_mfma_f32_16x16x32_bf16 v[56:59], v[154:157], v[206:209], v[56:59]
	v_mfma_f32_16x16x32_bf16 v[48:51], v[166:169], v[206:209], v[48:51]
	v_mfma_f32_16x16x32_bf16 v[80:83], v[162:165], v[180:183], v[80:83]
	v_mfma_f32_16x16x32_bf16 v[76:79], v[170:173], v[180:183], v[76:79]
	v_mfma_f32_16x16x32_bf16 v[72:75], v[162:165], v[194:197], v[72:75]
	v_mfma_f32_16x16x32_bf16 v[68:71], v[170:173], v[194:197], v[68:71]
	v_mfma_f32_16x16x32_bf16 v[64:67], v[162:165], v[202:205], v[64:67]
	v_mfma_f32_16x16x32_bf16 v[60:63], v[170:173], v[202:205], v[60:63]
	v_mfma_f32_16x16x32_bf16 v[56:59], v[162:165], v[210:213], v[56:59]
	v_mfma_f32_16x16x32_bf16 v[48:51], v[170:173], v[210:213], v[48:51]
	s_barrier
	s_setprio 0
	s_add_i32 s87, s88, s72
	v_lshl_add_u64 v[158:159], s[22:23], 0, v[130:131]
	s_mov_b32 m0, s87
	ds_read_b128 v[176:179], v175 offset:16384
	ds_read_b128 v[180:183], v175 offset:17408
	ds_read_b128 v[184:187], v175 offset:18432
	ds_read_b128 v[194:197], v175 offset:19456
	ds_read_b128 v[198:201], v175 offset:20480
	ds_read_b128 v[202:205], v175 offset:21504
	ds_read_b128 v[206:209], v175 offset:22528
	ds_read_b128 v[210:213], v175 offset:23552
	global_load_lds_dwordx4 v[158:159], off
	s_add_i32 m0, s87, 0x2000
	s_add_u32 s88, s22, 0xb0000
	v_lshl_add_u64 v[188:189], s[22:23], 0, v[160:161]
	s_addc_u32 s89, s23, 0
	s_add_i32 s80, s80, s72
	global_load_lds_dwordx4 v[188:189], off
	v_lshl_add_u64 v[190:191], s[88:89], 0, v[130:131]
	s_mov_b32 m0, s80
	v_lshl_add_u64 v[214:215], s[24:25], 0, v[132:133]
	global_load_lds_dwordx4 v[190:191], off
	v_lshl_add_u64 v[190:191], s[88:89], 0, v[160:161]
	s_add_i32 m0, s80, 0x2000
	s_nop 0
	global_load_lds_dwordx4 v[190:191], off
	v_lshl_add_u64 v[190:191], s[24:25], 0, v[128:129]
	s_mov_b32 m0, s73
	s_nop 0
	global_load_lds_dwordx4 v[190:191], off
	s_mov_b32 m0, s74
	s_nop 0
	global_load_lds_dwordx4 v[214:215], off
	s_waitcnt vmcnt(8) lgkmcnt(0)
	s_setprio 1
	s_barrier
	v_mfma_f32_16x16x32_bf16 v[96:99], v[138:141], v[176:179], v[96:99]
	v_mfma_f32_16x16x32_bf16 v[88:91], v[146:149], v[176:179], v[88:91]
	v_mfma_f32_16x16x32_bf16 v[84:87], v[138:141], v[184:187], v[84:87]
	v_mfma_f32_16x16x32_bf16 v[24:27], v[146:149], v[184:187], v[24:27]
	v_mfma_f32_16x16x32_bf16 v[20:23], v[138:141], v[198:201], v[20:23]
	v_mfma_f32_16x16x32_bf16 v[16:19], v[146:149], v[198:201], v[16:19]
	v_mfma_f32_16x16x32_bf16 v[12:15], v[138:141], v[206:209], v[12:15]
	v_mfma_f32_16x16x32_bf16 v[8:11], v[146:149], v[206:209], v[8:11]
	v_mfma_f32_16x16x32_bf16 v[96:99], v[142:145], v[180:183], v[96:99]
	v_mfma_f32_16x16x32_bf16 v[88:91], v[150:153], v[180:183], v[88:91]
	v_mfma_f32_16x16x32_bf16 v[84:87], v[142:145], v[194:197], v[84:87]
	v_mfma_f32_16x16x32_bf16 v[24:27], v[150:153], v[194:197], v[24:27]
	v_mfma_f32_16x16x32_bf16 v[20:23], v[142:145], v[202:205], v[20:23]
	v_mfma_f32_16x16x32_bf16 v[16:19], v[150:153], v[202:205], v[16:19]
	v_mfma_f32_16x16x32_bf16 v[12:15], v[142:145], v[210:213], v[12:15]
	v_mfma_f32_16x16x32_bf16 v[8:11], v[150:153], v[210:213], v[8:11]
	v_mfma_f32_16x16x32_bf16 v[52:55], v[154:157], v[176:179], v[52:55]
	v_mfma_f32_16x16x32_bf16 v[44:47], v[166:169], v[176:179], v[44:47]
	v_mfma_f32_16x16x32_bf16 v[40:43], v[154:157], v[184:187], v[40:43]
	v_mfma_f32_16x16x32_bf16 v[36:39], v[166:169], v[184:187], v[36:39]
	v_mfma_f32_16x16x32_bf16 v[32:35], v[154:157], v[198:201], v[32:35]
	v_mfma_f32_16x16x32_bf16 v[28:31], v[166:169], v[198:201], v[28:31]
	v_mfma_f32_16x16x32_bf16 v[4:7], v[154:157], v[206:209], v[4:7]
	v_mfma_f32_16x16x32_bf16 v[0:3], v[166:169], v[206:209], v[0:3]
	v_mfma_f32_16x16x32_bf16 v[52:55], v[162:165], v[180:183], v[52:55]
	v_mfma_f32_16x16x32_bf16 v[44:47], v[170:173], v[180:183], v[44:47]
	v_mfma_f32_16x16x32_bf16 v[40:43], v[162:165], v[194:197], v[40:43]
	v_mfma_f32_16x16x32_bf16 v[36:39], v[170:173], v[194:197], v[36:39]
	v_mfma_f32_16x16x32_bf16 v[32:35], v[162:165], v[202:205], v[32:35]
	v_mfma_f32_16x16x32_bf16 v[28:31], v[170:173], v[202:205], v[28:31]
	v_mfma_f32_16x16x32_bf16 v[4:7], v[162:165], v[210:213], v[4:7]
	v_mfma_f32_16x16x32_bf16 v[0:3], v[170:173], v[210:213], v[0:3]
	s_barrier
	s_setprio 0
	s_add_i32 s80, 0, 0x18000
	s_add_i32 s87, 0, 0x1c000
	v_add_u32_e32 v150, s80, v174
	v_add_u32_e32 v170, s87, v174
	ds_read_b128 v[138:141], v150
	ds_read_b128 v[142:145], v150 offset:1024
	ds_read_b128 v[146:149], v150 offset:2048
	ds_read_b128 v[150:153], v150 offset:3072
	ds_read_b128 v[154:157], v170
	ds_read_b128 v[162:165], v170 offset:1024
	ds_read_b128 v[166:169], v170 offset:2048
	ds_read_b128 v[170:173], v170 offset:3072
	s_add_u32 s24, s24, 0xb0000
	s_addc_u32 s25, s25, 0
	s_mov_b32 m0, s75
	v_lshl_add_u64 v[216:217], s[24:25], 0, v[128:129]
	ds_read_b128 v[176:179], v175 offset:32768
	ds_read_b128 v[180:183], v175 offset:33792
	ds_read_b128 v[184:187], v175 offset:34816
	ds_read_b128 v[194:197], v175 offset:35840
	ds_read_b128 v[198:201], v175 offset:36864
	ds_read_b128 v[202:205], v175 offset:37888
	ds_read_b128 v[206:209], v175 offset:38912
	ds_read_b128 v[210:213], v175 offset:39936
	global_load_lds_dwordx4 v[216:217], off
	v_lshl_add_u64 v[216:217], s[24:25], 0, v[132:133]
	s_mov_b32 m0, s76
	s_nop 0
	global_load_lds_dwordx4 v[216:217], off
	s_waitcnt vmcnt(8) lgkmcnt(0)
	s_setprio 1
	s_barrier
	v_mfma_f32_16x16x32_bf16 v[124:127], v[138:141], v[176:179], v[124:127]
	v_mfma_f32_16x16x32_bf16 v[120:123], v[146:149], v[176:179], v[120:123]
	v_mfma_f32_16x16x32_bf16 v[116:119], v[138:141], v[184:187], v[116:119]
	v_mfma_f32_16x16x32_bf16 v[112:115], v[146:149], v[184:187], v[112:115]
	v_mfma_f32_16x16x32_bf16 v[108:111], v[138:141], v[198:201], v[108:111]
	v_mfma_f32_16x16x32_bf16 v[104:107], v[146:149], v[198:201], v[104:107]
	v_mfma_f32_16x16x32_bf16 v[100:103], v[138:141], v[206:209], v[100:103]
	v_mfma_f32_16x16x32_bf16 v[92:95], v[146:149], v[206:209], v[92:95]
	v_mfma_f32_16x16x32_bf16 v[124:127], v[142:145], v[180:183], v[124:127]
	v_mfma_f32_16x16x32_bf16 v[120:123], v[150:153], v[180:183], v[120:123]
	v_mfma_f32_16x16x32_bf16 v[116:119], v[142:145], v[194:197], v[116:119]
	v_mfma_f32_16x16x32_bf16 v[112:115], v[150:153], v[194:197], v[112:115]
	v_mfma_f32_16x16x32_bf16 v[108:111], v[142:145], v[202:205], v[108:111]
	v_mfma_f32_16x16x32_bf16 v[104:107], v[150:153], v[202:205], v[104:107]
	v_mfma_f32_16x16x32_bf16 v[100:103], v[142:145], v[210:213], v[100:103]
	v_mfma_f32_16x16x32_bf16 v[92:95], v[150:153], v[210:213], v[92:95]
	v_mfma_f32_16x16x32_bf16 v[80:83], v[154:157], v[176:179], v[80:83]
	v_mfma_f32_16x16x32_bf16 v[76:79], v[166:169], v[176:179], v[76:79]
	v_mfma_f32_16x16x32_bf16 v[72:75], v[154:157], v[184:187], v[72:75]
	v_mfma_f32_16x16x32_bf16 v[68:71], v[166:169], v[184:187], v[68:71]
	v_mfma_f32_16x16x32_bf16 v[64:67], v[154:157], v[198:201], v[64:67]
	v_mfma_f32_16x16x32_bf16 v[60:63], v[166:169], v[198:201], v[60:63]
	v_mfma_f32_16x16x32_bf16 v[56:59], v[154:157], v[206:209], v[56:59]
	v_mfma_f32_16x16x32_bf16 v[48:51], v[166:169], v[206:209], v[48:51]
	v_mfma_f32_16x16x32_bf16 v[80:83], v[162:165], v[180:183], v[80:83]
	v_mfma_f32_16x16x32_bf16 v[76:79], v[170:173], v[180:183], v[76:79]
	v_mfma_f32_16x16x32_bf16 v[72:75], v[162:165], v[194:197], v[72:75]
	v_mfma_f32_16x16x32_bf16 v[68:71], v[170:173], v[194:197], v[68:71]
	v_mfma_f32_16x16x32_bf16 v[64:67], v[162:165], v[202:205], v[64:67]
	v_mfma_f32_16x16x32_bf16 v[60:63], v[170:173], v[202:205], v[60:63]
	v_mfma_f32_16x16x32_bf16 v[56:59], v[162:165], v[210:213], v[56:59]
	v_mfma_f32_16x16x32_bf16 v[48:51], v[170:173], v[210:213], v[48:51]
	s_barrier
	s_setprio 0
	s_add_i32 s24, s80, s72
	v_lshl_add_u64 v[158:159], v[158:159], 0, s[14:15]
	s_mov_b32 m0, s24
	ds_read_b128 v[176:179], v175 offset:49152
	ds_read_b128 v[180:183], v175 offset:50176
	ds_read_b128 v[184:187], v175 offset:51200
	ds_read_b128 v[194:197], v175 offset:52224
	ds_read_b128 v[198:201], v175 offset:53248
	ds_read_b128 v[202:205], v175 offset:54272
	ds_read_b128 v[206:209], v175 offset:55296
	ds_read_b128 v[210:213], v175 offset:56320
	global_load_lds_dwordx4 v[158:159], off
	s_add_i32 m0, s24, 0x2000
	s_add_u32 s22, s22, 0xb0080
	v_lshl_add_u64 v[158:159], v[188:189], 0, s[14:15]
	s_addc_u32 s23, s23, 0
	s_add_i32 s24, s87, s72
	global_load_lds_dwordx4 v[158:159], off
	v_lshl_add_u64 v[158:159], s[22:23], 0, v[130:131]
	s_mov_b32 m0, s24
	s_nop 0
	global_load_lds_dwordx4 v[158:159], off
	v_lshl_add_u64 v[158:159], s[22:23], 0, v[160:161]
	s_add_i32 m0, s24, 0x2000
	s_nop 0
	global_load_lds_dwordx4 v[158:159], off
	v_lshl_add_u64 v[158:159], v[190:191], 0, s[14:15]
	s_mov_b32 m0, s78
	s_nop 0
	global_load_lds_dwordx4 v[158:159], off
	v_lshl_add_u64 v[158:159], v[214:215], 0, s[14:15]
	s_mov_b32 m0, s79
	s_nop 0
	global_load_lds_dwordx4 v[158:159], off
	s_waitcnt vmcnt(8) lgkmcnt(0)
	s_setprio 1
	s_barrier
	v_mfma_f32_16x16x32_bf16 v[96:99], v[138:141], v[176:179], v[96:99]
	v_mfma_f32_16x16x32_bf16 v[88:91], v[146:149], v[176:179], v[88:91]
	v_mfma_f32_16x16x32_bf16 v[84:87], v[138:141], v[184:187], v[84:87]
	v_mfma_f32_16x16x32_bf16 v[24:27], v[146:149], v[184:187], v[24:27]
	v_mfma_f32_16x16x32_bf16 v[20:23], v[138:141], v[198:201], v[20:23]
	v_mfma_f32_16x16x32_bf16 v[16:19], v[146:149], v[198:201], v[16:19]
	v_mfma_f32_16x16x32_bf16 v[12:15], v[138:141], v[206:209], v[12:15]
	v_mfma_f32_16x16x32_bf16 v[8:11], v[146:149], v[206:209], v[8:11]
	v_mfma_f32_16x16x32_bf16 v[96:99], v[142:145], v[180:183], v[96:99]
	v_mfma_f32_16x16x32_bf16 v[88:91], v[150:153], v[180:183], v[88:91]
	v_mfma_f32_16x16x32_bf16 v[84:87], v[142:145], v[194:197], v[84:87]
	v_mfma_f32_16x16x32_bf16 v[24:27], v[150:153], v[194:197], v[24:27]
	v_mfma_f32_16x16x32_bf16 v[20:23], v[142:145], v[202:205], v[20:23]
	v_mfma_f32_16x16x32_bf16 v[16:19], v[150:153], v[202:205], v[16:19]
	v_mfma_f32_16x16x32_bf16 v[12:15], v[142:145], v[210:213], v[12:15]
	v_mfma_f32_16x16x32_bf16 v[8:11], v[150:153], v[210:213], v[8:11]
	v_mfma_f32_16x16x32_bf16 v[52:55], v[154:157], v[176:179], v[52:55]
	v_mfma_f32_16x16x32_bf16 v[44:47], v[166:169], v[176:179], v[44:47]
	v_mfma_f32_16x16x32_bf16 v[40:43], v[154:157], v[184:187], v[40:43]
	v_mfma_f32_16x16x32_bf16 v[36:39], v[166:169], v[184:187], v[36:39]
	v_mfma_f32_16x16x32_bf16 v[32:35], v[154:157], v[198:201], v[32:35]
	v_mfma_f32_16x16x32_bf16 v[28:31], v[166:169], v[198:201], v[28:31]
	v_mfma_f32_16x16x32_bf16 v[4:7], v[154:157], v[206:209], v[4:7]
	v_mfma_f32_16x16x32_bf16 v[0:3], v[166:169], v[206:209], v[0:3]
	v_mfma_f32_16x16x32_bf16 v[52:55], v[162:165], v[180:183], v[52:55]
	v_mfma_f32_16x16x32_bf16 v[44:47], v[170:173], v[180:183], v[44:47]
	v_mfma_f32_16x16x32_bf16 v[40:43], v[162:165], v[194:197], v[40:43]
	v_mfma_f32_16x16x32_bf16 v[36:39], v[170:173], v[194:197], v[36:39]
	v_mfma_f32_16x16x32_bf16 v[32:35], v[162:165], v[202:205], v[32:35]
	v_mfma_f32_16x16x32_bf16 v[28:31], v[170:173], v[202:205], v[28:31]
	v_mfma_f32_16x16x32_bf16 v[4:7], v[162:165], v[210:213], v[4:7]
	v_mfma_f32_16x16x32_bf16 v[0:3], v[170:173], v[210:213], v[0:3]
	s_barrier
	s_setprio 0
	s_add_i32 s19, s19, 2
	s_add_u32 s36, s36, 0x100
	s_addc_u32 s37, s37, 0
	s_add_u32 s67, s67, 0x100
	s_addc_u32 s81, s81, 0
	s_add_u32 s8, s8, 0xffffff00
	s_addc_u32 s9, s9, -1
	v_lshl_add_u64 v[134:135], v[134:135], 0, s[16:17]
	s_cmp_gt_u32 s19, 41
	v_lshl_add_u64 v[136:137], v[136:137], 0, s[16:17]
	s_cbranch_scc0 .LBB0_1570
	s_and_b64 vcc, exec, s[64:65]
	s_cbranch_vccz .LBB0_1573
	s_barrier

.LBB0_1583:
	s_and_b32 s0, s25, 0xffffffc0
	v_or_b32_e32 v0, s0, v56
	s_movk_i32 s37, 0x1600
	v_mad_i64_i32 v[32:33], s[40:41], v0, s37, v[48:49]
	v_add_co_u32_e32 v36, vcc, 0x16000, v32
	s_and_b32 s1, s23, 0x3e0
	s_nop 0
	v_addc_co_u32_e32 v37, vcc, 0, v33, vcc
	v_or_b32_e32 v0, s1, v56
	v_add_co_u32_e32 v38, vcc, 0x2c000, v32
	v_mul_u32_u24_e32 v0, 0xb00, v0
	s_nop 0
	v_addc_co_u32_e32 v39, vcc, 0, v33, vcc
	v_lshlrev_b32_e32 v160, 1, v0
	v_add_co_u32_e32 v44, vcc, 0x42000, v32
	v_lshl_add_u64 v[52:53], v[50:51], 0, v[160:161]
	s_nop 0
	v_addc_co_u32_e32 v45, vcc, 0, v33, vcc
	s_mov_b32 s37, 0x16000
	v_add_co_u32_e32 v54, vcc, s37, v52
	s_waitcnt lgkmcnt(0)
	global_load_dwordx4 v[0:3], v[32:33], off
	global_load_dwordx4 v[4:7], v[36:37], off
	v_addc_co_u32_e32 v55, vcc, 0, v53, vcc
	global_load_dwordx4 v[8:11], v[38:39], off
	global_load_dwordx4 v[12:15], v[44:45], off
	global_load_dwordx4 v[16:19], v[52:53], off
	global_load_dwordx4 v[20:23], v[54:55], off
	s_waitcnt vmcnt(1)
	v_mfma_f32_16x16x32_bf16 v[24:27], v[16:19], v[0:3], 0
	s_waitcnt vmcnt(0)
	v_mfma_f32_16x16x32_bf16 v[0:3], v[20:23], v[0:3], 0
	v_mfma_f32_16x16x32_bf16 v[28:31], v[16:19], v[4:7], 0
	v_mfma_f32_16x16x32_bf16 v[4:7], v[20:23], v[4:7], 0
	v_mfma_f32_16x16x32_bf16 v[40:43], v[16:19], v[8:11], 0
	v_mfma_f32_16x16x32_bf16 v[8:11], v[20:23], v[8:11], 0
	v_mfma_f32_16x16x32_bf16 v[16:19], v[16:19], v[12:15], 0
	v_mfma_f32_16x16x32_bf16 v[12:15], v[20:23], v[12:15], 0
	global_load_dwordx4 v[20:23], v[32:33], off offset:64
	global_load_dwordx4 v[62:65], v[36:37], off offset:64
	global_load_dwordx4 v[66:69], v[38:39], off offset:64
	global_load_dwordx4 v[70:73], v[44:45], off offset:64
	global_load_dwordx4 v[74:77], v[52:53], off offset:64
	global_load_dwordx4 v[78:81], v[54:55], off offset:64
	s_waitcnt vmcnt(1)
	v_mfma_f32_16x16x32_bf16 v[24:27], v[74:77], v[20:23], v[24:27]
	s_waitcnt vmcnt(0)
	v_mfma_f32_16x16x32_bf16 v[0:3], v[78:81], v[20:23], v[0:3]
	v_mfma_f32_16x16x32_bf16 v[20:23], v[74:77], v[62:65], v[28:31]
	v_mfma_f32_16x16x32_bf16 v[4:7], v[78:81], v[62:65], v[4:7]
	v_mfma_f32_16x16x32_bf16 v[28:31], v[74:77], v[66:69], v[40:43]
	v_mfma_f32_16x16x32_bf16 v[8:11], v[78:81], v[66:69], v[8:11]
	v_mfma_f32_16x16x32_bf16 v[16:19], v[74:77], v[70:73], v[16:19]
	v_mfma_f32_16x16x32_bf16 v[12:15], v[78:81], v[70:73], v[12:15]
	global_load_dwordx4 v[40:43], v[32:33], off offset:128
	global_load_dwordx4 v[62:65], v[36:37], off offset:128
	global_load_dwordx4 v[66:69], v[38:39], off offset:128
	global_load_dwordx4 v[70:73], v[44:45], off offset:128
	global_load_dwordx4 v[74:77], v[52:53], off offset:128
	global_load_dwordx4 v[78:81], v[54:55], off offset:128
	global_load_dwordx4 v[148:151], v[32:33], off offset:192
	global_load_dwordx4 v[152:155], v[36:37], off offset:192
	global_load_dwordx4 v[156:159], v[38:39], off offset:192
	global_load_dwordx4 v[162:165], v[44:45], off offset:192
	global_load_dwordx4 v[166:169], v[52:53], off offset:192
	global_load_dwordx4 v[170:173], v[54:55], off offset:192
	global_load_dwordx4 v[174:177], v[32:33], off offset:256
	global_load_dwordx4 v[178:181], v[36:37], off offset:256
	global_load_dwordx4 v[182:185], v[38:39], off offset:256
	global_load_dwordx4 v[88:91], v[44:45], off offset:256
	global_load_dwordx4 v[92:95], v[52:53], off offset:256
	global_load_dwordx4 v[96:99], v[54:55], off offset:256
	s_waitcnt vmcnt(12)
	v_mfma_f32_16x16x32_bf16 v[24:27], v[74:77], v[40:43], v[24:27]
	v_mfma_f32_16x16x32_bf16 v[0:3], v[78:81], v[40:43], v[0:3]
	v_mfma_f32_16x16x32_bf16 v[20:23], v[74:77], v[62:65], v[20:23]
	v_mfma_f32_16x16x32_bf16 v[4:7], v[78:81], v[62:65], v[4:7]
	v_mfma_f32_16x16x32_bf16 v[28:31], v[74:77], v[66:69], v[28:31]
	v_mfma_f32_16x16x32_bf16 v[8:11], v[78:81], v[66:69], v[8:11]
	v_mfma_f32_16x16x32_bf16 v[16:19], v[74:77], v[70:73], v[16:19]
	v_mfma_f32_16x16x32_bf16 v[12:15], v[78:81], v[70:73], v[12:15]
	global_load_dwordx4 v[40:43], v[32:33], off offset:320
	global_load_dwordx4 v[62:65], v[36:37], off offset:320
	global_load_dwordx4 v[66:69], v[38:39], off offset:320
	global_load_dwordx4 v[70:73], v[44:45], off offset:320
	global_load_dwordx4 v[74:77], v[52:53], off offset:320
	global_load_dwordx4 v[78:81], v[54:55], off offset:320
	s_waitcnt vmcnt(12)
	v_mfma_f32_16x16x32_bf16 v[24:27], v[166:169], v[148:151], v[24:27]
	v_mfma_f32_16x16x32_bf16 v[0:3], v[170:173], v[148:151], v[0:3]
	v_mfma_f32_16x16x32_bf16 v[20:23], v[166:169], v[152:155], v[20:23]
	v_mfma_f32_16x16x32_bf16 v[4:7], v[170:173], v[152:155], v[4:7]
	v_mfma_f32_16x16x32_bf16 v[28:31], v[166:169], v[156:159], v[28:31]
	v_mfma_f32_16x16x32_bf16 v[8:11], v[170:173], v[156:159], v[8:11]
	v_mfma_f32_16x16x32_bf16 v[16:19], v[166:169], v[162:165], v[16:19]
	v_mfma_f32_16x16x32_bf16 v[12:15], v[170:173], v[162:165], v[12:15]
	global_load_dwordx4 v[148:151], v[32:33], off offset:384
	global_load_dwordx4 v[152:155], v[36:37], off offset:384
	global_load_dwordx4 v[156:159], v[38:39], off offset:384
	global_load_dwordx4 v[162:165], v[44:45], off offset:384
	global_load_dwordx4 v[166:169], v[52:53], off offset:384
	global_load_dwordx4 v[170:173], v[54:55], off offset:384
	s_waitcnt vmcnt(12)
	v_mfma_f32_16x16x32_bf16 v[24:27], v[92:95], v[174:177], v[24:27]
	v_mfma_f32_16x16x32_bf16 v[0:3], v[96:99], v[174:177], v[0:3]
	v_mfma_f32_16x16x32_bf16 v[20:23], v[92:95], v[178:181], v[20:23]
	v_mfma_f32_16x16x32_bf16 v[4:7], v[96:99], v[178:181], v[4:7]
	v_mfma_f32_16x16x32_bf16 v[28:31], v[92:95], v[182:185], v[28:31]
	v_mfma_f32_16x16x32_bf16 v[8:11], v[96:99], v[182:185], v[8:11]
	v_mfma_f32_16x16x32_bf16 v[16:19], v[92:95], v[88:91], v[16:19]
	v_mfma_f32_16x16x32_bf16 v[12:15], v[96:99], v[88:91], v[12:15]
	global_load_dwordx4 v[174:177], v[32:33], off offset:448
	global_load_dwordx4 v[178:181], v[36:37], off offset:448
	global_load_dwordx4 v[182:185], v[38:39], off offset:448
	global_load_dwordx4 v[88:91], v[44:45], off offset:448
	global_load_dwordx4 v[92:95], v[52:53], off offset:448
	global_load_dwordx4 v[96:99], v[54:55], off offset:448
	s_waitcnt vmcnt(12)
	v_mfma_f32_16x16x32_bf16 v[24:27], v[74:77], v[40:43], v[24:27]
	v_mfma_f32_16x16x32_bf16 v[0:3], v[78:81], v[40:43], v[0:3]
	v_mfma_f32_16x16x32_bf16 v[20:23], v[74:77], v[62:65], v[20:23]
	v_mfma_f32_16x16x32_bf16 v[4:7], v[78:81], v[62:65], v[4:7]
	v_mfma_f32_16x16x32_bf16 v[28:31], v[74:77], v[66:69], v[28:31]
	v_mfma_f32_16x16x32_bf16 v[8:11], v[78:81], v[66:69], v[8:11]
	v_mfma_f32_16x16x32_bf16 v[16:19], v[74:77], v[70:73], v[16:19]
	v_mfma_f32_16x16x32_bf16 v[12:15], v[78:81], v[70:73], v[12:15]
	global_load_dwordx4 v[40:43], v[32:33], off offset:512
	global_load_dwordx4 v[62:65], v[36:37], off offset:512
	global_load_dwordx4 v[66:69], v[38:39], off offset:512
	global_load_dwordx4 v[70:73], v[44:45], off offset:512
	global_load_dwordx4 v[74:77], v[52:53], off offset:512
	global_load_dwordx4 v[78:81], v[54:55], off offset:512
	s_waitcnt vmcnt(12)
	v_mfma_f32_16x16x32_bf16 v[24:27], v[166:169], v[148:151], v[24:27]
	v_mfma_f32_16x16x32_bf16 v[0:3], v[170:173], v[148:151], v[0:3]
	v_mfma_f32_16x16x32_bf16 v[20:23], v[166:169], v[152:155], v[20:23]
	v_mfma_f32_16x16x32_bf16 v[4:7], v[170:173], v[152:155], v[4:7]
	v_mfma_f32_16x16x32_bf16 v[28:31], v[166:169], v[156:159], v[28:31]
	v_mfma_f32_16x16x32_bf16 v[8:11], v[170:173], v[156:159], v[8:11]
	v_mfma_f32_16x16x32_bf16 v[16:19], v[166:169], v[162:165], v[16:19]
	v_mfma_f32_16x16x32_bf16 v[12:15], v[170:173], v[162:165], v[12:15]
	s_waitcnt vmcnt(6)
	v_mfma_f32_16x16x32_bf16 v[24:27], v[92:95], v[174:177], v[24:27]
	v_mfma_f32_16x16x32_bf16 v[0:3], v[96:99], v[174:177], v[0:3]
	v_mfma_f32_16x16x32_bf16 v[20:23], v[92:95], v[178:181], v[20:23]
	v_mfma_f32_16x16x32_bf16 v[4:7], v[96:99], v[178:181], v[4:7]
	v_mfma_f32_16x16x32_bf16 v[28:31], v[92:95], v[182:185], v[28:31]
	v_mfma_f32_16x16x32_bf16 v[8:11], v[96:99], v[182:185], v[8:11]
	v_mfma_f32_16x16x32_bf16 v[16:19], v[92:95], v[88:91], v[16:19]
	v_mfma_f32_16x16x32_bf16 v[12:15], v[96:99], v[88:91], v[12:15]
	s_waitcnt vmcnt(0)
	v_mfma_f32_16x16x32_bf16 v[24:27], v[74:77], v[40:43], v[24:27]
	v_mfma_f32_16x16x32_bf16 v[0:3], v[78:81], v[40:43], v[0:3]
	v_mfma_f32_16x16x32_bf16 v[20:23], v[74:77], v[62:65], v[20:23]
	v_mfma_f32_16x16x32_bf16 v[4:7], v[78:81], v[62:65], v[4:7]
	v_mfma_f32_16x16x32_bf16 v[40:43], v[74:77], v[66:69], v[28:31]
	v_mfma_f32_16x16x32_bf16 v[8:11], v[78:81], v[66:69], v[8:11]
	v_mfma_f32_16x16x32_bf16 v[62:65], v[74:77], v[70:73], v[16:19]
	v_mfma_f32_16x16x32_bf16 v[12:15], v[78:81], v[70:73], v[12:15]
	s_nop 1
	global_load_dwordx4 v[16:19], v[32:33], off offset:576
	global_load_dwordx4 v[66:69], v[36:37], off offset:576
	global_load_dwordx4 v[70:73], v[38:39], off offset:576
	global_load_dwordx4 v[74:77], v[44:45], off offset:576
	global_load_dwordx4 v[78:81], v[52:53], off offset:576
	global_load_dwordx4 v[82:85], v[54:55], off offset:576
	s_waitcnt vmcnt(1)
	v_mfma_f32_16x16x32_bf16 v[28:31], v[78:81], v[16:19], v[24:27]
	s_waitcnt vmcnt(0)
	v_mfma_f32_16x16x32_bf16 v[24:27], v[82:85], v[16:19], v[0:3]
	v_mfma_f32_16x16x32_bf16 v[16:19], v[78:81], v[66:69], v[20:23]
	v_mfma_f32_16x16x32_bf16 v[20:23], v[82:85], v[66:69], v[4:7]
	v_mfma_f32_16x16x32_bf16 v[0:3], v[78:81], v[70:73], v[40:43]
	v_mfma_f32_16x16x32_bf16 v[4:7], v[82:85], v[70:73], v[8:11]
	v_mfma_f32_16x16x32_bf16 v[8:11], v[78:81], v[74:77], v[62:65]
	global_load_dwordx4 v[32:35], v[32:33], off offset:640
	s_nop 0
	global_load_dwordx4 v[40:43], v[36:37], off offset:640
	s_nop 0
	global_load_dwordx4 v[36:39], v[38:39], off offset:640
	s_nop 0
	global_load_dwordx4 v[44:47], v[44:45], off offset:640
	s_nop 0
	global_load_dwordx4 v[62:65], v[52:53], off offset:640
	s_nop 0
	global_load_dwordx4 v[52:55], v[54:55], off offset:640
	v_mfma_f32_16x16x32_bf16 v[12:15], v[82:85], v[74:77], v[12:15]
	s_waitcnt vmcnt(1)
	v_mfma_f32_16x16x32_bf16 v[28:31], v[62:65], v[32:35], v[28:31]
	s_waitcnt vmcnt(0)
	v_mfma_f32_16x16x32_bf16 v[24:27], v[52:55], v[32:35], v[24:27]
	v_add_u32_e32 v32, s19, v57
	v_mfma_f32_16x16x32_bf16 v[16:19], v[62:65], v[40:43], v[16:19]
	v_mfma_f32_16x16x32_bf16 v[20:23], v[52:55], v[40:43], v[20:23]
	v_mfma_f32_16x16x32_bf16 v[0:3], v[62:65], v[36:39], v[0:3]
	v_mfma_f32_16x16x32_bf16 v[4:7], v[52:55], v[36:39], v[4:7]
	v_mfma_f32_16x16x32_bf16 v[8:11], v[62:65], v[44:47], v[8:11]
	v_mfma_f32_16x16x32_bf16 v[12:15], v[52:55], v[44:47], v[12:15]
	ds_write_b128 v32, v[28:31]
	ds_write_b128 v32, v[24:27] offset:1024
	s_nop 0
	ds_write_b128 v32, v[16:19] offset:2048
	ds_write_b128 v32, v[20:23] offset:3072
	ds_write_b128 v32, v[0:3] offset:4096
	ds_write_b128 v32, v[4:7] offset:5120
	ds_write_b128 v32, v[8:11] offset:6144
	ds_write_b128 v32, v[12:15] offset:7168
	s_waitcnt lgkmcnt(0)
	s_barrier
	ds_read_b128 v[0:3], v58
	ds_read_b128 v[4:7], v58 offset:8192
	v_or_b32_e32 v17, s1, v60
	s_waitcnt lgkmcnt(0)
	v_pk_add_f32 v[6:7], v[2:3], v[6:7]
	v_pk_add_f32 v[4:5], v[0:1], v[4:5]
	ds_read_b128 v[0:3], v58 offset:16384
	s_waitcnt lgkmcnt(0)
	v_pk_add_f32 v[6:7], v[6:7], v[2:3]
	v_pk_add_f32 v[4:5], v[4:5], v[0:1]
	ds_read_b128 v[0:3], v58 offset:24576
	s_waitcnt lgkmcnt(0)
	v_pk_add_f32 v[6:7], v[6:7], v[2:3]
	v_pk_add_f32 v[4:5], v[4:5], v[0:1]
	ds_read_b128 v[0:3], v58 offset:32768
	s_waitcnt lgkmcnt(0)
	v_pk_add_f32 v[6:7], v[6:7], v[2:3]
	v_pk_add_f32 v[4:5], v[4:5], v[0:1]
	ds_read_b128 v[0:3], v58 offset:40960
	s_waitcnt lgkmcnt(0)
	v_pk_add_f32 v[6:7], v[6:7], v[2:3]
	v_pk_add_f32 v[4:5], v[4:5], v[0:1]
	ds_read_b128 v[0:3], v58 offset:49152
	s_waitcnt lgkmcnt(0)
	v_pk_add_f32 v[6:7], v[6:7], v[2:3]
	v_pk_add_f32 v[4:5], v[4:5], v[0:1]
	ds_read_b128 v[0:3], v58 offset:57344
	s_waitcnt lgkmcnt(0)
	s_barrier
	v_pk_add_f32 v[12:13], v[4:5], v[0:1]
	v_add_u32_e32 v0, s0, v59
	v_ashrrev_i32_e32 v1, 31, v0
	s_mov_b64 s[0:1], 0x10000
	v_lshl_add_u64 v[18:19], v[0:1], 0, s[0:1]
	v_lshlrev_b64 v[8:9], 3, v[18:19]
	v_lshl_add_u64 v[0:1], s[6:7], 0, v[8:9]
	global_load_dwordx2 v[0:1], v[0:1], off
	v_pk_add_f32 v[10:11], v[6:7], v[2:3]
	v_lshlrev_b64 v[18:19], 11, v[18:19]
	v_lshl_or_b32 v18, v17, 1, v18
	v_lshl_add_u64 v[20:21], s[4:5], 0, v[18:19]
	s_waitcnt vmcnt(0)
	v_pk_mul_f32 v[14:15], v[0:1], s[96:97] op_sel_hi:[1,0]
	s_nop 0
	v_fma_f32 v0, -v14, v14, v15
	v_max_f32_e32 v0, 0, v0
	v_add_f32_e32 v0, 0x3727c5ac, v0
	v_cmp_gt_f32_e32 vcc, s97, v0
	v_mul_f32_e32 v1, 0x4f800000, v0
	s_nop 0
	v_cndmask_b32_e32 v0, v0, v1, vcc
	v_sqrt_f32_e32 v1, v0
	s_nop 0
	v_add_u32_e32 v2, -1, v1
	v_fma_f32 v3, -v2, v1, v0
	v_cmp_ge_f32_e64 s[40:41], 0, v3
	v_add_u32_e32 v3, 1, v1
	s_nop 0
	v_cndmask_b32_e64 v2, v1, v2, s[40:41]
	v_fma_f32 v1, -v3, v1, v0
	v_cmp_lt_f32_e64 s[40:41], 0, v1
	s_nop 1
	v_cndmask_b32_e64 v1, v2, v3, s[40:41]
	v_mul_f32_e32 v2, 0x37800000, v1
	v_cndmask_b32_e32 v1, v1, v2, vcc
	v_cmp_class_f32_e32 vcc, v0, v248
	s_nop 1
	v_cndmask_b32_e32 v0, v1, v0, vcc
	v_div_scale_f32 v1, s[0:1], v0, v0, 1.0
	v_rcp_f32_e32 v2, v1
	s_nop 0
	v_fma_f32 v3, -v1, v2, 1.0
	v_fmac_f32_e32 v2, v3, v2
	v_div_scale_f32 v3, vcc, 1.0, v0, 1.0
	v_mul_f32_e32 v4, v3, v2
	v_fma_f32 v5, -v1, v4, v3
	v_fmac_f32_e32 v4, v5, v2
	v_fma_f32 v1, -v1, v4, v3
	v_div_fmas_f32 v1, v1, v2, v4
	v_div_fixup_f32 v16, v1, v0, 1.0
	v_lshlrev_b32_e32 v0, 2, v17
	global_load_dwordx4 v[4:7], v0, s[8:9]
	s_nop 0
	global_load_dwordx4 v[0:3], v0, s[42:43]
	s_waitcnt vmcnt(1)
	v_pk_mul_f32 v[4:5], v[4:5], v[16:17] op_sel_hi:[1,0]
	global_load_dwordx2 v[20:21], v[20:21], off
	s_waitcnt vmcnt(1)
	v_pk_fma_f32 v[0:1], v[14:15], v[4:5], v[0:1] op_sel_hi:[0,1,1] neg_lo:[1,0,0] neg_hi:[1,0,0]
	v_pk_mul_f32 v[6:7], v[6:7], v[16:17] op_sel_hi:[1,0]
	s_waitcnt vmcnt(0)
	v_lshlrev_b32_e32 v22, 16, v20
	v_and_b32_e32 v23, 0xffff0000, v20
	v_pk_fma_f32 v[0:1], v[22:23], v[4:5], v[0:1]
	v_lshlrev_b32_e32 v4, 16, v21
	v_and_b32_e32 v5, 0xffff0000, v21
	v_pk_fma_f32 v[2:3], v[14:15], v[6:7], v[2:3] op_sel_hi:[0,1,1] neg_lo:[1,0,0] neg_hi:[1,0,0]
	v_pk_fma_f32 v[2:3], v[4:5], v[6:7], v[2:3]
	v_pk_fma_f32 v[0:1], v[0:1], s[12:13], v[12:13] op_sel_hi:[1,0,1]
	v_pk_fma_f32 v[2:3], v[2:3], s[12:13], v[10:11] op_sel_hi:[1,0,1]
	v_cvt_pk_bf16_f32 v0, v0, v1
	v_cvt_pk_bf16_f32 v1, v2, v3
	v_lshl_add_u64 v[2:3], s[44:45], 0, v[18:19]
	global_store_dwordx2 v[2:3], v[0:1], off
	v_lshlrev_b32_e32 v2, 16, v0
	v_and_b32_e32 v0, 0xffff0000, v0
	v_lshlrev_b32_e32 v4, 16, v1
	v_and_b32_e32 v1, 0xffff0000, v1
	v_add_f32_e32 v3, v2, v0
	v_add_f32_e32 v5, v4, v1
	v_mul_f32_e32 v0, v0, v0
	v_mul_f32_e32 v1, v1, v1
	v_fmac_f32_e32 v0, v2, v2
	v_fmac_f32_e32 v1, v4, v4
	v_add_f32_e32 v2, v0, v1
	v_mbcnt_lo_u32_b32 v0, -1, 0
	v_mbcnt_hi_u32_b32 v0, -1, v0
	v_add_f32_e32 v3, v3, v5
	v_lshlrev_b32_e32 v0, 2, v0
	v_xor_b32_e32 v0, 64, v0
	ds_bpermute_b32 v0, v0, v3
	v_mbcnt_lo_u32_b32 v1, -1, 0
	v_mbcnt_hi_u32_b32 v1, -1, v1
	s_waitcnt lgkmcnt(0)
	v_add_f32_e32 v0, v3, v0
	v_mbcnt_lo_u32_b32 v3, -1, 0
	v_mbcnt_hi_u32_b32 v3, -1, v3
	v_lshlrev_b32_e32 v1, 2, v1
	v_lshlrev_b32_e32 v3, 2, v3
	v_xor_b32_e32 v3, 64, v3
	ds_bpermute_b32 v3, v3, v2
	v_xor_b32_e32 v1, 0x80, v1
	ds_bpermute_b32 v1, v1, v0
	s_waitcnt lgkmcnt(1)
	v_add_f32_e32 v2, v2, v3
	v_mbcnt_lo_u32_b32 v3, -1, 0
	v_mbcnt_hi_u32_b32 v3, -1, v3
	s_nop 0
	v_lshlrev_b32_e32 v3, 2, v3
	v_xor_b32_e32 v3, 0x80, v3
	ds_bpermute_b32 v3, v3, v2
	s_and_saveexec_b64 s[0:1], s[38:39]
	s_cbranch_execz .LBB0_1582
	s_waitcnt lgkmcnt(0)
	v_add_f32_e32 v2, v2, v3
	v_add_f32_e32 v3, v0, v1
	v_lshl_add_u64 v[0:1], s[46:47], 0, v[8:9]
	global_atomic_add_f32 v[0:1], v3, off
	global_atomic_add_f32 v[0:1], v2, off offset:4
	s_branch .LBB0_1582
